# wave/16-lane sum reductions in post, norm and final phases: ds_bpermute butterfly chains replaced by DPP row ops and permlane16/32 swaps (same f32 adds, different pairing order)
# speedup vs baseline: 1.0050x; 1.0050x over previous
; __device__ void phase_norm(const Ctx& c, const void* xlat, bool lat_f32, const void* xctx, bool ctx_f32, const float* __restrict__ g, const float* __restrict__ mod, int sh_off, int sc_off,
;                            bf16_t* __restrict__ dst, int nrows, const float* part) {
;     ...
;     for (int row = c.bid * 8 + c.wave; row < nrows; row += c.G * 8) {
;         f32x4 v[8];
;         if (row < TL) load_row32(v, xlat, lat_f32, (size_t)row * DM, c.lane); else load_row32(v, xctx, ctx_f32, (size_t)(row - TL) * DM, c.lane);
;         if (part != nullptr && row >= TL) {
;             const float* pr = part + (size_t)(row - TL) * DM + c.lane * 8; bf16_t* xo = XW + (size_t)row * DM + c.lane * 8;
; #pragma unroll
;             for (int i = 0; i < 4; ++i) {
; #pragma unroll
;                 for (int sp = 0; sp < 8; ++sp) { v[2 * i] += *(const f32x4*)(pr + (size_t)sp * TC * DM + i * 512); v[2 * i + 1] += *(const f32x4*)(pr + (size_t)sp * TC * DM + i * 512 + 4); }
;                 u32x4 w; w.x = cvt_pk_bf16(v[2 * i][0], v[2 * i][1]); w.y = cvt_pk_bf16(v[2 * i][2], v[2 * i][3]); w.z = cvt_pk_bf16(v[2 * i + 1][0], v[2 * i + 1][1]); w.w = cvt_pk_bf16(v[2 * i + 1][2], v[2 * i + 1][3]);
;                 *(u32x4*)(xo + i * 512) = w;
;                 __builtin_amdgcn_sched_barrier(0); }
;         }
;         float ss = 0.f;
; #pragma unroll
;         for (int i = 0; i < 8; ++i) ss += v[i][0] * v[i][0] + v[i][1] * v[i][1] + v[i][2] * v[i][2] + v[i][3] * v[i][3];
;         ss = wave_sum(ss, c.lane);
;         const float rstd = rsqrtf(ss * (1.f / DM) + EPS);
;         const int r = row < TL ? (row >> 11) : 4;
;         const float* md = mod + (size_t)r * MODW + c.lane * 8;
; #pragma unroll
;         for (int i = 0; i < 4; ++i) { const int cc = i * 512;
;             f32x4 y[2];
; #pragma unroll
;             for (int h = 0; h < 2; ++h) { const f32x4 gg = *(const f32x4*)(g + cc + c.lane * 8 + 4 * h), sh = *(const f32x4*)(md + sh_off + cc + 4 * h), sc = *(const f32x4*)(md + sc_off + cc + 4 * h);
; #pragma unroll
;                 for (int j = 0; j < 4; ++j) y[h][j] = v[2 * i + h][j] * rstd * gg[j] * (1.f + sc[j]) + sh[j]; }
;             u32x4 w; w.x = cvt_pk_bf16(y[0][0], y[0][1]); w.y = cvt_pk_bf16(y[0][2], y[0][3]); w.z = cvt_pk_bf16(y[1][0], y[1][1]); w.w = cvt_pk_bf16(y[1][2], y[1][3]);
;             *(u32x4*)(dst + (size_t)row * DM + cc + c.lane * 8) = w; }
.LBB0_203:
	s_or_b64 exec, exec, s[24:25]
	v_add_co_u32_e32 v58, vcc, s27, v8
	global_load_dwordx4 v[36:39], v[8:9], off
	global_load_dwordx4 v[32:35], v[8:9], off offset:16
	global_load_dwordx4 v[28:31], v[8:9], off offset:2048
	global_load_dwordx4 v[24:27], v[8:9], off offset:2064
	v_addc_co_u32_e32 v59, vcc, 0, v9, vcc
	v_lshl_add_u64 v[10:11], v[8:9], 0, s[4:5]
	global_load_dwordx4 v[20:23], v[58:59], off
	global_load_dwordx4 v[16:19], v[10:11], off offset:16
	v_lshl_add_u64 v[60:61], v[8:9], 0, s[6:7]
	global_load_dwordx4 v[12:15], v[58:59], off offset:2048
	global_load_dwordx4 v[8:11], v[60:61], off offset:16
	v_min_i32_e32 v40, 0x2000, v54
	v_ashrrev_i32_e32 v40, 11, v40
	v_mul_hi_i32_i24_e32 v59, 0xc000, v40
	v_mul_i32_i24_e32 v58, 0xc000, v40
	v_lshl_add_u64 v[58:59], v[42:43], 0, v[58:59]
	v_add_co_u32_e32 v60, vcc, s30, v58
	v_lshl_add_u64 v[88:89], v[58:59], 0, s[16:17]
	s_nop 0
	v_addc_co_u32_e32 v61, vcc, 0, v59, vcc
	global_load_dwordx4 v[72:75], v[60:61], off offset:-4096
	global_load_dwordx4 v[76:79], v[58:59], off offset:16
	global_load_dwordx4 v[80:83], v[58:59], off
	global_load_dwordx4 v[84:87], v[88:89], off offset:16
	v_lshlrev_b64 v[62:63], 12, v[62:63]
	v_lshl_add_u64 v[62:63], v[52:53], 0, v[62:63]
	v_lshl_add_u64 v[54:55], v[54:55], 0, s[8:9]
	v_lshl_add_u64 v[56:57], v[56:57], 0, s[10:11]
	s_waitcnt vmcnt(11)
	v_mul_f32_e32 v40, v37, v37
	s_waitcnt vmcnt(10)
	v_mul_f32_e32 v71, v33, v33
	s_waitcnt vmcnt(9)
	v_mul_f32_e32 v104, v29, v29
	v_fmac_f32_e32 v40, v36, v36
	v_fmac_f32_e32 v71, v32, v32
	s_waitcnt vmcnt(8)
	v_mul_f32_e32 v105, v25, v25
	v_fmac_f32_e32 v104, v28, v28
	v_fmac_f32_e32 v40, v38, v38
	v_fmac_f32_e32 v71, v34, v34
	s_waitcnt vmcnt(7)
	v_mov_b32_e32 v90, v21
	s_waitcnt vmcnt(6)
	v_mov_b32_e32 v91, v17
	v_fmac_f32_e32 v105, v24, v24
	v_fmac_f32_e32 v104, v30, v30
	v_mov_b32_e32 v88, v20
	v_mov_b32_e32 v89, v16
	v_fmac_f32_e32 v40, v39, v39
	v_fmac_f32_e32 v71, v35, v35
	v_pk_mul_f32 v[90:91], v[90:91], v[90:91]
	v_fmac_f32_e32 v105, v26, v26
	s_waitcnt vmcnt(5)
	v_mov_b32_e32 v94, v13
	s_waitcnt vmcnt(4)
	v_mov_b32_e32 v95, v9
	v_mov_b32_e32 v96, v22
	v_mov_b32_e32 v97, v18
	v_fmac_f32_e32 v104, v31, v31
	v_add_f32_e32 v40, v40, v71
	v_pk_fma_f32 v[88:89], v[88:89], v[88:89], v[90:91]
	v_mov_b32_e32 v92, v12
	v_mov_b32_e32 v93, v8
	v_mov_b32_e32 v100, v23
	v_mov_b32_e32 v101, v19
	v_pk_mul_f32 v[94:95], v[94:95], v[94:95]
	v_fmac_f32_e32 v105, v27, v27
	v_pk_fma_f32 v[88:89], v[96:97], v[96:97], v[88:89]
	v_add_f32_e32 v40, v40, v104
	v_mov_b32_e32 v98, v14
	v_mov_b32_e32 v99, v10
	v_pk_fma_f32 v[90:91], v[92:93], v[92:93], v[94:95]
	v_add_f32_e32 v40, v40, v105
	v_pk_fma_f32 v[88:89], v[100:101], v[100:101], v[88:89]
	v_mov_b32_e32 v102, v15
	v_mov_b32_e32 v103, v11
	v_pk_fma_f32 v[90:91], v[98:99], v[98:99], v[90:91]
	v_add_f32_e32 v40, v40, v88
	v_pk_fma_f32 v[90:91], v[102:103], v[102:103], v[90:91]
	v_add_f32_e32 v40, v40, v89
	v_add_f32_e32 v40, v40, v90
	v_add_f32_e32 v40, v40, v91
	v_add_co_u32_e32 v88, vcc, s29, v58
	s_waitcnt vmcnt(3)
	v_add_f32_e32 v72, 1.0, v72
	v_addc_co_u32_e32 v89, vcc, 0, v59, vcc
	s_waitcnt lgkmcnt(0)
	v_mov_b32_e32 v71, v40
	s_nop 1
	v_permlane32_swap_b32_e32 v40, v71
	s_nop 1
	v_add_f32_e32 v40, v40, v71
	v_add_f32_e32 v73, 1.0, v73
	v_add_f32_e32 v74, 1.0, v74
	v_add_f32_e32 v75, 1.0, v75
	s_waitcnt vmcnt(0)
	v_add_f32_e32 v84, 1.0, v84
	s_waitcnt lgkmcnt(0)
	v_mov_b32_e32 v71, v40
	s_nop 1
	v_permlane16_swap_b32_e32 v40, v71
	s_nop 1
	v_add_f32_e32 v40, v40, v71
	s_waitcnt lgkmcnt(0)
	s_nop 1
	v_add_f32_dpp v40, v40, v40 row_mirror row_mask:0xf bank_mask:0xf
	s_waitcnt lgkmcnt(0)
	s_nop 1
	v_add_f32_dpp v40, v40, v40 row_half_mirror row_mask:0xf bank_mask:0xf
	s_waitcnt lgkmcnt(0)
	s_nop 1
	v_add_f32_dpp v40, v40, v40 quad_perm:[2,3,0,1] row_mask:0xf bank_mask:0xf
	s_waitcnt lgkmcnt(0)
	s_nop 1
	v_add_f32_dpp v40, v40, v40 quad_perm:[1,0,3,2] row_mask:0xf bank_mask:0xf
	v_fmamk_f32 v40, v40, 0x3a000000, v70
	v_mul_f32_e32 v71, 0x4b800000, v40
	v_cmp_gt_f32_e32 vcc, s28, v40
	s_nop 1
	v_cndmask_b32_e32 v40, v40, v71, vcc
	v_rsq_f32_e32 v40, v40
	v_add_f32_e32 v71, 1.0, v85
	v_add_f32_e32 v85, 1.0, v86
	v_add_f32_e32 v86, 1.0, v87
	v_mul_f32_e32 v87, 0x45800000, v40
	v_cndmask_b32_e32 v40, v40, v87, vcc
	v_mul_f32_e32 v36, v36, v40
	v_mul_f32_e32 v37, v37, v40
	v_mul_f32_e32 v38, v38, v40
	v_mul_f32_e32 v39, v39, v40
	v_mul_f32_e32 v32, v32, v40
	v_mul_f32_e32 v33, v33, v40
	v_mul_f32_e32 v34, v34, v40
	v_mul_f32_e32 v35, v35, v40
	v_mul_f32_e32 v36, v0, v36
	v_mul_f32_e32 v37, v1, v37
	v_mul_f32_e32 v38, v2, v38
	v_mul_f32_e32 v39, v3, v39
	v_mul_f32_e32 v32, v4, v32
	v_mul_f32_e32 v33, v5, v33
	v_mul_f32_e32 v34, v6, v34
	v_mul_f32_e32 v35, v7, v35
	v_fma_f32 v36, v72, v36, v80
	v_fma_f32 v37, v73, v37, v81
	v_fma_f32 v38, v74, v38, v82
	v_fmac_f32_e32 v83, v75, v39
	v_fma_f32 v39, v84, v32, v76
	v_fma_f32 v71, v71, v33, v77
	v_fma_f32 v72, v85, v34, v78
	v_fmac_f32_e32 v79, v86, v35
	v_cvt_pk_bf16_f32 v32, v36, v37
	v_cvt_pk_bf16_f32 v33, v38, v83
	v_cvt_pk_bf16_f32 v34, v39, v71
	v_cvt_pk_bf16_f32 v35, v72, v79
	global_store_dwordx4 v[62:63], v[32:35], off
	global_load_dwordx4 v[32:35], v[44:45], off offset:2048
	s_nop 0
	global_load_dwordx4 v[36:39], v[88:89], off offset:2048
	v_lshl_add_u64 v[88:89], v[58:59], 0, s[18:19]
	global_load_dwordx4 v[72:75], v[44:45], off offset:2064
	global_load_dwordx4 v[76:79], v[88:89], off offset:16
	global_load_dwordx4 v[80:83], v[58:59], off offset:2048
	global_load_dwordx4 v[84:87], v[58:59], off offset:2064
	v_mul_f32_e32 v28, v28, v40
	v_mul_f32_e32 v29, v29, v40
	v_mul_f32_e32 v30, v30, v40
	v_mul_f32_e32 v31, v31, v40
	v_mul_f32_e32 v24, v24, v40
	v_mul_f32_e32 v25, v25, v40
	v_mul_f32_e32 v26, v26, v40
	v_mul_f32_e32 v27, v27, v40
	v_mul_f32_e32 v20, v20, v40
	v_mul_f32_e32 v21, v21, v40
	v_mul_f32_e32 v22, v22, v40
	v_mul_f32_e32 v23, v23, v40
	v_mul_f32_e32 v16, v16, v40
	v_mul_f32_e32 v17, v17, v40
	v_mul_f32_e32 v18, v18, v40
	v_mul_f32_e32 v19, v19, v40
	v_mul_f32_e32 v12, v12, v40
	v_mul_f32_e32 v13, v13, v40
	v_mul_f32_e32 v14, v14, v40
	v_mul_f32_e32 v15, v15, v40
	v_mul_f32_e32 v8, v8, v40
	v_mul_f32_e32 v9, v9, v40
	v_mul_f32_e32 v10, v10, v40
	v_mul_f32_e32 v11, v11, v40
	s_waitcnt vmcnt(5)
; __device__ __forceinline__ unsigned cvt_pk_bf16(float lo, float hi) { unsigned r; asm volatile("v_cvt_pk_bf16_f32 %0, %1, %2" : "=v"(r) : "v"(lo), "v"(hi)); return r; }
; __device__ void phase_norm(const Ctx& c, const void* xlat, bool lat_f32, const void* xctx, bool ctx_f32, const float* __restrict__ g, const float* __restrict__ mod, int sh_off, int sc_off,
;                            bf16_t* __restrict__ dst, int nrows, const float* part) {
;     ...
;         for (int i = 0; i < 4; ++i) { const int cc = i * 512;
;             f32x4 y[2];
; #pragma unroll
;             for (int h = 0; h < 2; ++h) { const f32x4 gg = *(const f32x4*)(g + cc + c.lane * 8 + 4 * h), sh = *(const f32x4*)(md + sh_off + cc + 4 * h), sc = *(const f32x4*)(md + sc_off + cc + 4 * h);
; #pragma unroll
;                 for (int j = 0; j < 4; ++j) y[h][j] = v[2 * i + h][j] * rstd * gg[j] * (1.f + sc[j]) + sh[j]; }
;             u32x4 w; w.x = cvt_pk_bf16(y[0][0], y[0][1]); w.y = cvt_pk_bf16(y[0][2], y[0][3]); w.z = cvt_pk_bf16(y[1][0], y[1][1]); w.w = cvt_pk_bf16(y[1][2], y[1][3]);
;             *(u32x4*)(dst + (size_t)row * DM + cc + c.lane * 8) = w; }
	v_mul_f32_e32 v28, v32, v28
	s_waitcnt vmcnt(4)
	v_add_f32_e32 v32, 1.0, v36
	v_mul_f32_e32 v29, v33, v29
	v_add_f32_e32 v33, 1.0, v37
	v_mul_f32_e32 v30, v34, v30
	v_add_f32_e32 v34, 1.0, v38
	v_mul_f32_e32 v31, v35, v31
	v_add_f32_e32 v35, 1.0, v39
	s_waitcnt vmcnt(3)
	v_mul_f32_e32 v24, v24, v72
	s_waitcnt vmcnt(2)
	v_add_f32_e32 v36, 1.0, v76
	v_mul_f32_e32 v25, v25, v73
	v_add_f32_e32 v37, 1.0, v77
	v_mul_f32_e32 v26, v26, v74
	v_add_f32_e32 v38, 1.0, v78
	v_mul_f32_e32 v27, v27, v75
	v_add_f32_e32 v39, 1.0, v79
	s_waitcnt vmcnt(1)
	v_fma_f32 v28, v32, v28, v80
	v_fma_f32 v29, v33, v29, v81
	v_fma_f32 v30, v34, v30, v82
	v_fmac_f32_e32 v83, v35, v31
	s_waitcnt vmcnt(0)
	v_fma_f32 v31, v24, v36, v84
	v_fma_f32 v32, v25, v37, v85
	v_fma_f32 v33, v26, v38, v86
	v_fmac_f32_e32 v87, v27, v39
	v_cvt_pk_bf16_f32 v24, v28, v29
	v_cvt_pk_bf16_f32 v25, v30, v83
	v_cvt_pk_bf16_f32 v26, v31, v32
	v_cvt_pk_bf16_f32 v27, v33, v87
	global_store_dwordx4 v[62:63], v[24:27], off offset:1024
	v_add_co_u32_e32 v80, vcc, s27, v58
	global_load_dwordx4 v[24:27], v[48:49], off
	global_load_dwordx4 v[28:31], v[60:61], off
	v_lshl_add_u64 v[72:73], v[58:59], 0, s[20:21]
	global_load_dwordx4 v[32:35], v[48:49], off offset:16
	global_load_dwordx4 v[36:39], v[72:73], off offset:16
	v_addc_co_u32_e32 v81, vcc, 0, v59, vcc
	v_lshl_add_u64 v[76:77], v[58:59], 0, s[4:5]
	global_load_dwordx4 v[72:75], v[80:81], off
	v_cmp_lt_i32_e32 vcc, s31, v54
	global_load_dwordx4 v[76:79], v[76:77], off offset:16
	s_or_b64 s[14:15], vcc, s[14:15]
	s_waitcnt vmcnt(5)
	v_mul_f32_e32 v20, v20, v24
	s_waitcnt vmcnt(4)
	v_add_f32_e32 v24, 1.0, v28
	v_mul_f32_e32 v21, v21, v25
	v_add_f32_e32 v25, 1.0, v29
	v_mul_f32_e32 v22, v22, v26
	v_add_f32_e32 v26, 1.0, v30
	v_mul_f32_e32 v23, v23, v27
	v_add_f32_e32 v27, 1.0, v31
	s_waitcnt vmcnt(3)
	v_mul_f32_e32 v16, v16, v32
	s_waitcnt vmcnt(2)
	v_add_f32_e32 v28, 1.0, v36
	v_mul_f32_e32 v17, v17, v33
	v_add_f32_e32 v29, 1.0, v37
	v_mul_f32_e32 v18, v18, v34
	v_add_f32_e32 v30, 1.0, v38
	v_mul_f32_e32 v19, v19, v35
	v_add_f32_e32 v31, 1.0, v39
	s_waitcnt vmcnt(1)
	v_fma_f32 v20, v20, v24, v72
	v_fma_f32 v21, v21, v25, v73
	v_fma_f32 v22, v22, v26, v74
	v_fmac_f32_e32 v75, v23, v27
	s_waitcnt vmcnt(0)
	v_fma_f32 v23, v16, v28, v76
	v_fma_f32 v24, v17, v29, v77
	v_fma_f32 v25, v18, v30, v78
	v_fmac_f32_e32 v79, v19, v31
	v_cvt_pk_bf16_f32 v16, v20, v21
	v_cvt_pk_bf16_f32 v17, v22, v75
	v_cvt_pk_bf16_f32 v18, v23, v24
	v_cvt_pk_bf16_f32 v19, v25, v79
	global_store_dwordx4 v[62:63], v[16:19], off offset:2048
	v_lshl_add_u64 v[36:37], v[58:59], 0, s[22:23]
	global_load_dwordx4 v[16:19], v[50:51], off
	global_load_dwordx4 v[20:23], v[60:61], off offset:2048
	global_load_dwordx4 v[24:27], v[50:51], off offset:16
	global_load_dwordx4 v[28:31], v[36:37], off offset:16
	global_load_dwordx4 v[32:35], v[80:81], off offset:2048
	v_lshl_add_u64 v[36:37], v[58:59], 0, s[6:7]
	global_load_dwordx4 v[36:39], v[36:37], off offset:16
	s_waitcnt vmcnt(5)
	v_mul_f32_e32 v12, v12, v16
	s_waitcnt vmcnt(4)
	v_add_f32_e32 v16, 1.0, v20
	v_mul_f32_e32 v13, v13, v17
	v_add_f32_e32 v17, 1.0, v21
	v_mul_f32_e32 v14, v14, v18
	v_add_f32_e32 v18, 1.0, v22
	v_mul_f32_e32 v15, v15, v19
	v_add_f32_e32 v19, 1.0, v23
	s_waitcnt vmcnt(3)
	v_mul_f32_e32 v8, v8, v24
	s_waitcnt vmcnt(2)
	v_add_f32_e32 v20, 1.0, v28
	v_mul_f32_e32 v9, v9, v25
	v_add_f32_e32 v21, 1.0, v29
	v_mul_f32_e32 v10, v10, v26
	v_add_f32_e32 v22, 1.0, v30
	v_mul_f32_e32 v11, v11, v27
	v_add_f32_e32 v23, 1.0, v31
	s_waitcnt vmcnt(1)
	v_fma_f32 v12, v12, v16, v32
	v_fma_f32 v13, v13, v17, v33
	v_fma_f32 v14, v14, v18, v34
	v_fmac_f32_e32 v35, v15, v19
	s_waitcnt vmcnt(0)
	v_fma_f32 v15, v8, v20, v36
	v_fma_f32 v16, v9, v21, v37
	v_fma_f32 v17, v10, v22, v38
	v_fmac_f32_e32 v39, v11, v23
	v_cvt_pk_bf16_f32 v8, v12, v13
	v_cvt_pk_bf16_f32 v9, v14, v35
	v_cvt_pk_bf16_f32 v10, v15, v16
	v_cvt_pk_bf16_f32 v11, v17, v39
	global_store_dwordx4 v[62:63], v[8:11], off offset:3072
	s_andn2_b64 exec, exec, s[14:15]
	s_cbranch_execz .LBB0_206

; __device__ __forceinline__ unsigned cvt_pk_bf16(float lo, float hi) { unsigned r; asm volatile("v_cvt_pk_bf16_f32 %0, %1, %2" : "=v"(r) : "v"(lo), "v"(hi)); return r; }
; __device__ __forceinline__ float lo_f(unsigned w) { return __uint_as_float(w << 16); }
; __device__ __forceinline__ float hi_f(unsigned w) { return __uint_as_float(w & 0xffff0000u); }
; __device__ void phase_post(const Ctx& c, int l, bool ctx_full) {
;     ...
;         for (int p = full ? 0 : 4; p < 5; ++p) {
;             const int hd = 4 * p + grp;
;             u32x4 raw;
;             if (full) raw = *(const u32x4*)(zr + hd * 128 + 8 * l16);
;             else raw = kv_share8(kvp + (size_t)(row - TL) * 1024 + grp * 128 + 8 * l16);
;             float own[8] = {lo_f(raw.x), hi_f(raw.x), lo_f(raw.y), hi_f(raw.y), lo_f(raw.z), hi_f(raw.z), lo_f(raw.w), hi_f(raw.w)};
;             float ss = 0.f;
; #pragma unroll
;             for (int i = 0; i < 8; ++i) ss += own[i] * own[i];
; #pragma unroll
;             for (int o = 8; o; o >>= 1) ss += __int_as_float(__builtin_amdgcn_ds_bpermute((c.lane ^ o) << 2, __float_as_int(ss)));
;             const float rstd = rsqrtf(ss * (1.f / 128.f) + EPS);
;             u32x4 pr;
;             pr.x = (unsigned)__builtin_amdgcn_ds_bpermute((c.lane ^ 4) << 2, (int)raw.x); pr.y = (unsigned)__builtin_amdgcn_ds_bpermute((c.lane ^ 4) << 2, (int)raw.y);
;             pr.z = (unsigned)__builtin_amdgcn_ds_bpermute((c.lane ^ 4) << 2, (int)raw.z); pr.w = (unsigned)__builtin_amdgcn_ds_bpermute((c.lane ^ 4) << 2, (int)raw.w);
;             const float par[8] = {lo_f(pr.x), hi_f(pr.x), lo_f(pr.y), hi_f(pr.y), lo_f(pr.z), hi_f(pr.z), lo_f(pr.w), hi_f(pr.w)};
;             float o8[8];
; #pragma unroll
;             for (int i = 0; i < 8; ++i) { const float on = own[i] * rstd * (p < 4 ? gqo[i] : gko[i]), pn = par[i] * rstd * (p < 4 ? gqp[i] : gkp[i]);
;                 o8[i] = firsth ? on * cs[i] - pn * sn[i] : on * cs[i] + pn * sn[i]; }
;             u32x4 w; w.x = cvt_pk_bf16(o8[0], o8[1]); w.y = cvt_pk_bf16(o8[2], o8[3]); w.z = cvt_pk_bf16(o8[4], o8[5]); w.w = cvt_pk_bf16(o8[6], o8[7]);
;             if (p < 4) *(u32x4*)(Qo + (size_t)row * DM + hd * 128 + 8 * l16) = w;
;             else *(u32x4*)(Ko + kvrow * 512 + grp * 128 + 8 * l16) = w;
.LBB0_373:
	s_nop 0
	v_mov_b64_e32 v[80:81], v[116:117]
	v_mov_b64_e32 v[82:83], v[118:119]
	v_mov_b64_e32 v[116:117], v[120:121]
	v_mov_b64_e32 v[118:119], v[122:123]
	v_mov_b64_e32 v[120:121], v[124:125]
	v_mov_b64_e32 v[122:123], v[126:127]
	v_mov_b64_e32 v[124:125], v[128:129]
	v_mov_b64_e32 v[126:127], v[130:131]
	v_lshl_add_u64 v[84:85], v[72:73], 0, s[2:3]
	s_add_u32 s2, s2, 0x400
	s_addc_u32 s3, s3, 0
	s_cmpk_eq_i32 s2, 0x1000
	v_and_b32_e32 v77, 0xffff0000, v80
	v_lshlrev_b32_e32 v49, 16, v80
	v_and_b32_e32 v86, 0xffff0000, v81
	v_lshlrev_b32_e32 v87, 16, v81
	v_mul_f32_e32 v109, v77, v77
	ds_bpermute_b32 v79, v88, v80
	ds_bpermute_b32 v106, v88, v81
	v_pk_mul_f32 v[80:81], v[86:87], v[86:87]
	v_fmac_f32_e32 v109, v49, v49
	v_and_b32_e32 v100, 0xffff0000, v82
	v_lshlrev_b32_e32 v101, 16, v82
	v_add_f32_e32 v81, v81, v109
	v_and_b32_e32 v102, 0xffff0000, v83
	v_lshlrev_b32_e32 v103, 16, v83
	ds_bpermute_b32 v107, v88, v82
	ds_bpermute_b32 v108, v88, v83
	v_pk_mul_f32 v[82:83], v[100:101], v[100:101]
	v_add_f32_e32 v80, v80, v81
	v_add_f32_e32 v80, v83, v80
	v_pk_mul_f32 v[104:105], v[102:103], v[102:103]
	v_add_f32_e32 v80, v82, v80
	v_add_f32_e32 v80, v105, v80
	v_add_f32_e32 v80, v104, v80
	s_waitcnt lgkmcnt(3)
	v_lshlrev_b32_e32 v81, 16, v79
	s_waitcnt lgkmcnt(2)
	v_lshlrev_b32_e32 v83, 16, v106
	v_and_b32_e32 v79, 0xffff0000, v79
	v_and_b32_e32 v106, 0xffff0000, v106
	s_waitcnt lgkmcnt(0)
	s_nop 1
	v_add_f32_dpp v80, v80, v80 row_mirror row_mask:0xf bank_mask:0xf
	v_lshlrev_b32_e32 v109, 16, v107
	v_and_b32_e32 v107, 0xffff0000, v107
	v_lshlrev_b32_e32 v110, 16, v108
	v_and_b32_e32 v108, 0xffff0000, v108
	s_waitcnt lgkmcnt(0)
	s_nop 1
	v_add_f32_dpp v80, v80, v80 row_half_mirror row_mask:0xf bank_mask:0xf
	s_waitcnt lgkmcnt(0)
	s_nop 1
	v_add_f32_dpp v80, v80, v80 quad_perm:[2,3,0,1] row_mask:0xf bank_mask:0xf
	s_waitcnt lgkmcnt(0)
	s_nop 1
	v_add_f32_dpp v80, v80, v80 quad_perm:[1,0,3,2] row_mask:0xf bank_mask:0xf
	v_fmamk_f32 v80, v80, 0x3c000000, v94
	v_mul_f32_e32 v82, 0x4b800000, v80
	v_cmp_gt_f32_e32 vcc, s29, v80
	s_nop 1
	v_cndmask_b32_e32 v80, v80, v82, vcc
	v_rsq_f32_e32 v80, v80
	s_nop 0
	v_mul_f32_e32 v82, 0x45800000, v80
	v_cndmask_b32_e32 v80, v80, v82, vcc
	v_mul_f32_e32 v81, v80, v81
	v_mul_f32_e32 v83, v80, v83
	v_mul_f32_e32 v49, v80, v49
	v_mul_f32_e32 v77, v80, v77
	v_mul_f32_e32 v79, v80, v79
	v_mul_f32_e32 v82, v80, v87
	v_mul_f32_e32 v86, v80, v86
	v_mul_f32_e32 v87, v80, v106
	v_mul_f32_e32 v101, v80, v101
	v_mul_f32_e32 v104, v80, v109
	v_mul_f32_e32 v100, v80, v100
	v_mul_f32_e32 v105, v80, v107
	v_mul_f32_e32 v103, v80, v103
	v_mul_f32_e32 v106, v80, v110
	v_mul_f32_e32 v102, v80, v102
	v_mul_f32_e32 v80, v80, v108
	v_mul_f32_e32 v81, v43, v81
	v_mul_f32_e32 v83, v17, v83
	v_mul_f32_e32 v79, v16, v79
	v_mul_f32_e32 v87, v18, v87
	v_mul_f32_e32 v104, v19, v104
	v_mul_f32_e32 v105, v40, v105
	v_mul_f32_e32 v106, v41, v106
	v_mul_f32_e32 v80, v42, v80
	v_mul_f32_e32 v81, v25, v81
	v_mul_f32_e32 v83, v29, v83
	v_mul_f32_e32 v49, v0, v49
	v_mul_f32_e32 v82, v2, v82
	v_mul_f32_e32 v79, v27, v79
	v_mul_f32_e32 v87, v31, v87
	v_mul_f32_e32 v104, v33, v104
	v_mul_f32_e32 v105, v35, v105
	v_mul_f32_e32 v106, v37, v106
	v_mul_f32_e32 v80, v39, v80
	v_cndmask_b32_e64 v81, v81, -v81, s[4:5]
	v_cndmask_b32_e64 v83, v83, -v83, s[4:5]
	v_mul_f32_e32 v77, v1, v77
	v_mul_f32_e32 v86, v3, v86
	v_mul_f32_e32 v101, v8, v101
	v_mul_f32_e32 v100, v9, v100
	v_mul_f32_e32 v103, v10, v103
	v_mul_f32_e32 v102, v11, v102
	v_cndmask_b32_e64 v79, v79, -v79, s[4:5]
	v_cndmask_b32_e64 v87, v87, -v87, s[4:5]
	v_cndmask_b32_e64 v104, v104, -v104, s[4:5]
	v_cndmask_b32_e64 v105, v105, -v105, s[4:5]
	v_cndmask_b32_e64 v106, v106, -v106, s[4:5]
	v_cndmask_b32_e64 v107, v80, -v80, s[4:5]
	v_fmac_f32_e32 v81, v24, v49
	v_fmac_f32_e32 v83, v28, v82
	v_fmac_f32_e32 v79, v26, v77
	v_fmac_f32_e32 v87, v30, v86
	v_fmac_f32_e32 v104, v32, v101
	v_fmac_f32_e32 v105, v34, v100
	v_fmac_f32_e32 v106, v36, v103
	v_fmac_f32_e32 v107, v38, v102
	v_cvt_pk_bf16_f32 v80, v81, v79
	v_cvt_pk_bf16_f32 v81, v83, v87
	v_cvt_pk_bf16_f32 v82, v104, v105
	v_cvt_pk_bf16_f32 v83, v106, v107
	global_store_dwordx4 v[84:85], v[80:83], off
	s_cbranch_scc0 .LBB0_373
	s_nop 0
	v_mov_b64_e32 v[80:81], s[16:17]
	v_mad_i64_i32 v[80:81], s[2:3], v48, s23, v[80:81]
	v_mov_b32_e32 v77, v51
	v_lshl_add_u64 v[82:83], v[80:81], 0, v[76:77]
	v_mov_b32_e32 v79, v51
	v_lshl_add_u64 v[82:83], v[82:83], 0, v[78:79]
	v_add_co_u32_e32 v82, vcc, s30, v82
	v_add_u32_e32 v49, 0xffffe000, v48
	s_nop 0
	v_addc_co_u32_e32 v83, vcc, 0, v83, vcc
	v_mov_b64_e32 v[84:85], v[132:133]
	v_mov_b64_e32 v[86:87], v[134:135]
	v_ashrrev_i32_e32 v77, 11, v48
	v_lshrrev_b32_e32 v49, 8, v49
	v_or_b32_e32 v79, 0x800, v99
	v_cndmask_b32_e64 v49, v49, v77, s[6:7]
	v_mov_b32_e32 v101, v51
	v_and_b32_e32 v113, 0xffff0000, v84
	v_lshlrev_b32_e32 v112, 16, v84
	v_and_b32_e32 v102, 0xffff0000, v85
	v_lshlrev_b32_e32 v103, 16, v85
	v_mul_f32_e32 v100, v113, v113
	v_pk_mul_f32 v[82:83], v[102:103], v[102:103]
	v_fmac_f32_e32 v100, v112, v112
	v_and_b32_e32 v104, 0xffff0000, v86
	v_lshlrev_b32_e32 v105, 16, v86
	v_add_f32_e32 v83, v83, v100
	v_pk_mul_f32 v[108:109], v[104:105], v[104:105]
	v_add_f32_e32 v82, v82, v83
	v_and_b32_e32 v106, 0xffff0000, v87
	v_lshlrev_b32_e32 v107, 16, v87
	v_add_f32_e32 v82, v109, v82
	v_pk_mul_f32 v[110:111], v[106:107], v[106:107]
	v_add_f32_e32 v82, v108, v82
	v_add_f32_e32 v82, v111, v82
	v_add_f32_e32 v108, v110, v82
	ds_bpermute_b32 v109, v57, v108
	v_cndmask_b32_e64 v100, v79, v99, s[6:7]
	v_mad_i64_i32 v[100:101], s[2:3], v49, s31, v[100:101]
	ds_bpermute_b32 v49, v88, v84
	s_waitcnt lgkmcnt(1)
; __device__ __forceinline__ float lo_f(unsigned w) { return __uint_as_float(w << 16); }
; __device__ void phase_post(const Ctx& c, int l, bool ctx_full) {
;     ...
;         for (int p = full ? 0 : 4; p < 5; ++p) {
;             const int hd = 4 * p + grp;
;             u32x4 raw;
;             if (full) raw = *(const u32x4*)(zr + hd * 128 + 8 * l16);
;             else raw = kv_share8(kvp + (size_t)(row - TL) * 1024 + grp * 128 + 8 * l16);
;             float own[8] = {lo_f(raw.x), hi_f(raw.x), lo_f(raw.y), hi_f(raw.y), lo_f(raw.z), hi_f(raw.z), lo_f(raw.w), hi_f(raw.w)};
;             float ss = 0.f;
; #pragma unroll
;             for (int i = 0; i < 8; ++i) ss += own[i] * own[i];
; #pragma unroll
;             for (int o = 8; o; o >>= 1) ss += __int_as_float(__builtin_amdgcn_ds_bpermute((c.lane ^ o) << 2, __float_as_int(ss)));
;             const float rstd = rsqrtf(ss * (1.f / 128.f) + EPS);
;             u32x4 pr;
;             pr.x = (unsigned)__builtin_amdgcn_ds_bpermute((c.lane ^ 4) << 2, (int)raw.x); pr.y = (unsigned)__builtin_amdgcn_ds_bpermute((c.lane ^ 4) << 2, (int)raw.y);
;             pr.z = (unsigned)__builtin_amdgcn_ds_bpermute((c.lane ^ 4) << 2, (int)raw.z); pr.w = (unsigned)__builtin_amdgcn_ds_bpermute((c.lane ^ 4) << 2, (int)raw.w);
;             const float par[8] = {lo_f(pr.x), hi_f(pr.x), lo_f(pr.y), hi_f(pr.y), lo_f(pr.z), hi_f(pr.z), lo_f(pr.w), hi_f(pr.w)};
;             float o8[8];
; #pragma unroll
;             for (int i = 0; i < 8; ++i) { const float on = own[i] * rstd * (p < 4 ? gqo[i] : gko[i]), pn = par[i] * rstd * (p < 4 ? gqp[i] : gkp[i]);
;                 o8[i] = firsth ? on * cs[i] - pn * sn[i] : on * cs[i] + pn * sn[i]; }
;             u32x4 w; w.x = cvt_pk_bf16(o8[0], o8[1]); w.y = cvt_pk_bf16(o8[2], o8[3]); w.z = cvt_pk_bf16(o8[4], o8[5]); w.w = cvt_pk_bf16(o8[6], o8[7]);
;             if (p < 4) *(u32x4*)(Qo + (size_t)row * DM + hd * 128 + 8 * l16) = w;
;             else *(u32x4*)(Ko + kvrow * 512 + grp * 128 + 8 * l16) = w;
;         }
;         if (!full) *(u32x4*)(Vo + kvrow * 512 + c.lane * 8) = kv_share8(kvp + (size_t)(row - TL) * 1024 + 512 + c.lane * 8);
;         if (full) {
;             float fv[16]; float ss = 0.f;
; #pragma unroll
;             for (int i = 0; i < 2; ++i) { const int cc = i * 512 + c.lane * 8;
;                 const u32x4 zv = *(const u32x4*)(zr + OFF_GV + cc);
	v_add_f32_e32 v77, v108, v109
	ds_bpermute_b32 v84, v88, v85
	ds_bpermute_b32 v85, v88, v86
	ds_bpermute_b32 v86, v88, v87
	s_waitcnt lgkmcnt(3)
	v_lshlrev_b32_e32 v87, 16, v49
	s_waitcnt lgkmcnt(3)
	s_nop 1
	v_add_f32_dpp v77, v77, v77 row_half_mirror row_mask:0xf bank_mask:0xf
	v_and_b32_e32 v49, 0xffff0000, v49
	s_waitcnt lgkmcnt(1)
	v_lshlrev_b32_e32 v109, 16, v85
	v_lshlrev_b32_e32 v108, 16, v84
	v_and_b32_e32 v84, 0xffff0000, v84
	s_waitcnt lgkmcnt(0)
	s_nop 1
	v_add_f32_dpp v77, v77, v77 quad_perm:[2,3,0,1] row_mask:0xf bank_mask:0xf
	v_lshl_add_u64 v[82:83], v[80:81], 0, v[50:51]
	v_lshlrev_b64 v[100:101], 10, v[100:101]
	v_lshl_add_u64 v[100:101], v[52:53], 0, v[100:101]
	s_waitcnt lgkmcnt(0)
	s_nop 1
	v_add_f32_dpp v77, v77, v77 quad_perm:[1,0,3,2] row_mask:0xf bank_mask:0xf
	v_fmamk_f32 v77, v77, 0x3c000000, v94
	v_mul_f32_e32 v79, 0x4b800000, v77
	v_cmp_gt_f32_e32 vcc, s29, v77
	s_nop 1
	v_cndmask_b32_e32 v77, v77, v79, vcc
	v_rsq_f32_e32 v77, v77
	v_and_b32_e32 v79, 0xffff0000, v85
	v_lshlrev_b32_e32 v85, 16, v86
	v_and_b32_e32 v86, 0xffff0000, v86
	v_mul_f32_e32 v110, 0x45800000, v77
	v_cndmask_b32_e32 v77, v77, v110, vcc
	v_mul_f32_e32 v87, v77, v87
	v_mul_f32_e32 v49, v77, v49
	v_mul_f32_e32 v109, v77, v109
	v_mul_f32_e32 v110, v77, v112
	v_mul_f32_e32 v111, v77, v113
	v_mul_f32_e32 v103, v77, v103
	v_mul_f32_e32 v108, v77, v108
	v_mul_f32_e32 v102, v77, v102
	v_mul_f32_e32 v84, v77, v84
	v_mul_f32_e32 v105, v77, v105
	v_mul_f32_e32 v104, v77, v104
	v_mul_f32_e32 v79, v77, v79
	v_mul_f32_e32 v107, v77, v107
	v_mul_f32_e32 v85, v77, v85
	v_mul_f32_e32 v106, v77, v106
	v_mul_f32_e32 v77, v77, v86
	v_mul_f32_e32 v87, v47, v87
	v_mul_f32_e32 v49, v20, v49
	v_mul_f32_e32 v109, v23, v109
	v_mul_f32_e32 v108, v21, v108
	v_mul_f32_e32 v84, v22, v84
	v_mul_f32_e32 v79, v44, v79
	v_mul_f32_e32 v85, v45, v85
	v_mul_f32_e32 v77, v46, v77
	v_mul_f32_e32 v25, v25, v87
	v_mul_f32_e32 v27, v27, v49
	v_mul_f32_e32 v33, v33, v109
	v_mul_f32_e32 v86, v4, v110
	v_mul_f32_e32 v110, v5, v111
	v_mul_f32_e32 v105, v12, v105
	v_mul_f32_e32 v29, v29, v108
	v_mul_f32_e32 v31, v31, v84
	v_mul_f32_e32 v35, v35, v79
	v_mul_f32_e32 v37, v37, v85
	v_mul_f32_e32 v39, v39, v77
	v_cndmask_b32_e64 v25, v25, -v25, s[4:5]
	v_cndmask_b32_e64 v27, v27, -v27, s[4:5]
	v_cndmask_b32_e64 v33, v33, -v33, s[4:5]
	v_mul_f32_e32 v103, v6, v103
	v_mul_f32_e32 v102, v7, v102
	v_mul_f32_e32 v104, v13, v104
	v_mul_f32_e32 v107, v14, v107
	v_mul_f32_e32 v106, v15, v106
	v_cndmask_b32_e64 v29, v29, -v29, s[4:5]
	v_cndmask_b32_e64 v31, v31, -v31, s[4:5]
	v_cndmask_b32_e64 v35, v35, -v35, s[4:5]
	v_cndmask_b32_e64 v37, v37, -v37, s[4:5]
	v_cndmask_b32_e64 v39, v39, -v39, s[4:5]
	v_fmac_f32_e32 v25, v24, v86
	v_fmac_f32_e32 v27, v26, v110
	v_fmac_f32_e32 v33, v32, v105
	v_add_co_u32_e32 v32, vcc, s28, v82
	v_fmac_f32_e32 v29, v28, v103
	v_fmac_f32_e32 v31, v30, v102
	v_fmac_f32_e32 v35, v34, v104
	v_fmac_f32_e32 v37, v36, v107
	v_fmac_f32_e32 v39, v38, v106
	v_cvt_pk_bf16_f32 v24, v25, v27
	v_cvt_pk_bf16_f32 v25, v29, v31
	v_cvt_pk_bf16_f32 v26, v33, v35
	v_cvt_pk_bf16_f32 v27, v37, v39
	global_store_dwordx4 v[100:101], v[24:27], off
	v_addc_co_u32_e32 v33, vcc, 0, v83, vcc
	v_mov_b64_e32 v[28:29], v[136:137]
	v_mov_b64_e32 v[30:31], v[138:139]
	v_mov_b64_e32 v[24:25], v[140:141]
	v_mov_b64_e32 v[26:27], v[142:143]
	v_lshlrev_b32_e32 v32, 16, v28
	v_and_b32_e32 v28, 0xffff0000, v28
	v_mul_f32_e32 v35, 0x3d372713, v32
	v_lshlrev_b32_e32 v33, 16, v29
	v_mul_f32_e32 v37, 0x3d372713, v28
	v_mul_f32_e32 v35, v35, v32
	v_mul_f32_e32 v36, 0.5, v32
	v_mul_f32_e32 v39, 0x3d372713, v33
	v_mul_f32_e32 v37, v37, v28
	v_fma_f32 v32, v35, v32, v32
	v_mul_f32_e32 v38, 0.5, v28
	v_mul_f32_e32 v39, v39, v33
	v_fma_f32 v28, v37, v28, v28
	v_mul_f32_e32 v32, 0x3f4c422a, v32
	v_mul_f32_e32 v49, 0.5, v33
	v_fma_f32 v33, v39, v33, v33
	v_mul_f32_e32 v28, 0x3f4c422a, v28
	v_add_f32_e32 v32, v32, v32
	v_mul_f32_e32 v33, 0x3f4c422a, v33
	v_add_f32_e32 v28, v28, v28
	v_mul_f32_e32 v32, 0x3fb8aa3b, v32
	v_add_f32_e32 v33, v33, v33
	v_mul_f32_e32 v28, 0x3fb8aa3b, v28
	v_exp_f32_e32 v32, v32
	v_mul_f32_e32 v33, 0x3fb8aa3b, v33
	v_exp_f32_e32 v28, v28
	v_exp_f32_e32 v33, v33
	v_lshlrev_b32_e32 v34, 16, v30
	v_mul_f32_e32 v79, 0x3d372713, v34
	v_add_f32_e32 v32, 1.0, v32
	v_and_b32_e32 v29, 0xffff0000, v29
	v_mul_f32_e32 v79, v79, v34
	v_add_f32_e32 v28, 1.0, v28
	v_div_scale_f32 v39, s[2:3], v32, v32, 2.0
	v_mul_f32_e32 v77, 0x3d372713, v29
	v_fma_f32 v37, v79, v34, v34
	v_add_f32_e32 v33, 1.0, v33
	v_div_scale_f32 v79, s[2:3], v28, v28, 2.0
	v_rcp_f32_e32 v101, v39
	v_mul_f32_e32 v77, v77, v29
	v_div_scale_f32 v85, s[8:9], v33, v33, 2.0
	v_rcp_f32_e32 v102, v79
	v_fma_f32 v35, v77, v29, v29
	v_rcp_f32_e32 v103, v85
	v_mul_f32_e32 v35, 0x3f4c422a, v35
	v_add_f32_e32 v35, v35, v35
	v_fma_f32 v105, -v39, v101, 1.0
	v_mul_f32_e32 v35, 0x3fb8aa3b, v35
	v_div_scale_f32 v77, vcc, 2.0, v32, 2.0
	v_fma_f32 v106, -v79, v102, 1.0
	v_fmac_f32_e32 v101, v105, v101
	v_exp_f32_e32 v35, v35
	v_div_scale_f32 v84, s[2:3], 2.0, v28, 2.0
	v_fma_f32 v107, -v85, v103, 1.0
	v_fmac_f32_e32 v102, v106, v102
	v_mul_f32_e32 v105, v77, v101
	v_div_scale_f32 v86, s[8:9], 2.0, v33, 2.0
	v_fmac_f32_e32 v103, v107, v103
	v_mul_f32_e32 v106, v84, v102
	v_fma_f32 v109, -v39, v105, v77
	v_mul_f32_e32 v107, v86, v103
	v_fma_f32 v110, -v79, v106, v84
	v_fmac_f32_e32 v105, v109, v101
	v_fma_f32 v111, -v85, v107, v86
	v_fmac_f32_e32 v106, v110, v102
	v_fma_f32 v39, -v39, v105, v77
	v_add_f32_e32 v35, 1.0, v35
	v_fmac_f32_e32 v107, v111, v103
	v_fma_f32 v77, -v79, v106, v84
	v_div_fmas_f32 v39, v39, v101, v105
	s_mov_b64 vcc, s[2:3]
; __device__ __forceinline__ float lo_f(unsigned w) { return __uint_as_float(w << 16); }
; __device__ __forceinline__ float hi_f(unsigned w) { return __uint_as_float(w & 0xffff0000u); }
; __device__ __forceinline__ float gelu_tanh(float x) {
;     const float y = 0.7978845608028654f * (x + 0.044715f * x * x * x);
;     const float e = __expf(2.f * y);
;     const float th = 1.f - 2.f / (e + 1.f);
;     return 0.5f * x * (1.f + th);
; }
; __device__ void phase_post(const Ctx& c, int l, bool ctx_full) {
;     ...
;             for (int i = 0; i < 2; ++i) { const int cc = i * 512 + c.lane * 8;
;                 const u32x4 zv = *(const u32x4*)(zr + OFF_GV + cc);
;                 fv[i * 8 + 0] = gelu_tanh(lo_f(zv.x)); fv[i * 8 + 1] = gelu_tanh(hi_f(zv.x)); fv[i * 8 + 2] = gelu_tanh(lo_f(zv.y)); fv[i * 8 + 3] = gelu_tanh(hi_f(zv.y));
;                 fv[i * 8 + 4] = gelu_tanh(lo_f(zv.z)); fv[i * 8 + 5] = gelu_tanh(hi_f(zv.z)); fv[i * 8 + 6] = gelu_tanh(lo_f(zv.w)); fv[i * 8 + 7] = gelu_tanh(hi_f(zv.w));
; #pragma unroll
;                 for (int j = 0; j < 8; ++j) ss += fv[i * 8 + j] * fv[i * 8 + j]; }
	v_div_scale_f32 v87, s[10:11], v35, v35, 2.0
	v_fma_f32 v79, -v85, v107, v86
	v_div_fixup_f32 v32, v39, v32, 2.0
	v_div_fmas_f32 v39, v77, v102, v106
	s_mov_b64 vcc, s[8:9]
	v_rcp_f32_e32 v104, v87
	v_sub_f32_e32 v32, 1.0, v32
	v_div_fixup_f32 v28, v39, v28, 2.0
	v_div_fmas_f32 v39, v79, v103, v107
	v_add_f32_e32 v32, 1.0, v32
	v_sub_f32_e32 v28, 1.0, v28
	v_div_fixup_f32 v33, v39, v33, 2.0
	v_mul_f32_e32 v37, 0x3f4c422a, v37
	v_mul_f32_e32 v77, v36, v32
	v_add_f32_e32 v28, 1.0, v28
	v_sub_f32_e32 v32, 1.0, v33
	v_add_f32_e32 v37, v37, v37
	v_mul_f32_e32 v79, v38, v28
	v_add_f32_e32 v28, 1.0, v32
	v_fma_f32 v108, -v87, v104, 1.0
	v_mul_f32_e32 v85, v49, v28
	v_mul_f32_e32 v28, 0x3fb8aa3b, v37
	v_div_scale_f32 v100, s[10:11], 2.0, v35, 2.0
	v_fmac_f32_e32 v104, v108, v104
	v_exp_f32_e32 v28, v28
	v_mul_f32_e32 v108, v100, v104
	v_fma_f32 v112, -v87, v108, v100
	v_fmac_f32_e32 v108, v112, v104
	v_fma_f32 v84, -v87, v108, v100
	s_mov_b64 vcc, s[10:11]
	v_add_f32_e32 v28, 1.0, v28
	v_div_fmas_f32 v32, v84, v104, v108
	v_div_scale_f32 v33, s[2:3], v28, v28, 2.0
	v_div_fixup_f32 v32, v32, v35, 2.0
	v_rcp_f32_e32 v35, v33
	v_sub_f32_e32 v32, 1.0, v32
	v_mul_f32_e32 v29, 0.5, v29
	v_add_f32_e32 v32, 1.0, v32
	v_mul_f32_e32 v84, v29, v32
	v_fma_f32 v29, -v33, v35, 1.0
	v_fmac_f32_e32 v35, v29, v35
	v_div_scale_f32 v29, vcc, 2.0, v28, 2.0
	v_mul_f32_e32 v32, v29, v35
	v_fma_f32 v36, -v33, v32, v29
	v_fmac_f32_e32 v32, v36, v35
	v_and_b32_e32 v30, 0xffff0000, v30
	v_fma_f32 v29, -v33, v32, v29
	v_mul_f32_e32 v33, 0x3d372713, v30
	v_mul_f32_e32 v33, v33, v30
	v_fma_f32 v33, v33, v30, v30
	v_mul_f32_e32 v33, 0x3f4c422a, v33
	v_add_f32_e32 v33, v33, v33
	v_mul_f32_e32 v33, 0x3fb8aa3b, v33
	v_exp_f32_e32 v33, v33
	v_div_fmas_f32 v29, v29, v35, v32
	v_div_fixup_f32 v28, v29, v28, 2.0
	v_sub_f32_e32 v28, 1.0, v28
	v_add_f32_e32 v29, 1.0, v33
	v_div_scale_f32 v32, s[2:3], v29, v29, 2.0
	v_rcp_f32_e32 v33, v32
	v_mul_f32_e32 v34, 0.5, v34
	v_add_f32_e32 v28, 1.0, v28
	v_mul_f32_e32 v86, v34, v28
	v_fma_f32 v28, -v32, v33, 1.0
	v_fmac_f32_e32 v33, v28, v33
	v_div_scale_f32 v28, vcc, 2.0, v29, 2.0
	v_mul_f32_e32 v34, v28, v33
	v_fma_f32 v35, -v32, v34, v28
	v_fmac_f32_e32 v34, v35, v33
	v_fma_f32 v28, -v32, v34, v28
	v_lshlrev_b32_e32 v32, 16, v31
	v_mul_f32_e32 v35, 0x3d372713, v32
	v_mul_f32_e32 v35, v35, v32
	v_fma_f32 v35, v35, v32, v32
	v_mul_f32_e32 v35, 0x3f4c422a, v35
	v_add_f32_e32 v35, v35, v35
	v_mul_f32_e32 v35, 0x3fb8aa3b, v35
	v_exp_f32_e32 v35, v35
	v_div_fmas_f32 v28, v28, v33, v34
	v_div_fixup_f32 v28, v28, v29, 2.0
	v_sub_f32_e32 v28, 1.0, v28
	v_add_f32_e32 v29, 1.0, v35
	v_div_scale_f32 v33, s[2:3], v29, v29, 2.0
	v_rcp_f32_e32 v34, v33
	v_mul_f32_e32 v30, 0.5, v30
	v_add_f32_e32 v28, 1.0, v28
	v_mul_f32_e32 v87, v30, v28
	v_fma_f32 v28, -v33, v34, 1.0
	v_fmac_f32_e32 v34, v28, v34
	v_div_scale_f32 v28, vcc, 2.0, v29, 2.0
	v_mul_f32_e32 v30, v28, v34
	v_fma_f32 v35, -v33, v30, v28
	v_fmac_f32_e32 v30, v35, v34
	v_and_b32_e32 v31, 0xffff0000, v31
	v_fma_f32 v28, -v33, v30, v28
	v_mul_f32_e32 v33, 0x3d372713, v31
	v_mul_f32_e32 v33, v33, v31
	v_fma_f32 v33, v33, v31, v31
	v_mul_f32_e32 v33, 0x3f4c422a, v33
	v_add_f32_e32 v33, v33, v33
	v_mul_f32_e32 v33, 0x3fb8aa3b, v33
	v_exp_f32_e32 v33, v33
	v_div_fmas_f32 v28, v28, v34, v30
	v_div_fixup_f32 v28, v28, v29, 2.0
	v_sub_f32_e32 v28, 1.0, v28
	v_add_f32_e32 v29, 1.0, v33
	v_div_scale_f32 v30, s[2:3], v29, v29, 2.0
	v_rcp_f32_e32 v33, v30
	v_mul_f32_e32 v32, 0.5, v32
	v_add_f32_e32 v28, 1.0, v28
	v_mul_f32_e32 v100, v32, v28
	v_fma_f32 v28, -v30, v33, 1.0
	v_fmac_f32_e32 v33, v28, v33
	v_div_scale_f32 v28, vcc, 2.0, v29, 2.0
	v_mul_f32_e32 v32, v28, v33
	v_fma_f32 v34, -v30, v32, v28
	v_fmac_f32_e32 v32, v34, v33
	v_fma_f32 v28, -v30, v32, v28
	v_div_fmas_f32 v28, v28, v33, v32
	v_div_fixup_f32 v28, v28, v29, 2.0
	v_sub_f32_e32 v28, 1.0, v28
	v_mul_f32_e32 v29, 0.5, v31
	v_add_f32_e32 v28, 1.0, v28
	v_mul_f32_e32 v101, v29, v28
	v_lshlrev_b32_e32 v28, 16, v24
	v_mul_f32_e32 v29, 0x3d372713, v28
	v_mul_f32_e32 v29, v29, v28
	v_fma_f32 v29, v29, v28, v28
	v_mul_f32_e32 v29, 0x3f4c422a, v29
	v_add_f32_e32 v29, v29, v29
	v_mul_f32_e32 v29, 0x3fb8aa3b, v29
	v_exp_f32_e32 v29, v29
	v_and_b32_e32 v24, 0xffff0000, v24
	v_mul_f32_e32 v28, 0.5, v28
	v_mul_f32_e32 v30, v79, v79
	v_add_f32_e32 v29, 1.0, v29
	v_div_scale_f32 v31, s[2:3], v29, v29, 2.0
	v_rcp_f32_e32 v32, v31
	v_fmac_f32_e32 v30, v77, v77
	v_fmac_f32_e32 v30, v85, v85
	v_fmac_f32_e32 v30, v84, v84
	v_fma_f32 v33, -v31, v32, 1.0
	v_fmac_f32_e32 v32, v33, v32
	v_div_scale_f32 v33, vcc, 2.0, v29, 2.0
	v_mul_f32_e32 v34, v33, v32
	v_fma_f32 v35, -v31, v34, v33
	v_fmac_f32_e32 v34, v35, v32
	v_fma_f32 v31, -v31, v34, v33
	v_mul_f32_e32 v33, 0x3d372713, v24
	v_mul_f32_e32 v33, v33, v24
	v_fma_f32 v33, v33, v24, v24
	v_mul_f32_e32 v33, 0x3f4c422a, v33
	v_add_f32_e32 v33, v33, v33
	v_mul_f32_e32 v33, 0x3fb8aa3b, v33
	v_exp_f32_e32 v33, v33
	v_div_fmas_f32 v31, v31, v32, v34
	v_div_fixup_f32 v29, v31, v29, 2.0
	v_sub_f32_e32 v29, 1.0, v29
	v_add_f32_e32 v31, 1.0, v33
	v_div_scale_f32 v32, s[2:3], v31, v31, 2.0
	v_rcp_f32_e32 v33, v32
	v_add_f32_e32 v29, 1.0, v29
	v_mul_f32_e32 v102, v28, v29
	v_mul_f32_e32 v24, 0.5, v24
	v_fma_f32 v28, -v32, v33, 1.0
	v_fmac_f32_e32 v33, v28, v33
	v_div_scale_f32 v28, vcc, 2.0, v31, 2.0
	v_mul_f32_e32 v29, v28, v33
	v_fma_f32 v34, -v32, v29, v28
	v_fmac_f32_e32 v29, v34, v33
	v_fma_f32 v28, -v32, v29, v28
	v_lshlrev_b32_e32 v32, 16, v25
	v_mul_f32_e32 v34, 0x3d372713, v32
	v_mul_f32_e32 v34, v34, v32
	v_fma_f32 v34, v34, v32, v32
	v_mul_f32_e32 v34, 0x3f4c422a, v34
	v_add_f32_e32 v34, v34, v34
; __device__ __forceinline__ float lo_f(unsigned w) { return __uint_as_float(w << 16); }
; __device__ __forceinline__ float hi_f(unsigned w) { return __uint_as_float(w & 0xffff0000u); }
; __device__ void phase_post(const Ctx& c, int l, bool ctx_full) {
;     ...
;             for (int i = 0; i < 2; ++i) { const int cc = i * 512 + c.lane * 8;
;                 const u32x4 zv = *(const u32x4*)(zr + OFF_GV + cc);
;                 fv[i * 8 + 0] = gelu_tanh(lo_f(zv.x)); fv[i * 8 + 1] = gelu_tanh(hi_f(zv.x)); fv[i * 8 + 2] = gelu_tanh(lo_f(zv.y)); fv[i * 8 + 3] = gelu_tanh(hi_f(zv.y));
;                 fv[i * 8 + 4] = gelu_tanh(lo_f(zv.z)); fv[i * 8 + 5] = gelu_tanh(hi_f(zv.z)); fv[i * 8 + 6] = gelu_tanh(lo_f(zv.w)); fv[i * 8 + 7] = gelu_tanh(hi_f(zv.w));
; #pragma unroll
;                 for (int j = 0; j < 8; ++j) ss += fv[i * 8 + j] * fv[i * 8 + j]; }
;             ss = wave_sum(ss, c.lane); const float rstd = rsqrtf(ss * (1.f / 1024.f) + EPS);
	v_mul_f32_e32 v34, 0x3fb8aa3b, v34
	v_exp_f32_e32 v34, v34
	v_div_fmas_f32 v28, v28, v33, v29
	v_div_fixup_f32 v28, v28, v31, 2.0
	v_sub_f32_e32 v28, 1.0, v28
	v_add_f32_e32 v29, 1.0, v34
	v_div_scale_f32 v31, s[2:3], v29, v29, 2.0
	v_rcp_f32_e32 v33, v31
	v_add_f32_e32 v28, 1.0, v28
	v_mul_f32_e32 v103, v24, v28
	v_and_b32_e32 v25, 0xffff0000, v25
	v_fma_f32 v24, -v31, v33, 1.0
	v_fmac_f32_e32 v33, v24, v33
	v_div_scale_f32 v24, vcc, 2.0, v29, 2.0
	v_mul_f32_e32 v28, v24, v33
	v_fma_f32 v34, -v31, v28, v24
	v_fmac_f32_e32 v28, v34, v33
	v_fma_f32 v24, -v31, v28, v24
	v_mul_f32_e32 v31, 0x3d372713, v25
	v_mul_f32_e32 v31, v31, v25
	v_fma_f32 v31, v31, v25, v25
	v_mul_f32_e32 v31, 0x3f4c422a, v31
	v_add_f32_e32 v31, v31, v31
	v_mul_f32_e32 v31, 0x3fb8aa3b, v31
	v_exp_f32_e32 v31, v31
	v_div_fmas_f32 v24, v24, v33, v28
	v_div_fixup_f32 v24, v24, v29, 2.0
	v_sub_f32_e32 v24, 1.0, v24
	v_add_f32_e32 v28, 1.0, v31
	v_div_scale_f32 v29, s[2:3], v28, v28, 2.0
	v_rcp_f32_e32 v31, v29
	v_mul_f32_e32 v32, 0.5, v32
	v_add_f32_e32 v24, 1.0, v24
	v_mul_f32_e32 v104, v32, v24
	v_fma_f32 v24, -v29, v31, 1.0
	v_fmac_f32_e32 v31, v24, v31
	v_div_scale_f32 v24, vcc, 2.0, v28, 2.0
	v_mul_f32_e32 v32, v24, v31
	v_fma_f32 v33, -v29, v32, v24
	v_fmac_f32_e32 v32, v33, v31
	v_fma_f32 v24, -v29, v32, v24
	v_div_fmas_f32 v24, v24, v31, v32
	v_div_fixup_f32 v24, v24, v28, 2.0
	v_mul_f32_e32 v32, 0.5, v25
	v_lshlrev_b32_e32 v25, 16, v26
	v_sub_f32_e32 v31, 1.0, v24
	v_and_b32_e32 v24, 0xffff0000, v26
	v_mul_f32_e32 v26, 0x3d372713, v25
	v_mul_f32_e32 v26, v26, v25
	v_mov_b32_e32 v28, v25
	v_fmac_f32_e32 v28, v26, v28
	v_mul_f32_e32 v26, 0x3f4c422a, v28
	v_add_f32_e32 v26, v26, v26
	v_mul_f32_e32 v26, 0x3fb8aa3b, v26
	v_exp_f32_e32 v29, v26
	v_mul_f32_e32 v26, 0x3d372713, v24
	v_mul_f32_e32 v26, v26, v24
	v_mov_b32_e32 v28, v24
	v_fmac_f32_e32 v28, v26, v28
	v_mul_f32_e32 v26, 0x3f4c422a, v28
	v_add_f32_e32 v26, v26, v26
	v_mul_f32_e32 v26, 0x3fb8aa3b, v26
	v_exp_f32_e32 v28, v26
	v_add_f32_e32 v26, 1.0, v31
	v_mul_f32_e32 v105, v32, v26
	v_lshlrev_b32_e32 v35, 16, v27
	v_pk_add_f32 v[28:29], v[28:29], 1.0 op_sel_hi:[1,0]
	v_fmac_f32_e32 v30, v86, v86
	v_div_scale_f32 v26, s[2:3], v29, v29, 2.0
	v_rcp_f32_e32 v31, v26
	v_fmac_f32_e32 v30, v87, v87
	v_fmac_f32_e32 v30, v100, v100
	v_fmac_f32_e32 v30, v101, v101
	v_fma_f32 v32, -v26, v31, 1.0
	v_fmac_f32_e32 v31, v32, v31
	v_div_scale_f32 v32, vcc, 2.0, v29, 2.0
	v_mul_f32_e32 v33, v32, v31
	v_fma_f32 v34, -v26, v33, v32
	v_fmac_f32_e32 v33, v34, v31
	v_fma_f32 v26, -v26, v33, v32
	v_div_scale_f32 v32, s[2:3], v28, v28, 2.0
	v_rcp_f32_e32 v34, v32
	v_div_fmas_f32 v26, v26, v31, v33
	v_div_fixup_f32 v29, v26, v29, 2.0
	v_fmac_f32_e32 v30, v102, v102
	v_fma_f32 v26, -v32, v34, 1.0
	v_fmac_f32_e32 v34, v26, v34
	v_div_scale_f32 v26, vcc, 2.0, v28, 2.0
	v_mul_f32_e32 v31, v26, v34
	v_fma_f32 v33, -v32, v31, v26
	v_fmac_f32_e32 v31, v33, v34
	v_fma_f32 v26, -v32, v31, v26
	v_div_fmas_f32 v26, v26, v34, v31
	v_div_fixup_f32 v28, v26, v28, 2.0
	v_mul_f32_e32 v26, 0x3d372713, v35
	v_and_b32_e32 v34, 0xffff0000, v27
	v_mul_f32_e32 v26, v26, v35
	v_mov_b32_e32 v27, v35
	v_fmac_f32_e32 v27, v26, v27
	v_mul_f32_e32 v26, 0x3f4c422a, v27
	v_add_f32_e32 v26, v26, v26
	v_mul_f32_e32 v26, 0x3fb8aa3b, v26
	v_exp_f32_e32 v27, v26
	v_mul_f32_e32 v26, 0x3d372713, v34
	v_mul_f32_e32 v26, v26, v34
	v_mov_b32_e32 v31, v34
	v_fmac_f32_e32 v31, v26, v31
	v_mul_f32_e32 v26, 0x3f4c422a, v31
	v_add_f32_e32 v26, v26, v26
	v_mul_f32_e32 v26, 0x3fb8aa3b, v26
	v_exp_f32_e32 v26, v26
	v_pk_add_f32 v[28:29], v[28:29], 1.0 op_sel_hi:[1,0] neg_lo:[1,0] neg_hi:[1,0]
	v_fmac_f32_e32 v30, v103, v103
	v_pk_mul_f32 v[24:25], v[24:25], 0.5 op_sel_hi:[1,0]
	v_pk_add_f32 v[28:29], v[28:29], 1.0 op_sel_hi:[1,0]
	v_fmac_f32_e32 v30, v104, v104
	v_pk_mul_f32 v[36:37], v[24:25], v[28:29]
	v_fmac_f32_e32 v30, v105, v105
	v_pk_add_f32 v[24:25], v[26:27], 1.0 op_sel_hi:[1,0]
	v_pk_mul_f32 v[26:27], v[36:37], v[36:37]
	v_div_scale_f32 v38, s[2:3], v25, v25, 2.0
	v_add_f32_e32 v27, v27, v30
	v_add_f32_e32 v49, v26, v27
	ds_read_b128 v[26:29], v210 offset:12304
	ds_read_b128 v[30:33], v210 offset:12288
	v_rcp_f32_e32 v39, v38
	v_pk_mul_f32 v[34:35], v[34:35], 0.5 op_sel_hi:[1,0]
	v_fma_f32 v106, -v38, v39, 1.0
	v_fmac_f32_e32 v39, v106, v39
	v_div_scale_f32 v106, vcc, 2.0, v25, 2.0
	v_mul_f32_e32 v107, v106, v39
	v_fma_f32 v108, -v38, v107, v106
	v_fmac_f32_e32 v107, v108, v39
	v_fma_f32 v38, -v38, v107, v106
	v_div_scale_f32 v106, s[2:3], v24, v24, 2.0
	v_rcp_f32_e32 v108, v106
	v_div_fmas_f32 v38, v38, v39, v107
	v_div_fixup_f32 v25, v38, v25, 2.0
	v_fma_f32 v38, -v106, v108, 1.0
	v_fmac_f32_e32 v108, v38, v108
	v_div_scale_f32 v38, vcc, 2.0, v24, 2.0
	v_mul_f32_e32 v39, v38, v108
	v_fma_f32 v107, -v106, v39, v38
	v_fmac_f32_e32 v39, v107, v108
	v_fma_f32 v38, -v106, v39, v38
	v_div_fmas_f32 v38, v38, v108, v39
	v_div_fixup_f32 v24, v38, v24, 2.0
	v_pk_add_f32 v[24:25], v[24:25], 1.0 op_sel_hi:[1,0] neg_lo:[1,0] neg_hi:[1,0]
	s_nop 0
	v_pk_add_f32 v[24:25], v[24:25], 1.0 op_sel_hi:[1,0]
	s_nop 0
	v_pk_mul_f32 v[38:39], v[34:35], v[24:25]
	s_nop 0
	v_pk_mul_f32 v[24:25], v[38:39], v[38:39]
	s_nop 0
	v_add_f32_e32 v25, v25, v49
	v_add_f32_e32 v24, v24, v25
	v_ashrrev_i32_e32 v49, 31, v48
	s_waitcnt lgkmcnt(0)
; __device__ __forceinline__ unsigned cvt_pk_bf16(float lo, float hi) { unsigned r; asm volatile("v_cvt_pk_bf16_f32 %0, %1, %2" : "=v"(r) : "v"(lo), "v"(hi)); return r; }
; __device__ __forceinline__ float lo_f(unsigned w) { return __uint_as_float(w << 16); }
; __device__ __forceinline__ float hi_f(unsigned w) { return __uint_as_float(w & 0xffff0000u); }
; __device__ __forceinline__ float wave_sum(float v, int lane) {
; #pragma unroll
;     for (int o = 32; o; o >>= 1) v += __int_as_float(__builtin_amdgcn_ds_bpermute((lane ^ o) << 2, __float_as_int(v)));
;     return v;
; __device__ void phase_post(const Ctx& c, int l, bool ctx_full) {
;     ...
;             ss = wave_sum(ss, c.lane); const float rstd = rsqrtf(ss * (1.f / 1024.f) + EPS);
; #pragma unroll
;             for (int i = 0; i < 2; ++i) { const int cc = i * 512 + c.lane * 8;
;                 const f32x4 g0 = *(const f32x4*)(gv + cc), g1 = *(const f32x4*)(gv + cc + 4);
;                 u32x4 w;
;                 w.x = cvt_pk_bf16(fv[i * 8 + 0] * rstd * g0[0], fv[i * 8 + 1] * rstd * g0[1]); w.y = cvt_pk_bf16(fv[i * 8 + 2] * rstd * g0[2], fv[i * 8 + 3] * rstd * g0[3]);
;                 w.z = cvt_pk_bf16(fv[i * 8 + 4] * rstd * g1[0], fv[i * 8 + 5] * rstd * g1[1]); w.w = cvt_pk_bf16(fv[i * 8 + 6] * rstd * g1[2], fv[i * 8 + 7] * rstd * g1[3]);
;                 *(u32x4*)(VN + (size_t)row * 1024 + cc) = w; }
; #pragma unroll
;             for (int i = 0; i < 2; ++i) { const int cc = i * 512 + c.lane * 8;
;                 float a[8] = {0.f, 0.f, 0.f, 0.f, 0.f, 0.f, 0.f, 0.f};
; #pragma unroll
;                 for (int k = 0; k < 3; ++k) { const int tt = t + k - 1;
;                     if (tt >= 0 && tt < slen) { const bf16_t* z2 = zr + (ptrdiff_t)(k - 1) * IN_DIM;
;                         const u32x4 cg = *(const u32x4*)(z2 + OFF_CC + cc), hh = *(const u32x4*)(z2 + OFF_CH + cc);
;                         const f32x4 w0 = *(const f32x4*)(wsc + k * 1024 + cc), w1 = *(const f32x4*)(wsc + k * 1024 + cc + 4);
;                         a[0] += w0[0] * lo_f(cg.x) * lo_f(hh.x); a[1] += w0[1] * hi_f(cg.x) * hi_f(hh.x); a[2] += w0[2] * lo_f(cg.y) * lo_f(hh.y); a[3] += w0[3] * hi_f(cg.y) * hi_f(hh.y);
	v_mov_b32_e32 v25, v24
	s_nop 1
	v_permlane32_swap_b32_e32 v24, v25
	s_nop 1
	v_add_f32_e32 v24, v24, v25
	s_waitcnt lgkmcnt(0)
	v_mov_b32_e32 v25, v24
	s_nop 1
	v_permlane16_swap_b32_e32 v24, v25
	s_nop 1
	v_add_f32_e32 v24, v24, v25
	s_waitcnt lgkmcnt(0)
	s_nop 1
	v_add_f32_dpp v24, v24, v24 row_mirror row_mask:0xf bank_mask:0xf
	s_waitcnt lgkmcnt(0)
	s_nop 1
	v_add_f32_dpp v24, v24, v24 row_half_mirror row_mask:0xf bank_mask:0xf
	s_waitcnt lgkmcnt(0)
	s_nop 1
	v_add_f32_dpp v24, v24, v24 quad_perm:[2,3,0,1] row_mask:0xf bank_mask:0xf
	s_waitcnt lgkmcnt(0)
	s_nop 1
	v_add_f32_dpp v24, v24, v24 quad_perm:[1,0,3,2] row_mask:0xf bank_mask:0xf
	v_fmamk_f32 v24, v24, 0x3a800000, v94
	v_mul_f32_e32 v25, 0x4b800000, v24
	v_cmp_gt_f32_e32 vcc, s29, v24
	s_nop 1
	v_cndmask_b32_e32 v24, v24, v25, vcc
	v_rsq_f32_e32 v24, v24
	s_nop 0
	v_mul_f32_e32 v25, 0x45800000, v24
	v_cndmask_b32_e32 v106, v24, v25, vcc
	v_mul_f32_e32 v34, v77, v106
	s_waitcnt lgkmcnt(0)
	v_mul_f32_e32 v30, v30, v34
	v_mul_f32_e32 v34, v79, v106
	v_mul_f32_e32 v31, v31, v34
	v_cvt_pk_bf16_f32 v30, v30, v31
	v_mul_f32_e32 v31, v85, v106
	v_mul_f32_e32 v31, v32, v31
	v_mul_f32_e32 v32, v84, v106
	v_mul_f32_e32 v32, v33, v32
	v_cvt_pk_bf16_f32 v31, v31, v32
	v_mul_f32_e32 v32, v86, v106
	v_mul_f32_e32 v26, v26, v32
	v_mul_f32_e32 v32, v87, v106
	v_lshlrev_b64 v[24:25], 11, v[48:49]
	v_mul_f32_e32 v27, v27, v32
	v_cvt_pk_bf16_f32 v32, v26, v27
	v_mul_f32_e32 v26, v100, v106
	v_mul_f32_e32 v27, v101, v106
	v_lshl_add_u64 v[84:85], v[68:69], 0, v[24:25]
	v_mul_f32_e32 v26, v28, v26
	v_mul_f32_e32 v27, v29, v27
	v_cvt_pk_bf16_f32 v33, v26, v27
	global_store_dwordx4 v[84:85], v[30:33], off
	ds_read_b128 v[28:31], v210 offset:14336
	s_nop 0
	ds_read_b128 v[32:35], v210 offset:14352
	v_mul_f32_e32 v27, v102, v106
	v_cndmask_b32_e64 v26, v97, v98, s[6:7]
	s_waitcnt lgkmcnt(1)
	v_mul_f32_e32 v27, v28, v27
	v_mul_f32_e32 v28, v103, v106
	v_mul_f32_e32 v28, v29, v28
	v_cvt_pk_bf16_f32 v28, v27, v28
	v_mul_f32_e32 v27, v104, v106
	v_mul_f32_e32 v29, v105, v106
	v_mul_f32_e32 v27, v30, v27
	v_mul_f32_e32 v29, v31, v29
	v_cvt_pk_bf16_f32 v29, v27, v29
	v_mul_f32_e32 v27, v37, v106
	v_mul_f32_e32 v30, v36, v106
	s_waitcnt lgkmcnt(0)
	v_mul_f32_e32 v27, v32, v27
	v_mul_f32_e32 v30, v33, v30
	v_cvt_pk_bf16_f32 v30, v27, v30
	v_mul_f32_e32 v27, v39, v106
	v_mul_f32_e32 v31, v38, v106
	v_mul_f32_e32 v27, v34, v27
	v_mul_f32_e32 v31, v35, v31
	v_cvt_pk_bf16_f32 v31, v27, v31
	v_add_u32_e32 v27, -1, v99
	v_mov_b32_e32 v36, v51
	v_mov_b32_e32 v37, v51
	global_store_dwordx4 v[84:85], v[28:31], off offset:1024
	v_cmp_lt_u32_e64 s[6:7], v27, v26
	v_mov_b64_e32 v[38:39], v[36:37]
	v_mov_b64_e32 v[84:85], v[36:37]
	v_mov_b64_e32 v[86:87], v[36:37]
	s_and_saveexec_b64 s[2:3], s[6:7]
	s_cbranch_execz .LBB0_376
	v_add_co_u32_e32 v28, vcc, 0xffffc000, v82
	s_nop 1
	v_addc_co_u32_e32 v29, vcc, -1, v83, vcc
	v_mov_b64_e32 v[28:29], v[152:153]
	v_mov_b64_e32 v[30:31], v[154:155]
	v_add_co_u32_e32 v86, vcc, 0xffffd000, v82
	v_lshlrev_b32_e32 v100, 16, v30
	v_addc_co_u32_e32 v87, vcc, -1, v83, vcc
	ds_read_b128 v[32:35], v210 offset:0
	v_mov_b64_e32 v[36:37], v[156:157]
	v_mov_b64_e32 v[38:39], v[158:159]
	ds_read_b128 v[82:85], v210 offset:16
	v_lshlrev_b32_e32 v86, 16, v28
	v_and_b32_e32 v87, 0xffff0000, v28
	v_lshlrev_b32_e32 v28, 16, v29
	v_and_b32_e32 v29, 0xffff0000, v29
	v_and_b32_e32 v101, 0xffff0000, v30
	v_lshlrev_b32_e32 v30, 16, v31
	v_and_b32_e32 v31, 0xffff0000, v31
	s_waitcnt lgkmcnt(1)
	v_pk_mul_f32 v[32:33], v[32:33], v[86:87]
	s_waitcnt lgkmcnt(1)
	v_lshlrev_b32_e32 v86, 16, v36
	v_and_b32_e32 v87, 0xffff0000, v36
	v_pk_mul_f32 v[28:29], v[34:35], v[28:29]
	v_lshlrev_b32_e32 v34, 16, v37
	v_and_b32_e32 v35, 0xffff0000, v37
	s_waitcnt lgkmcnt(0)
	v_pk_mul_f32 v[82:83], v[82:83], v[100:101]
	v_lshlrev_b32_e32 v100, 16, v38
	v_and_b32_e32 v101, 0xffff0000, v38
	v_pk_mul_f32 v[30:31], v[84:85], v[30:31]
	v_lshlrev_b32_e32 v102, 16, v39
	v_and_b32_e32 v103, 0xffff0000, v39
	v_pk_fma_f32 v[36:37], v[32:33], v[86:87], 0 op_sel_hi:[1,1,0]
	v_pk_fma_f32 v[38:39], v[28:29], v[34:35], 0 op_sel_hi:[1,1,0]
	v_pk_fma_f32 v[84:85], v[82:83], v[100:101], 0 op_sel_hi:[1,1,0]
	v_pk_fma_f32 v[86:87], v[30:31], v[102:103], 0 op_sel_hi:[1,1,0]

; __device__ __forceinline__ unsigned cvt_pk_bf16(float lo, float hi) { unsigned r; asm volatile("v_cvt_pk_bf16_f32 %0, %1, %2" : "=v"(r) : "v"(lo), "v"(hi)); return r; }
; __device__ __forceinline__ float wave_sum(float v, int lane) {
; #pragma unroll
;     for (int o = 32; o; o >>= 1) v += __int_as_float(__builtin_amdgcn_ds_bpermute((lane ^ o) << 2, __float_as_int(v)));
;     return v;
; __device__ void phase_norm(const Ctx& c, const void* xlat, bool lat_f32, const void* xctx, bool ctx_f32, const float* __restrict__ g, const float* __restrict__ mod, int sh_off, int sc_off,
;                            bf16_t* __restrict__ dst, int nrows, const float* part) {
;     ...
;         float ss = 0.f;
; #pragma unroll
;         for (int i = 0; i < 8; ++i) ss += v[i][0] * v[i][0] + v[i][1] * v[i][1] + v[i][2] * v[i][2] + v[i][3] * v[i][3];
;         ss = wave_sum(ss, c.lane);
;         const float rstd = rsqrtf(ss * (1.f / DM) + EPS);
;         const int r = row < TL ? (row >> 11) : 4;
;         const float* md = mod + (size_t)r * MODW + c.lane * 8;
; #pragma unroll
;         for (int i = 0; i < 4; ++i) { const int cc = i * 512;
;             f32x4 y[2];
; #pragma unroll
;             for (int h = 0; h < 2; ++h) { const f32x4 gg = *(const f32x4*)(g + cc + c.lane * 8 + 4 * h), sh = *(const f32x4*)(md + sh_off + cc + 4 * h), sc = *(const f32x4*)(md + sc_off + cc + 4 * h);
; #pragma unroll
;                 for (int j = 0; j < 4; ++j) y[h][j] = v[2 * i + h][j] * rstd * gg[j] * (1.f + sc[j]) + sh[j]; }
;             u32x4 w; w.x = cvt_pk_bf16(y[0][0], y[0][1]); w.y = cvt_pk_bf16(y[0][2], y[0][3]); w.z = cvt_pk_bf16(y[1][0], y[1][1]); w.w = cvt_pk_bf16(y[1][2], y[1][3]);
;             *(u32x4*)(dst + (size_t)row * DM + cc + c.lane * 8) = w; }
.LBB0_791:
	s_or_b64 exec, exec, s[80:81]
	s_waitcnt vmcnt(0)
	v_mul_f32_e32 v33, v29, v29
	v_mul_f32_e32 v34, v25, v25
	v_fmac_f32_e32 v33, v28, v28
	v_fmac_f32_e32 v34, v24, v24
	v_fmac_f32_e32 v33, v30, v30
	v_fmac_f32_e32 v34, v26, v26
	v_fmac_f32_e32 v33, v31, v31
	v_fmac_f32_e32 v34, v27, v27
	v_add_f32_e32 v33, v34, v33
	v_mul_f32_e32 v34, v21, v21
	v_fmac_f32_e32 v34, v20, v20
	v_fmac_f32_e32 v34, v22, v22
	v_fmac_f32_e32 v34, v23, v23
	v_add_f32_e32 v33, v34, v33
	v_mul_f32_e32 v34, v17, v17
	v_fmac_f32_e32 v34, v16, v16
	v_fmac_f32_e32 v34, v18, v18
	v_fmac_f32_e32 v34, v19, v19
	v_add_f32_e32 v33, v34, v33
	v_min_i32_e32 v34, 0x2000, v32
	v_mov_b32_e32 v52, v13
	v_mov_b32_e32 v53, v9
	v_ashrrev_i32_e32 v34, 11, v34
	v_pk_mul_f32 v[76:77], v[52:53], v[52:53]
	v_mul_hi_i32_i24_e32 v53, 0xc000, v34
	v_mul_i32_i24_e32 v52, 0xc000, v34
	v_lshl_add_u64 v[52:53], v[42:43], 0, v[52:53]
	v_add_co_u32_e32 v54, vcc, s92, v52
	v_mov_b32_e32 v74, v12
	v_mov_b32_e32 v75, v8
	v_addc_co_u32_e32 v55, vcc, 0, v53, vcc
	v_add_co_u32_e32 v56, vcc, s93, v52
	v_pk_fma_f32 v[74:75], v[74:75], v[74:75], v[76:77]
	v_mov_b32_e32 v76, v14
	v_mov_b32_e32 v77, v10
	global_load_dwordx4 v[58:61], v[44:45], off offset:16
	global_load_dwordx4 v[62:65], v[44:45], off
	v_addc_co_u32_e32 v57, vcc, 0, v53, vcc
	global_load_dwordx4 v[66:69], v[54:55], off offset:-4096
	global_load_dwordx4 v[70:73], v[56:57], off offset:-4096
	v_pk_fma_f32 v[74:75], v[76:77], v[76:77], v[74:75]
	v_mov_b32_e32 v76, v15
	v_mov_b32_e32 v77, v11
	v_pk_fma_f32 v[74:75], v[76:77], v[76:77], v[74:75]
	v_lshl_add_u64 v[78:79], v[52:53], 0, s[66:67]
	v_add_f32_e32 v33, v75, v33
	v_add_f32_e32 v33, v74, v33
	v_lshl_add_u64 v[74:75], v[52:53], 0, s[64:65]
	global_load_dwordx4 v[74:77], v[74:75], off offset:16
	s_nop 0
	global_load_dwordx4 v[78:81], v[78:79], off offset:16
	v_mov_b32_e32 v92, v5
	v_mov_b32_e32 v93, v1
	v_mov_b32_e32 v82, v4
	v_mov_b32_e32 v83, v0
	v_pk_mul_f32 v[92:93], v[92:93], v[92:93]
	v_add_u32_e32 v32, s8, v32
	v_pk_fma_f32 v[82:83], v[82:83], v[82:83], v[92:93]
	v_mov_b32_e32 v92, v6
	v_mov_b32_e32 v93, v2
	v_pk_fma_f32 v[82:83], v[92:93], v[92:93], v[82:83]
	v_mov_b32_e32 v92, v7
	v_mov_b32_e32 v93, v3
	v_pk_fma_f32 v[82:83], v[92:93], v[92:93], v[82:83]
	s_nop 0
	v_add_f32_e32 v33, v83, v33
	v_add_f32_e32 v33, v82, v33
	s_waitcnt lgkmcnt(0)
	v_mov_b32_e32 v34, v33
	s_nop 1
	v_permlane32_swap_b32_e32 v33, v34
	s_nop 1
	v_add_f32_e32 v33, v33, v34
	s_waitcnt lgkmcnt(0)
	v_mov_b32_e32 v34, v33
	s_nop 1
	v_permlane16_swap_b32_e32 v33, v34
	s_nop 1
	v_add_f32_e32 v33, v33, v34
	s_waitcnt lgkmcnt(0)
	s_nop 1
	v_add_f32_dpp v33, v33, v33 row_mirror row_mask:0xf bank_mask:0xf
	s_waitcnt lgkmcnt(0)
	s_nop 1
	v_add_f32_dpp v33, v33, v33 row_half_mirror row_mask:0xf bank_mask:0xf
	s_waitcnt lgkmcnt(0)
	s_nop 1
	v_add_f32_dpp v33, v33, v33 quad_perm:[2,3,0,1] row_mask:0xf bank_mask:0xf
	s_waitcnt lgkmcnt(0)
	s_nop 1
	v_add_f32_dpp v33, v33, v33 quad_perm:[1,0,3,2] row_mask:0xf bank_mask:0xf
	v_fmamk_f32 v33, v33, 0x3a000000, v90
	v_mul_f32_e32 v34, 0x4b800000, v33
	v_cmp_gt_f32_e32 vcc, s44, v33
	s_nop 1
	v_cndmask_b32_e32 v33, v33, v34, vcc
	v_rsq_f32_e32 v33, v33
	s_nop 0
	v_mul_f32_e32 v34, 0x45800000, v33
	v_cndmask_b32_e32 v33, v33, v34, vcc
	v_mul_f32_e32 v28, v28, v33
	v_mul_f32_e32 v29, v29, v33
	v_mul_f32_e32 v30, v30, v33
	s_waitcnt vmcnt(4)
	v_mul_f32_e32 v28, v62, v28
	v_mul_f32_e32 v29, v63, v29
	v_mul_f32_e32 v30, v64, v30
	s_waitcnt vmcnt(2)
	v_add_f32_e32 v34, 1.0, v70
	v_fma_f32 v28, v34, v28, v66
	v_add_f32_e32 v34, 1.0, v71
	v_fma_f32 v29, v34, v29, v67
	v_add_f32_e32 v34, 1.0, v72
	v_mul_f32_e32 v31, v31, v33
	v_fma_f32 v30, v34, v30, v68
	v_mul_f32_e32 v31, v65, v31
	v_add_f32_e32 v34, 1.0, v73
	v_mul_f32_e32 v24, v24, v33
	v_fmac_f32_e32 v69, v34, v31
	v_mul_f32_e32 v24, v58, v24
	s_waitcnt vmcnt(0)
	v_add_f32_e32 v31, 1.0, v78
	v_mul_f32_e32 v25, v25, v33
	v_fma_f32 v24, v31, v24, v74
	v_mul_f32_e32 v25, v59, v25
	v_add_f32_e32 v31, 1.0, v79
	v_mul_f32_e32 v26, v26, v33
	v_fma_f32 v25, v31, v25, v75
	v_mul_f32_e32 v26, v60, v26
	v_add_f32_e32 v31, 1.0, v80
	v_add_co_u32_e32 v82, vcc, s90, v52
	v_fma_f32 v31, v31, v26, v76
	v_mul_f32_e32 v26, v27, v33
	v_addc_co_u32_e32 v83, vcc, 0, v53, vcc
	v_mul_f32_e32 v26, v61, v26
	v_add_f32_e32 v27, 1.0, v81
	v_fmac_f32_e32 v77, v27, v26
	v_cvt_pk_bf16_f32 v26, v28, v29
	v_cvt_pk_bf16_f32 v27, v30, v69
	v_cvt_pk_bf16_f32 v28, v24, v25
	v_add_co_u32_e32 v24, vcc, s91, v50
	v_cvt_pk_bf16_f32 v29, v31, v77
	v_lshl_add_u64 v[30:31], v[52:53], 0, s[70:71]
	s_nop 0
	v_addc_co_u32_e32 v25, vcc, 0, v51, vcc
	global_store_dwordx4 v[24:25], v[26:29], off
	global_load_dwordx4 v[26:29], v[44:45], off offset:2048
	s_nop 0
	global_load_dwordx4 v[58:61], v[82:83], off offset:2048
	global_load_dwordx4 v[62:65], v[44:45], off offset:2064
	global_load_dwordx4 v[66:69], v[30:31], off offset:16
	v_add_co_u32_e32 v30, vcc, s89, v52
	v_mul_f32_e32 v23, v23, v33
	s_nop 0
	v_addc_co_u32_e32 v31, vcc, 0, v53, vcc
	global_load_dwordx4 v[70:73], v[30:31], off offset:2048
	v_lshl_add_u64 v[30:31], v[52:53], 0, s[68:69]
	global_load_dwordx4 v[74:77], v[30:31], off offset:16
	v_mul_f32_e32 v16, v16, v33
	v_mul_f32_e32 v20, v20, v33
	v_mul_f32_e32 v17, v17, v33
	v_mul_f32_e32 v21, v21, v33
	v_mul_f32_e32 v22, v22, v33
	v_mul_f32_e32 v18, v18, v33
	v_mul_f32_e32 v8, v8, v33
	v_mul_f32_e32 v9, v9, v33
	v_mul_f32_e32 v10, v10, v33
	v_mul_f32_e32 v11, v11, v33
	v_mul_f32_e32 v12, v12, v33
	v_mul_f32_e32 v13, v13, v33
	v_mul_f32_e32 v14, v14, v33
	v_mul_f32_e32 v15, v15, v33
	v_mul_f32_e32 v0, v0, v33
	v_mul_f32_e32 v1, v1, v33
	v_mul_f32_e32 v2, v2, v33
	v_mul_f32_e32 v3, v3, v33
	v_mul_f32_e32 v4, v4, v33
	v_cmp_lt_i32_e32 vcc, s94, v32
	v_mul_f32_e32 v5, v5, v33
	v_mul_f32_e32 v6, v6, v33
	v_mul_f32_e32 v7, v7, v33
	s_or_b64 s[14:15], vcc, s[14:15]
	v_lshl_add_u64 v[50:51], v[50:51], 0, s[10:11]
	s_waitcnt vmcnt(5)
; __device__ __forceinline__ unsigned cvt_pk_bf16(float lo, float hi) { unsigned r; asm volatile("v_cvt_pk_bf16_f32 %0, %1, %2" : "=v"(r) : "v"(lo), "v"(hi)); return r; }
; __device__ void phase_norm(const Ctx& c, const void* xlat, bool lat_f32, const void* xctx, bool ctx_f32, const float* __restrict__ g, const float* __restrict__ mod, int sh_off, int sc_off,
;                            bf16_t* __restrict__ dst, int nrows, const float* part) {
;     ...
;         for (int i = 0; i < 4; ++i) { const int cc = i * 512;
;             f32x4 y[2];
; #pragma unroll
;             for (int h = 0; h < 2; ++h) { const f32x4 gg = *(const f32x4*)(g + cc + c.lane * 8 + 4 * h), sh = *(const f32x4*)(md + sh_off + cc + 4 * h), sc = *(const f32x4*)(md + sc_off + cc + 4 * h);
; #pragma unroll
;                 for (int j = 0; j < 4; ++j) y[h][j] = v[2 * i + h][j] * rstd * gg[j] * (1.f + sc[j]) + sh[j]; }
;             u32x4 w; w.x = cvt_pk_bf16(y[0][0], y[0][1]); w.y = cvt_pk_bf16(y[0][2], y[0][3]); w.z = cvt_pk_bf16(y[1][0], y[1][1]); w.w = cvt_pk_bf16(y[1][2], y[1][3]);
;             *(u32x4*)(dst + (size_t)row * DM + cc + c.lane * 8) = w; }
	v_mul_f32_e32 v23, v29, v23
	s_waitcnt vmcnt(4)
	v_add_f32_e32 v29, 1.0, v61
	s_waitcnt vmcnt(3)
	v_mul_f32_e32 v16, v62, v16
	s_waitcnt vmcnt(2)
	v_add_f32_e32 v30, 1.0, v66
	v_mul_f32_e32 v20, v26, v20
	v_add_f32_e32 v26, 1.0, v58
	v_mul_f32_e32 v17, v63, v17
	v_add_f32_e32 v31, 1.0, v67
	v_mul_f32_e32 v21, v27, v21
	s_waitcnt vmcnt(1)
	v_fmac_f32_e32 v73, v29, v23
	v_add_f32_e32 v27, 1.0, v59
	s_waitcnt vmcnt(0)
	v_fma_f32 v23, v30, v16, v74
	v_mul_f32_e32 v16, v19, v33
	v_mul_f32_e32 v22, v28, v22
	v_add_f32_e32 v28, 1.0, v60
	v_mul_f32_e32 v18, v64, v18
	v_add_f32_e32 v34, 1.0, v68
	v_fma_f32 v20, v26, v20, v70
	v_fma_f32 v26, v31, v17, v75
	v_mul_f32_e32 v16, v65, v16
	v_add_f32_e32 v17, 1.0, v69
	v_fma_f32 v21, v27, v21, v71
	v_fma_f32 v22, v28, v22, v72
	v_fma_f32 v27, v34, v18, v76
	v_fmac_f32_e32 v77, v17, v16
	v_cvt_pk_bf16_f32 v16, v20, v21
	v_cvt_pk_bf16_f32 v17, v22, v73
	v_cvt_pk_bf16_f32 v18, v23, v26
	v_cvt_pk_bf16_f32 v19, v27, v77
	global_store_dwordx4 v[24:25], v[16:19], off offset:1024
	v_lshl_add_u64 v[30:31], v[52:53], 0, s[74:75]
	global_load_dwordx4 v[16:19], v[46:47], off
	global_load_dwordx4 v[20:23], v[56:57], off
	global_load_dwordx4 v[26:29], v[46:47], off offset:16
	global_load_dwordx4 v[58:61], v[30:31], off offset:16
	global_load_dwordx4 v[62:65], v[54:55], off
	v_lshl_add_u64 v[30:31], v[52:53], 0, s[72:73]
	global_load_dwordx4 v[66:69], v[30:31], off offset:16
	v_lshl_add_u64 v[30:31], v[52:53], 0, s[76:77]
	s_waitcnt vmcnt(5)
	v_mul_f32_e32 v8, v8, v16
	s_waitcnt vmcnt(4)
	v_add_f32_e32 v16, 1.0, v20
	v_mul_f32_e32 v9, v9, v17
	v_add_f32_e32 v17, 1.0, v21
	v_mul_f32_e32 v10, v10, v18
	v_add_f32_e32 v18, 1.0, v22
	v_mul_f32_e32 v11, v11, v19
	v_add_f32_e32 v19, 1.0, v23
	s_waitcnt vmcnt(3)
	v_mul_f32_e32 v12, v12, v26
	s_waitcnt vmcnt(2)
	v_add_f32_e32 v20, 1.0, v58
	v_mul_f32_e32 v13, v13, v27
	v_add_f32_e32 v21, 1.0, v59
	v_mul_f32_e32 v14, v14, v28
	v_add_f32_e32 v22, 1.0, v60
	v_mul_f32_e32 v15, v15, v29
	v_add_f32_e32 v23, 1.0, v61
	s_waitcnt vmcnt(1)
	v_fma_f32 v8, v8, v16, v62
	v_fma_f32 v9, v9, v17, v63
	v_fma_f32 v10, v10, v18, v64
	v_fmac_f32_e32 v65, v11, v19
	s_waitcnt vmcnt(0)
	v_fma_f32 v11, v12, v20, v66
	v_fma_f32 v12, v13, v21, v67
	v_fma_f32 v13, v14, v22, v68
	v_fmac_f32_e32 v69, v15, v23
	v_cvt_pk_bf16_f32 v8, v8, v9
	v_cvt_pk_bf16_f32 v9, v10, v65
	v_cvt_pk_bf16_f32 v10, v11, v12
	v_cvt_pk_bf16_f32 v11, v13, v69
	global_store_dwordx4 v[24:25], v[8:11], off offset:2048
	global_load_dwordx4 v[8:11], v[48:49], off
	s_nop 0
	global_load_dwordx4 v[12:15], v[56:57], off offset:2048
	v_lshl_add_u64 v[20:21], v[52:53], 0, s[78:79]
	global_load_dwordx4 v[16:19], v[48:49], off offset:16
	s_nop 0
	global_load_dwordx4 v[20:23], v[20:21], off offset:16
	s_nop 0
	global_load_dwordx4 v[26:29], v[54:55], off offset:2048
	s_waitcnt vmcnt(4)
	v_mul_f32_e32 v0, v0, v8
	global_load_dwordx4 v[52:55], v[30:31], off offset:16
	s_waitcnt vmcnt(4)
	v_add_f32_e32 v8, 1.0, v12
	v_mul_f32_e32 v1, v1, v9
	v_add_f32_e32 v9, 1.0, v13
	v_mul_f32_e32 v2, v2, v10
	v_add_f32_e32 v10, 1.0, v14
	v_mul_f32_e32 v3, v3, v11
	v_add_f32_e32 v11, 1.0, v15
	s_waitcnt vmcnt(3)
	v_mul_f32_e32 v4, v4, v16
	s_waitcnt vmcnt(2)
	v_add_f32_e32 v12, 1.0, v20
	v_mul_f32_e32 v5, v5, v17
	v_add_f32_e32 v13, 1.0, v21
	v_mul_f32_e32 v6, v6, v18
	v_add_f32_e32 v14, 1.0, v22
	v_mul_f32_e32 v7, v7, v19
	v_add_f32_e32 v15, 1.0, v23
	s_waitcnt vmcnt(1)
	v_fma_f32 v0, v0, v8, v26
	v_fma_f32 v1, v1, v9, v27
	v_fma_f32 v2, v2, v10, v28
	v_fmac_f32_e32 v29, v3, v11
	v_cvt_pk_bf16_f32 v0, v0, v1
	v_cvt_pk_bf16_f32 v1, v2, v29
	s_waitcnt vmcnt(0)
	v_fma_f32 v3, v4, v12, v52
	v_fma_f32 v4, v5, v13, v53
	v_fma_f32 v5, v6, v14, v54
	v_fmac_f32_e32 v55, v7, v15
	v_cvt_pk_bf16_f32 v2, v3, v4
	v_cvt_pk_bf16_f32 v3, v5, v55
	global_store_dwordx4 v[24:25], v[0:3], off offset:3072
	s_andn2_b64 exec, exec, s[14:15]
	s_cbranch_execz .LBB0_798

; __device__ __forceinline__ unsigned cvt_pk_bf16(float lo, float hi) { unsigned r; asm volatile("v_cvt_pk_bf16_f32 %0, %1, %2" : "=v"(r) : "v"(lo), "v"(hi)); return r; }
; __device__ __forceinline__ float wave_sum(float v, int lane) {
; #pragma unroll
;     for (int o = 32; o; o >>= 1) v += __int_as_float(__builtin_amdgcn_ds_bpermute((lane ^ o) << 2, __float_as_int(v)));
;     return v;
; __device__ void phase_norm(const Ctx& c, const void* xlat, bool lat_f32, const void* xctx, bool ctx_f32, const float* __restrict__ g, const float* __restrict__ mod, int sh_off, int sc_off,
;                            bf16_t* __restrict__ dst, int nrows, const float* part) {
;     ...
;         float ss = 0.f;
; #pragma unroll
;         for (int i = 0; i < 8; ++i) ss += v[i][0] * v[i][0] + v[i][1] * v[i][1] + v[i][2] * v[i][2] + v[i][3] * v[i][3];
;         ss = wave_sum(ss, c.lane);
;         const float rstd = rsqrtf(ss * (1.f / DM) + EPS);
;         const int r = row < TL ? (row >> 11) : 4;
;         const float* md = mod + (size_t)r * MODW + c.lane * 8;
; #pragma unroll
;         for (int i = 0; i < 4; ++i) { const int cc = i * 512;
;             f32x4 y[2];
; #pragma unroll
;             for (int h = 0; h < 2; ++h) { const f32x4 gg = *(const f32x4*)(g + cc + c.lane * 8 + 4 * h), sh = *(const f32x4*)(md + sh_off + cc + 4 * h), sc = *(const f32x4*)(md + sc_off + cc + 4 * h);
; #pragma unroll
;                 for (int j = 0; j < 4; ++j) y[h][j] = v[2 * i + h][j] * rstd * gg[j] * (1.f + sc[j]) + sh[j]; }
;             u32x4 w; w.x = cvt_pk_bf16(y[0][0], y[0][1]); w.y = cvt_pk_bf16(y[0][2], y[0][3]); w.z = cvt_pk_bf16(y[1][0], y[1][1]); w.w = cvt_pk_bf16(y[1][2], y[1][3]);
;             *(u32x4*)(dst + (size_t)row * DM + cc + c.lane * 8) = w; }
.LBB0_1179:
	s_or_b64 exec, exec, s[82:83]
	v_mul_f32_e32 v0, v65, v65
	v_mul_f32_e32 v1, v61, v61
	v_fmac_f32_e32 v0, v64, v64
	v_fmac_f32_e32 v1, v60, v60
	v_fmac_f32_e32 v0, v62, v62
	v_fmac_f32_e32 v1, v58, v58
	v_fmac_f32_e32 v0, v63, v63
	v_fmac_f32_e32 v1, v59, v59
	v_add_f32_e32 v0, v1, v0
	v_mul_f32_e32 v1, v57, v57
	v_fmac_f32_e32 v1, v56, v56
	v_fmac_f32_e32 v1, v54, v54
	v_fmac_f32_e32 v1, v55, v55
	v_add_f32_e32 v0, v1, v0
	v_mul_f32_e32 v1, v53, v53
	v_fmac_f32_e32 v1, v52, v52
	v_fmac_f32_e32 v1, v50, v50
	v_fmac_f32_e32 v1, v51, v51
	v_mov_b32_e32 v2, v49
	v_mov_b32_e32 v3, v47
	v_add_f32_e32 v4, v1, v0
	v_mov_b32_e32 v0, v48
	v_mov_b32_e32 v1, v46
	v_pk_mul_f32 v[2:3], v[2:3], v[2:3]
	s_nop 0
	v_pk_fma_f32 v[0:1], v[0:1], v[0:1], v[2:3]
	v_mov_b32_e32 v2, v44
	v_mov_b32_e32 v3, v42
	v_pk_fma_f32 v[0:1], v[2:3], v[2:3], v[0:1]
	v_mov_b32_e32 v2, v45
	v_mov_b32_e32 v3, v43
	v_pk_fma_f32 v[0:1], v[2:3], v[2:3], v[0:1]
	v_mov_b32_e32 v2, v37
	v_add_f32_e32 v1, v1, v4
	v_mov_b32_e32 v3, v41
	v_add_f32_e32 v4, v0, v1
	v_mov_b32_e32 v0, v36
	v_mov_b32_e32 v1, v40
	v_pk_mul_f32 v[2:3], v[2:3], v[2:3]
	s_nop 0
	v_pk_fma_f32 v[0:1], v[0:1], v[0:1], v[2:3]
	v_mov_b32_e32 v2, v34
	v_mov_b32_e32 v3, v38
	v_pk_fma_f32 v[0:1], v[2:3], v[2:3], v[0:1]
	v_mov_b32_e32 v2, v35
	v_mov_b32_e32 v3, v39
	v_pk_fma_f32 v[0:1], v[2:3], v[2:3], v[0:1]
	s_nop 0
	v_add_f32_e32 v1, v1, v4
	v_add_f32_e32 v0, v0, v1
	s_waitcnt lgkmcnt(0)
	v_mov_b32_e32 v1, v0
	s_nop 1
	v_permlane32_swap_b32_e32 v0, v1
	s_nop 1
	v_add_f32_e32 v0, v0, v1
	s_waitcnt lgkmcnt(0)
	v_mov_b32_e32 v1, v0
	s_nop 1
	v_permlane16_swap_b32_e32 v0, v1
	s_nop 1
	v_add_f32_e32 v0, v0, v1
	s_waitcnt lgkmcnt(0)
	s_nop 1
	v_add_f32_dpp v0, v0, v0 row_mirror row_mask:0xf bank_mask:0xf
	s_waitcnt lgkmcnt(0)
	s_nop 1
	v_add_f32_dpp v0, v0, v0 row_half_mirror row_mask:0xf bank_mask:0xf
	s_waitcnt lgkmcnt(0)
	s_nop 1
	v_add_f32_dpp v0, v0, v0 quad_perm:[2,3,0,1] row_mask:0xf bank_mask:0xf
	s_waitcnt lgkmcnt(0)
	s_nop 1
	v_add_f32_dpp v0, v0, v0 quad_perm:[1,0,3,2] row_mask:0xf bank_mask:0xf
	v_fmamk_f32 v0, v0, 0x3a000000, v93
	v_cmp_gt_f32_e32 vcc, s87, v0
	v_mul_f32_e32 v1, 0x4b800000, v0
	s_nop 0
	v_cndmask_b32_e32 v0, v0, v1, vcc
	v_rsq_f32_e32 v0, v0
	s_nop 0
	v_mul_f32_e32 v1, 0x45800000, v0
	v_cndmask_b32_e32 v12, v0, v1, vcc
	v_min_i32_e32 v0, 0x2000, v30
	v_ashrrev_i32_e32 v0, 11, v0
	v_mul_hi_i32_i24_e32 v1, 0xc000, v0
	v_mul_i32_i24_e32 v0, 0xc000, v0
	v_lshl_add_u64 v[66:67], v[20:21], 0, v[0:1]
	v_add_co_u32_e32 v70, vcc, s86, v66
	v_lshl_add_u64 v[80:81], v[66:67], 0, s[8:9]
	s_nop 0
	v_addc_co_u32_e32 v71, vcc, 0, v67, vcc
	v_add_co_u32_e32 v68, vcc, s97, v66
	global_load_dwordx4 v[4:7], v[22:23], off offset:16
	global_load_dwordx4 v[72:75], v[22:23], off
	global_load_dwordx4 v[0:3], v[66:67], off offset:16
	global_load_dwordx4 v[8:11], v[66:67], off
	v_addc_co_u32_e32 v69, vcc, 0, v67, vcc
	global_load_dwordx4 v[76:79], v[68:69], off offset:-4096
	s_nop 0
	global_load_dwordx4 v[80:83], v[80:81], off offset:16
	v_mul_f32_e32 v60, v60, v12
	v_mul_f32_e32 v64, v64, v12
	v_mul_f32_e32 v62, v62, v12
	v_mul_f32_e32 v54, v54, v12
	v_mul_f32_e32 v56, v56, v12
	v_mul_f32_e32 v40, v40, v12
	v_lshl_add_u64 v[30:31], v[30:31], 0, s[18:19]
	s_waitcnt vmcnt(5)
	v_mul_f32_e32 v4, v4, v60
	s_waitcnt vmcnt(4)
	v_mul_f32_e32 v64, v72, v64
	v_mul_f32_e32 v62, v74, v62
	s_waitcnt vmcnt(1)
	v_add_f32_e32 v72, 1.0, v76
	s_waitcnt vmcnt(0)
	v_add_f32_e32 v60, 1.0, v80
	v_fma_f32 v4, v60, v4, v0
	v_mul_f32_e32 v0, v61, v12
	v_mul_f32_e32 v0, v5, v0
	v_add_f32_e32 v5, 1.0, v81
	v_fma_f32 v8, v72, v64, v8
	v_mul_f32_e32 v64, v65, v12
	v_fma_f32 v5, v5, v0, v1
	v_mul_f32_e32 v0, v58, v12
	v_mul_f32_e32 v64, v73, v64
	v_add_f32_e32 v65, 1.0, v77
	v_mul_f32_e32 v0, v6, v0
	v_add_f32_e32 v1, 1.0, v82
	v_fma_f32 v9, v65, v64, v9
	v_add_f32_e32 v64, 1.0, v78
	v_fma_f32 v6, v1, v0, v2
	v_mul_f32_e32 v0, v59, v12
	v_fma_f32 v10, v64, v62, v10
	v_mul_f32_e32 v62, v63, v12
	v_mul_f32_e32 v0, v7, v0
	v_add_f32_e32 v1, 1.0, v83
	v_mul_f32_e32 v62, v75, v62
	v_add_f32_e32 v63, 1.0, v79
	v_fmac_f32_e32 v3, v1, v0
	v_fmac_f32_e32 v11, v63, v62
	v_cvt_pk_bf16_f32 v0, v8, v9
	v_cvt_pk_bf16_f32 v1, v10, v11
	v_cvt_pk_bf16_f32 v2, v4, v5
	v_cvt_pk_bf16_f32 v3, v6, v3
	global_store_dwordx4 v[32:33], v[0:3], off offset:-2048
	v_lshl_add_u64 v[72:73], v[66:67], 0, s[10:11]
	global_load_dwordx4 v[0:3], v[24:25], off offset:16
	global_load_dwordx4 v[4:7], v[24:25], off
	global_load_dwordx4 v[8:11], v[66:67], off offset:2064
	global_load_dwordx4 v[58:61], v[66:67], off offset:2048
	global_load_dwordx4 v[62:65], v[70:71], off offset:2048
	s_nop 0
	global_load_dwordx4 v[70:73], v[72:73], off offset:16
	s_waitcnt vmcnt(4)
; __device__ __forceinline__ unsigned cvt_pk_bf16(float lo, float hi) { unsigned r; asm volatile("v_cvt_pk_bf16_f32 %0, %1, %2" : "=v"(r) : "v"(lo), "v"(hi)); return r; }
; __device__ void phase_norm(const Ctx& c, const void* xlat, bool lat_f32, const void* xctx, bool ctx_f32, const float* __restrict__ g, const float* __restrict__ mod, int sh_off, int sc_off,
;                            bf16_t* __restrict__ dst, int nrows, const float* part) {
;     ...
;         for (int i = 0; i < 4; ++i) { const int cc = i * 512;
;             f32x4 y[2];
; #pragma unroll
;             for (int h = 0; h < 2; ++h) { const f32x4 gg = *(const f32x4*)(g + cc + c.lane * 8 + 4 * h), sh = *(const f32x4*)(md + sh_off + cc + 4 * h), sc = *(const f32x4*)(md + sc_off + cc + 4 * h);
; #pragma unroll
;                 for (int j = 0; j < 4; ++j) y[h][j] = v[2 * i + h][j] * rstd * gg[j] * (1.f + sc[j]) + sh[j]; }
;             u32x4 w; w.x = cvt_pk_bf16(y[0][0], y[0][1]); w.y = cvt_pk_bf16(y[0][2], y[0][3]); w.z = cvt_pk_bf16(y[1][0], y[1][1]); w.w = cvt_pk_bf16(y[1][2], y[1][3]);
;             *(u32x4*)(dst + (size_t)row * DM + cc + c.lane * 8) = w; }
	v_mul_f32_e32 v6, v6, v54
	v_mul_f32_e32 v4, v4, v56
	s_waitcnt vmcnt(1)
	v_add_f32_e32 v54, 1.0, v64
	v_fma_f32 v6, v54, v6, v60
	v_mul_f32_e32 v54, v55, v12
	v_mul_f32_e32 v7, v7, v54
	v_add_f32_e32 v54, 1.0, v65
	v_fmac_f32_e32 v61, v54, v7
	v_mul_f32_e32 v7, v52, v12
	v_mul_f32_e32 v0, v0, v7
	s_waitcnt vmcnt(0)
	v_add_f32_e32 v7, 1.0, v70
	v_fma_f32 v7, v7, v0, v8
	v_mul_f32_e32 v0, v53, v12
	v_mul_f32_e32 v0, v1, v0
	v_add_f32_e32 v1, 1.0, v71
	v_fma_f32 v8, v1, v0, v9
	v_mul_f32_e32 v0, v50, v12
	v_add_f32_e32 v56, 1.0, v62
	v_mul_f32_e32 v0, v2, v0
	v_add_f32_e32 v1, 1.0, v72
	v_fma_f32 v4, v56, v4, v58
	v_mul_f32_e32 v56, v57, v12
	v_fma_f32 v9, v1, v0, v10
	v_mul_f32_e32 v0, v51, v12
	v_mul_f32_e32 v5, v5, v56
	v_add_f32_e32 v56, 1.0, v63
	v_mul_f32_e32 v0, v3, v0
	v_add_f32_e32 v1, 1.0, v73
	v_fma_f32 v5, v56, v5, v59
	v_fmac_f32_e32 v11, v1, v0
	v_cvt_pk_bf16_f32 v0, v4, v5
	v_cvt_pk_bf16_f32 v1, v6, v61
	v_cvt_pk_bf16_f32 v2, v7, v8
	v_cvt_pk_bf16_f32 v3, v9, v11
	global_store_dwordx4 v[32:33], v[0:3], off offset:-1024
	v_add_co_u32_e32 v8, vcc, s89, v66
	s_nop 0
	v_lshl_add_u64 v[0:1], v[66:67], 0, s[50:51]
	global_load_dwordx4 v[50:53], v[26:27], off offset:16
	global_load_dwordx4 v[54:57], v[26:27], off
	v_addc_co_u32_e32 v9, vcc, 0, v67, vcc
	v_lshl_add_u64 v[10:11], v[66:67], 0, s[14:15]
	global_load_dwordx4 v[4:7], v[8:9], off
	s_nop 0
	global_load_dwordx4 v[0:3], v[0:1], off offset:16
	s_nop 0
	global_load_dwordx4 v[58:61], v[68:69], off
	global_load_dwordx4 v[62:65], v[10:11], off offset:16
	v_mul_f32_e32 v10, v46, v12
	v_cmp_lt_i32_e32 vcc, s85, v30
	s_or_b64 s[22:23], vcc, s[22:23]
	s_waitcnt vmcnt(4)
	v_mul_f32_e32 v10, v10, v54
	s_waitcnt vmcnt(1)
	v_add_f32_e32 v11, 1.0, v58
	v_fma_f32 v4, v10, v11, v4
	v_mul_f32_e32 v10, v47, v12
	v_mul_f32_e32 v10, v10, v55
	v_add_f32_e32 v11, 1.0, v59
	v_fma_f32 v5, v10, v11, v5
	v_mul_f32_e32 v10, v42, v12
	v_mul_f32_e32 v10, v10, v56
	v_add_f32_e32 v11, 1.0, v60
	v_fma_f32 v6, v10, v11, v6
	v_mul_f32_e32 v10, v43, v12
	v_mul_f32_e32 v10, v10, v57
	v_add_f32_e32 v11, 1.0, v61
	v_fmac_f32_e32 v7, v10, v11
	v_mul_f32_e32 v10, v48, v12
	v_mul_f32_e32 v10, v10, v50
	s_waitcnt vmcnt(0)
	v_add_f32_e32 v11, 1.0, v62
	v_fma_f32 v10, v10, v11, v0
	v_mul_f32_e32 v0, v49, v12
	v_mul_f32_e32 v0, v0, v51
	v_add_f32_e32 v11, 1.0, v63
	v_fma_f32 v11, v0, v11, v1
	v_mul_f32_e32 v0, v44, v12
	v_mul_f32_e32 v0, v0, v52
	v_add_f32_e32 v1, 1.0, v64
	v_fma_f32 v42, v0, v1, v2
	v_mul_f32_e32 v0, v45, v12
	v_mul_f32_e32 v0, v0, v53
	v_add_f32_e32 v1, 1.0, v65
	v_fmac_f32_e32 v3, v0, v1
	v_cvt_pk_bf16_f32 v0, v4, v5
	v_cvt_pk_bf16_f32 v1, v6, v7
	v_cvt_pk_bf16_f32 v2, v10, v11
	v_cvt_pk_bf16_f32 v3, v42, v3
	global_store_dwordx4 v[32:33], v[0:3], off
	v_lshl_add_u64 v[42:43], v[66:67], 0, s[66:67]
	v_lshl_add_u64 v[50:51], v[66:67], 0, s[16:17]
	global_load_dwordx4 v[0:3], v[28:29], off offset:16
	global_load_dwordx4 v[4:7], v[28:29], off
	s_nop 0
	global_load_dwordx4 v[8:11], v[8:9], off offset:2048
	s_nop 0
	global_load_dwordx4 v[42:45], v[42:43], off offset:16
	s_nop 0
	global_load_dwordx4 v[46:49], v[68:69], off offset:2048
	s_nop 0
	global_load_dwordx4 v[50:53], v[50:51], off offset:16
	s_waitcnt vmcnt(4)
	v_mul_f32_e32 v4, v40, v4
	s_waitcnt vmcnt(1)
	v_add_f32_e32 v40, 1.0, v46
	v_fma_f32 v4, v4, v40, v8
	v_mul_f32_e32 v8, v41, v12
	v_mul_f32_e32 v5, v8, v5
	v_add_f32_e32 v8, 1.0, v47
	v_fma_f32 v5, v5, v8, v9
	v_mul_f32_e32 v8, v38, v12
	v_mul_f32_e32 v6, v8, v6
	v_add_f32_e32 v8, 1.0, v48
	v_fma_f32 v6, v6, v8, v10
	v_mul_f32_e32 v8, v39, v12
	v_mul_f32_e32 v7, v8, v7
	v_add_f32_e32 v8, 1.0, v49
	v_fmac_f32_e32 v11, v7, v8
	v_mul_f32_e32 v7, v36, v12
	v_mul_f32_e32 v0, v7, v0
	s_waitcnt vmcnt(0)
	v_add_f32_e32 v7, 1.0, v50
	v_fma_f32 v7, v0, v7, v42
	v_mul_f32_e32 v0, v37, v12
	v_mul_f32_e32 v0, v0, v1
	v_add_f32_e32 v1, 1.0, v51
	v_fma_f32 v8, v0, v1, v43
	v_mul_f32_e32 v0, v34, v12
	v_mul_f32_e32 v0, v0, v2
	v_add_f32_e32 v1, 1.0, v52
	v_fma_f32 v9, v0, v1, v44
	v_mul_f32_e32 v0, v35, v12
	v_mul_f32_e32 v0, v0, v3
	v_add_f32_e32 v1, 1.0, v53
	v_fmac_f32_e32 v45, v0, v1
	v_cvt_pk_bf16_f32 v0, v4, v5
	v_cvt_pk_bf16_f32 v1, v6, v11
	v_cvt_pk_bf16_f32 v2, v7, v8
	v_cvt_pk_bf16_f32 v3, v9, v45
	global_store_dwordx4 v[32:33], v[0:3], off offset:1024
	v_lshl_add_u64 v[32:33], v[32:33], 0, s[20:21]
	s_andn2_b64 exec, exec, s[22:23]
	s_cbranch_execz .LBB0_1182

; __device__ __forceinline__ unsigned cvt_pk_bf16(float lo, float hi) { unsigned r; asm volatile("v_cvt_pk_bf16_f32 %0, %1, %2" : "=v"(r) : "v"(lo), "v"(hi)); return r; }
; __device__ __forceinline__ float lo_f(unsigned w) { return __uint_as_float(w << 16); }
; __device__ __forceinline__ float hi_f(unsigned w) { return __uint_as_float(w & 0xffff0000u); }
; __device__ void phase_post(const Ctx& c, int l, bool ctx_full) {
;     ...
;             float ss = 0.f;
; #pragma unroll
;             for (int i = 0; i < 8; ++i) ss += own[i] * own[i];
; #pragma unroll
;             for (int o = 8; o; o >>= 1) ss += __int_as_float(__builtin_amdgcn_ds_bpermute((c.lane ^ o) << 2, __float_as_int(ss)));
;             const float rstd = rsqrtf(ss * (1.f / 128.f) + EPS);
;             u32x4 pr;
;             pr.x = (unsigned)__builtin_amdgcn_ds_bpermute((c.lane ^ 4) << 2, (int)raw.x); pr.y = (unsigned)__builtin_amdgcn_ds_bpermute((c.lane ^ 4) << 2, (int)raw.y);
;             pr.z = (unsigned)__builtin_amdgcn_ds_bpermute((c.lane ^ 4) << 2, (int)raw.z); pr.w = (unsigned)__builtin_amdgcn_ds_bpermute((c.lane ^ 4) << 2, (int)raw.w);
;             const float par[8] = {lo_f(pr.x), hi_f(pr.x), lo_f(pr.y), hi_f(pr.y), lo_f(pr.z), hi_f(pr.z), lo_f(pr.w), hi_f(pr.w)};
;             float o8[8];
; #pragma unroll
;             for (int i = 0; i < 8; ++i) { const float on = own[i] * rstd * (p < 4 ? gqo[i] : gko[i]), pn = par[i] * rstd * (p < 4 ? gqp[i] : gkp[i]);
;                 o8[i] = firsth ? on * cs[i] - pn * sn[i] : on * cs[i] + pn * sn[i]; }
;             u32x4 w; w.x = cvt_pk_bf16(o8[0], o8[1]); w.y = cvt_pk_bf16(o8[2], o8[3]); w.z = cvt_pk_bf16(o8[4], o8[5]); w.w = cvt_pk_bf16(o8[6], o8[7]);
;             if (p < 4) *(u32x4*)(Qo + (size_t)row * DM + hd * 128 + 8 * l16) = w;
;             else *(u32x4*)(Ko + kvrow * 512 + grp * 128 + 8 * l16) = w;
.LBB0_1455:
	s_or_b64 exec, exec, s[2:3]
	v_and_b32_e32 v136, 0xffff0000, v48
	v_lshlrev_b32_e32 v56, 16, v48
	v_mul_f32_e32 v132, v136, v136
	v_and_b32_e32 v128, 0xffff0000, v49
	v_lshlrev_b32_e32 v129, 16, v49
	v_fmac_f32_e32 v132, v56, v56
	v_pk_mul_f32 v[130:131], v[128:129], v[128:129]
	ds_bpermute_b32 v48, v67, v48
	v_add_f32_e32 v131, v131, v132
	v_add_f32_e32 v134, v130, v131
	v_and_b32_e32 v130, 0xffff0000, v50
	v_lshlrev_b32_e32 v131, 16, v50
	v_pk_mul_f32 v[132:133], v[130:131], v[130:131]
	v_cmp_eq_u32_e64 s[6:7], 3, v53
	v_add_f32_e32 v133, v133, v134
	v_add_f32_e32 v137, v132, v133
	v_and_b32_e32 v132, 0xffff0000, v51
	v_lshlrev_b32_e32 v133, 16, v51
	v_pk_mul_f32 v[134:135], v[132:133], v[132:133]
	v_cndmask_b32_e64 v140, v0, v4, s[6:7]
	v_add_f32_e32 v135, v135, v137
	v_add_f32_e32 v134, v134, v135
	s_waitcnt lgkmcnt(0)
	v_lshlrev_b32_e32 v137, 16, v48
	ds_bpermute_b32 v49, v67, v49
	v_and_b32_e32 v48, 0xffff0000, v48
	ds_bpermute_b32 v50, v67, v50
	s_waitcnt lgkmcnt(2)
	s_nop 1
	v_add_f32_dpp v134, v134, v134 row_mirror row_mask:0xf bank_mask:0xf
	ds_bpermute_b32 v51, v67, v51
	s_waitcnt lgkmcnt(1)
	s_nop 1
	v_add_f32_dpp v134, v134, v134 row_half_mirror row_mask:0xf bank_mask:0xf
	s_waitcnt lgkmcnt(0)
	v_lshlrev_b32_e32 v139, 16, v51
	v_and_b32_e32 v51, 0xffff0000, v51
	s_waitcnt lgkmcnt(0)
	s_nop 1
	v_add_f32_dpp v134, v134, v134 quad_perm:[2,3,0,1] row_mask:0xf bank_mask:0xf
	s_waitcnt lgkmcnt(0)
	s_nop 1
	v_add_f32_dpp v134, v134, v134 quad_perm:[1,0,3,2] row_mask:0xf bank_mask:0xf
	v_fmamk_f32 v134, v134, 0x3c000000, v124
	v_mul_f32_e32 v135, 0x4b800000, v134
	v_cmp_gt_f32_e64 s[2:3], s78, v134
	s_nop 1
	v_cndmask_b32_e64 v134, v134, v135, s[2:3]
	v_rsq_f32_e32 v134, v134
	v_lshlrev_b32_e32 v135, 16, v49
	v_and_b32_e32 v49, 0xffff0000, v49
	v_mul_f32_e32 v138, 0x45800000, v134
	v_cndmask_b32_e64 v134, v134, v138, s[2:3]
	v_mul_f32_e32 v56, v134, v56
	v_mul_f32_e32 v56, v140, v56
	v_mul_f32_e32 v137, v134, v137
	v_cndmask_b32_e64 v140, v16, v20, s[6:7]
	v_mul_f32_e32 v137, v140, v137
	v_mul_f32_e32 v137, v33, v137
	v_cndmask_b32_e64 v137, v137, -v137, s[4:5]
	v_fmac_f32_e32 v137, v32, v56
	v_mul_f32_e32 v56, v134, v136
	v_cndmask_b32_e64 v136, v1, v5, s[6:7]
	v_mul_f32_e32 v56, v136, v56
	v_mul_f32_e32 v48, v134, v48
	v_cndmask_b32_e64 v136, v17, v21, s[6:7]
	v_mul_f32_e32 v48, v136, v48
	v_mul_f32_e32 v48, v35, v48
	v_cndmask_b32_e64 v48, v48, -v48, s[4:5]
	v_fmac_f32_e32 v48, v34, v56
	v_mul_f32_e32 v56, v134, v129
	v_cndmask_b32_e64 v129, v2, v6, s[6:7]
	v_mul_f32_e32 v56, v129, v56
	v_mul_f32_e32 v129, v134, v135
	v_cndmask_b32_e64 v135, v18, v22, s[6:7]
	v_mul_f32_e32 v129, v135, v129
	v_mul_f32_e32 v129, v37, v129
	v_cndmask_b32_e64 v129, v129, -v129, s[4:5]
	v_fmac_f32_e32 v129, v36, v56
	v_mul_f32_e32 v56, v134, v128
	v_cndmask_b32_e64 v128, v3, v7, s[6:7]
	v_mul_f32_e32 v56, v128, v56
	v_mul_f32_e32 v49, v134, v49
	v_cndmask_b32_e64 v128, v19, v23, s[6:7]
	v_mul_f32_e32 v49, v128, v49
	v_mul_f32_e32 v49, v39, v49
	v_cndmask_b32_e64 v49, v49, -v49, s[4:5]
	v_lshlrev_b32_e32 v138, 16, v50
	v_fmac_f32_e32 v49, v38, v56
	v_mul_f32_e32 v56, v134, v131
	v_cndmask_b32_e64 v128, v8, v12, s[6:7]
	v_mul_f32_e32 v56, v128, v56
	v_mul_f32_e32 v128, v134, v138
	v_cndmask_b32_e64 v131, v24, v28, s[6:7]
	v_mul_f32_e32 v128, v131, v128
	v_mul_f32_e32 v128, v41, v128
	v_cndmask_b32_e64 v128, v128, -v128, s[4:5]
	v_and_b32_e32 v50, 0xffff0000, v50
	v_fmac_f32_e32 v128, v40, v56
	v_mul_f32_e32 v56, v134, v130
	v_cndmask_b32_e64 v130, v9, v13, s[6:7]
	v_mul_f32_e32 v56, v130, v56
	v_mul_f32_e32 v50, v134, v50
	v_cndmask_b32_e64 v130, v25, v29, s[6:7]
	v_mul_f32_e32 v50, v130, v50
	v_mul_f32_e32 v50, v43, v50
	v_cndmask_b32_e64 v50, v50, -v50, s[4:5]
	v_fmac_f32_e32 v50, v42, v56
	v_mul_f32_e32 v56, v134, v133
	v_cndmask_b32_e64 v130, v10, v14, s[6:7]
	v_mul_f32_e32 v56, v130, v56
	v_mul_f32_e32 v130, v134, v139
	v_cndmask_b32_e64 v131, v26, v30, s[6:7]
	v_mul_f32_e32 v130, v131, v130
	v_mul_f32_e32 v130, v45, v130
	v_cndmask_b32_e64 v130, v130, -v130, s[4:5]
	v_fmac_f32_e32 v130, v44, v56
	v_mul_f32_e32 v56, v134, v132
	v_cndmask_b32_e64 v131, v11, v15, s[6:7]
	v_mul_f32_e32 v56, v131, v56
	v_mul_f32_e32 v51, v134, v51
	v_cndmask_b32_e64 v131, v27, v31, s[6:7]
	v_mul_f32_e32 v51, v131, v51
	v_mul_f32_e32 v51, v47, v51
	v_cndmask_b32_e64 v51, v51, -v51, s[4:5]
	v_cmp_ne_u32_e64 s[2:3], 3, v53
	v_fmac_f32_e32 v51, v46, v56
	v_cvt_pk_bf16_f32 v48, v137, v48
	v_cvt_pk_bf16_f32 v49, v129, v49
	v_cvt_pk_bf16_f32 v50, v128, v50
	v_cvt_pk_bf16_f32 v51, v130, v51
	s_and_saveexec_b64 s[6:7], s[2:3]
	s_xor_b64 s[2:3], exec, s[6:7]
	s_cbranch_execz .LBB0_1457
	global_store_dwordx4 v[116:117], v[48:51], off

; __device__ __forceinline__ float lo_f(unsigned w) { return __uint_as_float(w << 16); }
; __device__ __forceinline__ float hi_f(unsigned w) { return __uint_as_float(w & 0xffff0000u); }
; __device__ __forceinline__ float gelu_tanh(float x) {
;     const float y = 0.7978845608028654f * (x + 0.044715f * x * x * x);
;     const float e = __expf(2.f * y);
;     const float th = 1.f - 2.f / (e + 1.f);
;     return 0.5f * x * (1.f + th);
; }
; __device__ void phase_post(const Ctx& c, int l, bool ctx_full) {
;     ...
;         if (full) {
;             float fv[16]; float ss = 0.f;
; #pragma unroll
;             for (int i = 0; i < 2; ++i) { const int cc = i * 512 + c.lane * 8;
;                 const u32x4 zv = *(const u32x4*)(zr + OFF_GV + cc);
;                 fv[i * 8 + 0] = gelu_tanh(lo_f(zv.x)); fv[i * 8 + 1] = gelu_tanh(hi_f(zv.x)); fv[i * 8 + 2] = gelu_tanh(lo_f(zv.y)); fv[i * 8 + 3] = gelu_tanh(hi_f(zv.y));
;                 fv[i * 8 + 4] = gelu_tanh(lo_f(zv.z)); fv[i * 8 + 5] = gelu_tanh(hi_f(zv.z)); fv[i * 8 + 6] = gelu_tanh(lo_f(zv.w)); fv[i * 8 + 7] = gelu_tanh(hi_f(zv.w));
; #pragma unroll
;                 for (int j = 0; j < 8; ++j) ss += fv[i * 8 + j] * fv[i * 8 + j]; }
.LBB0_1461:
	s_or_saveexec_b64 s[72:73], s[2:3]
	v_ashrrev_i32_e32 v53, 31, v52
	s_xor_b64 exec, exec, s[72:73]
	s_cbranch_execz .LBB0_1446
	v_mov_b64_e32 v[32:33], s[14:15]
	v_mad_i64_i32 v[40:41], s[2:3], v52, s74, v[32:33]
	v_lshlrev_b32_e32 v56, 1, v54
	v_lshl_add_u64 v[42:43], v[40:41], 0, v[56:57]
	v_add_co_u32_e32 v32, vcc, 0x2000, v42
	s_nop 1
	v_addc_co_u32_e32 v33, vcc, 0, v43, vcc
	v_mov_b64_e32 v[36:37], v[168:169]
	v_mov_b64_e32 v[38:39], v[170:171]
	v_lshl_add_u64 v[32:33], v[42:43], 0, s[20:21]
	v_mov_b64_e32 v[32:33], v[172:173]
	v_mov_b64_e32 v[34:35], v[174:175]
	v_lshlrev_b32_e32 v44, 16, v36
	v_and_b32_e32 v36, 0xffff0000, v36
	v_mul_f32_e32 v47, 0x3d372713, v44
	v_lshlrev_b32_e32 v45, 16, v37
	v_mul_f32_e32 v49, 0x3d372713, v36
	v_mul_f32_e32 v47, v47, v44
	v_mul_f32_e32 v48, 0.5, v44
	v_mul_f32_e32 v51, 0x3d372713, v45
	v_mul_f32_e32 v49, v49, v36
	v_fma_f32 v44, v47, v44, v44
	v_mul_f32_e32 v50, 0.5, v36
	v_mul_f32_e32 v51, v51, v45
	v_fma_f32 v36, v49, v36, v36
	v_mul_f32_e32 v44, 0x3f4c422a, v44
	v_mul_f32_e32 v92, 0.5, v45
	v_fma_f32 v45, v51, v45, v45
	v_mul_f32_e32 v36, 0x3f4c422a, v36
	v_add_f32_e32 v44, v44, v44
	v_mul_f32_e32 v45, 0x3f4c422a, v45
	v_add_f32_e32 v36, v36, v36
	v_mul_f32_e32 v44, 0x3fb8aa3b, v44
	v_add_f32_e32 v45, v45, v45
	v_mul_f32_e32 v36, 0x3fb8aa3b, v36
	v_exp_f32_e32 v44, v44
	v_mul_f32_e32 v45, 0x3fb8aa3b, v45
	v_exp_f32_e32 v36, v36
	v_exp_f32_e32 v45, v45
	v_and_b32_e32 v37, 0xffff0000, v37
	v_mul_f32_e32 v93, 0x3d372713, v37
	v_add_f32_e32 v44, 1.0, v44
	v_mul_f32_e32 v93, v93, v37
	v_add_f32_e32 v36, 1.0, v36
	v_div_scale_f32 v49, s[2:3], v44, v44, 2.0
	v_fma_f32 v47, v93, v37, v37
	v_add_f32_e32 v45, 1.0, v45
	v_div_scale_f32 v93, s[2:3], v36, v36, 2.0
	v_rcp_f32_e32 v99, v49
	v_div_scale_f32 v95, s[6:7], v45, v45, 2.0
	v_rcp_f32_e32 v100, v93
	v_rcp_f32_e32 v101, v95
	v_fma_f32 v103, -v49, v99, 1.0
	v_div_scale_f32 v51, vcc, 2.0, v44, 2.0
	v_fma_f32 v104, -v93, v100, 1.0
	v_fmac_f32_e32 v99, v103, v99
	v_div_scale_f32 v94, s[2:3], 2.0, v36, 2.0
	v_fma_f32 v105, -v95, v101, 1.0
	v_fmac_f32_e32 v100, v104, v100
	v_mul_f32_e32 v103, v51, v99
	v_div_scale_f32 v96, s[6:7], 2.0, v45, 2.0
	v_fmac_f32_e32 v101, v105, v101
	v_mul_f32_e32 v104, v94, v100
	v_fma_f32 v107, -v49, v103, v51
	v_mul_f32_e32 v47, 0x3f4c422a, v47
	v_mul_f32_e32 v105, v96, v101
	v_fma_f32 v108, -v93, v104, v94
	v_fmac_f32_e32 v103, v107, v99
	v_add_f32_e32 v47, v47, v47
	v_fma_f32 v109, -v95, v105, v96
	v_fmac_f32_e32 v104, v108, v100
	v_fma_f32 v49, -v49, v103, v51
	v_mul_f32_e32 v47, 0x3fb8aa3b, v47
	v_fmac_f32_e32 v105, v109, v101
	v_fma_f32 v51, -v93, v104, v94
	v_div_fmas_f32 v49, v49, v99, v103
	s_mov_b64 vcc, s[2:3]
	v_exp_f32_e32 v47, v47
	v_fma_f32 v93, -v95, v105, v96
	v_div_fixup_f32 v44, v49, v44, 2.0
	v_div_fmas_f32 v49, v51, v100, v104
	s_mov_b64 vcc, s[6:7]
	v_sub_f32_e32 v44, 1.0, v44
	v_div_fixup_f32 v36, v49, v36, 2.0
	v_div_fmas_f32 v49, v93, v101, v105
	v_add_f32_e32 v44, 1.0, v44
	v_sub_f32_e32 v36, 1.0, v36
	v_div_fixup_f32 v45, v49, v45, 2.0
	v_mul_f32_e32 v51, v48, v44
	v_add_f32_e32 v36, 1.0, v36
	v_sub_f32_e32 v44, 1.0, v45
	v_lshlrev_b32_e32 v46, 16, v38
	v_add_f32_e32 v47, 1.0, v47
	v_mul_f32_e32 v50, v50, v36
	v_add_f32_e32 v36, 1.0, v44
	v_div_scale_f32 v97, s[8:9], v47, v47, 2.0
	v_mul_f32_e32 v92, v92, v36
	v_mul_f32_e32 v36, 0x3d372713, v46
	v_rcp_f32_e32 v102, v97
	v_mul_f32_e32 v36, v36, v46
	v_fma_f32 v36, v36, v46, v46
	v_mul_f32_e32 v36, 0x3f4c422a, v36
	v_add_f32_e32 v36, v36, v36
	v_fma_f32 v106, -v97, v102, 1.0
	v_mul_f32_e32 v36, 0x3fb8aa3b, v36
	v_div_scale_f32 v98, s[8:9], 2.0, v47, 2.0
	v_fmac_f32_e32 v102, v106, v102
	v_exp_f32_e32 v36, v36
	v_mul_f32_e32 v106, v98, v102
	v_fma_f32 v110, -v97, v106, v98
	v_fmac_f32_e32 v106, v110, v102
	v_fma_f32 v94, -v97, v106, v98
	s_mov_b64 vcc, s[8:9]
	v_add_f32_e32 v36, 1.0, v36
	v_div_fmas_f32 v44, v94, v102, v106
	v_div_scale_f32 v45, s[2:3], v36, v36, 2.0
	v_div_fixup_f32 v44, v44, v47, 2.0
	v_rcp_f32_e32 v47, v45
	v_sub_f32_e32 v44, 1.0, v44
	v_mul_f32_e32 v37, 0.5, v37
	v_add_f32_e32 v44, 1.0, v44
	v_mul_f32_e32 v93, v37, v44
	v_fma_f32 v37, -v45, v47, 1.0
	v_fmac_f32_e32 v47, v37, v47
	v_div_scale_f32 v37, vcc, 2.0, v36, 2.0
	v_mul_f32_e32 v44, v37, v47
	v_fma_f32 v48, -v45, v44, v37
	v_fmac_f32_e32 v44, v48, v47
	v_and_b32_e32 v38, 0xffff0000, v38
	v_fma_f32 v37, -v45, v44, v37
	v_mul_f32_e32 v45, 0x3d372713, v38
	v_mul_f32_e32 v45, v45, v38
	v_fma_f32 v45, v45, v38, v38
	v_mul_f32_e32 v45, 0x3f4c422a, v45
	v_add_f32_e32 v45, v45, v45
	v_mul_f32_e32 v45, 0x3fb8aa3b, v45
	v_exp_f32_e32 v45, v45
	v_div_fmas_f32 v37, v37, v47, v44
	v_div_fixup_f32 v36, v37, v36, 2.0
	v_sub_f32_e32 v36, 1.0, v36
	v_add_f32_e32 v37, 1.0, v45
	v_div_scale_f32 v44, s[2:3], v37, v37, 2.0
	v_rcp_f32_e32 v45, v44
	v_mul_f32_e32 v46, 0.5, v46
	v_add_f32_e32 v36, 1.0, v36
	v_mul_f32_e32 v94, v46, v36
	v_fma_f32 v36, -v44, v45, 1.0
	v_fmac_f32_e32 v45, v36, v45
	v_div_scale_f32 v36, vcc, 2.0, v37, 2.0
	v_mul_f32_e32 v46, v36, v45
	v_fma_f32 v47, -v44, v46, v36
	v_fmac_f32_e32 v46, v47, v45
	v_fma_f32 v36, -v44, v46, v36
	v_lshlrev_b32_e32 v44, 16, v39
	v_mul_f32_e32 v47, 0x3d372713, v44
	v_mul_f32_e32 v47, v47, v44
	v_fma_f32 v47, v47, v44, v44
	v_mul_f32_e32 v47, 0x3f4c422a, v47
	v_add_f32_e32 v47, v47, v47
	v_mul_f32_e32 v47, 0x3fb8aa3b, v47
	v_exp_f32_e32 v47, v47
	v_div_fmas_f32 v36, v36, v45, v46
	v_div_fixup_f32 v36, v36, v37, 2.0
	v_sub_f32_e32 v36, 1.0, v36
	v_add_f32_e32 v37, 1.0, v47
	v_div_scale_f32 v45, s[2:3], v37, v37, 2.0
	v_rcp_f32_e32 v46, v45
	v_mul_f32_e32 v38, 0.5, v38
	v_add_f32_e32 v36, 1.0, v36
	v_mul_f32_e32 v95, v38, v36
; __device__ __forceinline__ float lo_f(unsigned w) { return __uint_as_float(w << 16); }
; __device__ __forceinline__ float hi_f(unsigned w) { return __uint_as_float(w & 0xffff0000u); }
; __device__ __forceinline__ float gelu_tanh(float x) {
;     const float y = 0.7978845608028654f * (x + 0.044715f * x * x * x);
;     const float e = __expf(2.f * y);
;     const float th = 1.f - 2.f / (e + 1.f);
;     return 0.5f * x * (1.f + th);
; }
; __device__ void phase_post(const Ctx& c, int l, bool ctx_full) {
;     ...
;             for (int i = 0; i < 2; ++i) { const int cc = i * 512 + c.lane * 8;
;                 const u32x4 zv = *(const u32x4*)(zr + OFF_GV + cc);
;                 fv[i * 8 + 0] = gelu_tanh(lo_f(zv.x)); fv[i * 8 + 1] = gelu_tanh(hi_f(zv.x)); fv[i * 8 + 2] = gelu_tanh(lo_f(zv.y)); fv[i * 8 + 3] = gelu_tanh(hi_f(zv.y));
;                 fv[i * 8 + 4] = gelu_tanh(lo_f(zv.z)); fv[i * 8 + 5] = gelu_tanh(hi_f(zv.z)); fv[i * 8 + 6] = gelu_tanh(lo_f(zv.w)); fv[i * 8 + 7] = gelu_tanh(hi_f(zv.w));
; #pragma unroll
;                 for (int j = 0; j < 8; ++j) ss += fv[i * 8 + j] * fv[i * 8 + j]; }
	v_fma_f32 v36, -v45, v46, 1.0
	v_fmac_f32_e32 v46, v36, v46
	v_div_scale_f32 v36, vcc, 2.0, v37, 2.0
	v_mul_f32_e32 v38, v36, v46
	v_fma_f32 v47, -v45, v38, v36
	v_fmac_f32_e32 v38, v47, v46
	v_and_b32_e32 v39, 0xffff0000, v39
	v_fma_f32 v36, -v45, v38, v36
	v_mul_f32_e32 v45, 0x3d372713, v39
	v_mul_f32_e32 v45, v45, v39
	v_fma_f32 v45, v45, v39, v39
	v_mul_f32_e32 v45, 0x3f4c422a, v45
	v_add_f32_e32 v45, v45, v45
	v_mul_f32_e32 v45, 0x3fb8aa3b, v45
	v_exp_f32_e32 v45, v45
	v_div_fmas_f32 v36, v36, v46, v38
	v_div_fixup_f32 v36, v36, v37, 2.0
	v_sub_f32_e32 v36, 1.0, v36
	v_add_f32_e32 v37, 1.0, v45
	v_div_scale_f32 v38, s[2:3], v37, v37, 2.0
	v_rcp_f32_e32 v45, v38
	v_mul_f32_e32 v44, 0.5, v44
	v_add_f32_e32 v36, 1.0, v36
	v_mul_f32_e32 v96, v44, v36
	v_fma_f32 v36, -v38, v45, 1.0
	v_fmac_f32_e32 v45, v36, v45
	v_div_scale_f32 v36, vcc, 2.0, v37, 2.0
	v_mul_f32_e32 v44, v36, v45
	v_fma_f32 v46, -v38, v44, v36
	v_fmac_f32_e32 v44, v46, v45
	v_fma_f32 v36, -v38, v44, v36
	v_div_fmas_f32 v36, v36, v45, v44
	v_div_fixup_f32 v36, v36, v37, 2.0
	v_sub_f32_e32 v36, 1.0, v36
	v_mul_f32_e32 v37, 0.5, v39
	v_add_f32_e32 v36, 1.0, v36
	v_mul_f32_e32 v97, v37, v36
	v_lshlrev_b32_e32 v36, 16, v32
	v_mul_f32_e32 v37, 0x3d372713, v36
	v_mul_f32_e32 v37, v37, v36
	v_fma_f32 v37, v37, v36, v36
	v_mul_f32_e32 v37, 0x3f4c422a, v37
	v_add_f32_e32 v37, v37, v37
	v_mul_f32_e32 v37, 0x3fb8aa3b, v37
	v_exp_f32_e32 v37, v37
	v_and_b32_e32 v32, 0xffff0000, v32
	v_mul_f32_e32 v36, 0.5, v36
	v_mul_f32_e32 v44, v50, v50
	v_add_f32_e32 v37, 1.0, v37
	v_div_scale_f32 v38, s[2:3], v37, v37, 2.0
	v_rcp_f32_e32 v39, v38
	v_fmac_f32_e32 v44, v51, v51
	v_fmac_f32_e32 v44, v92, v92
	v_fmac_f32_e32 v44, v93, v93
	v_fma_f32 v45, -v38, v39, 1.0
	v_fmac_f32_e32 v39, v45, v39
	v_div_scale_f32 v45, vcc, 2.0, v37, 2.0
	v_mul_f32_e32 v46, v45, v39
	v_fma_f32 v47, -v38, v46, v45
	v_fmac_f32_e32 v46, v47, v39
	v_fma_f32 v38, -v38, v46, v45
	v_mul_f32_e32 v45, 0x3d372713, v32
	v_mul_f32_e32 v45, v45, v32
	v_fma_f32 v45, v45, v32, v32
	v_mul_f32_e32 v45, 0x3f4c422a, v45
	v_add_f32_e32 v45, v45, v45
	v_mul_f32_e32 v45, 0x3fb8aa3b, v45
	v_exp_f32_e32 v45, v45
	v_div_fmas_f32 v38, v38, v39, v46
	v_div_fixup_f32 v37, v38, v37, 2.0
	v_sub_f32_e32 v37, 1.0, v37
	v_add_f32_e32 v38, 1.0, v45
	v_div_scale_f32 v39, s[2:3], v38, v38, 2.0
	v_rcp_f32_e32 v45, v39
	v_add_f32_e32 v37, 1.0, v37
	v_mul_f32_e32 v98, v36, v37
	v_mul_f32_e32 v32, 0.5, v32
	v_fma_f32 v36, -v39, v45, 1.0
	v_fmac_f32_e32 v45, v36, v45
	v_div_scale_f32 v36, vcc, 2.0, v38, 2.0
	v_mul_f32_e32 v37, v36, v45
	v_fma_f32 v46, -v39, v37, v36
	v_fmac_f32_e32 v37, v46, v45
	v_fma_f32 v36, -v39, v37, v36
	v_lshlrev_b32_e32 v39, 16, v33
	v_mul_f32_e32 v46, 0x3d372713, v39
	v_mul_f32_e32 v46, v46, v39
	v_fma_f32 v46, v46, v39, v39
	v_mul_f32_e32 v46, 0x3f4c422a, v46
	v_add_f32_e32 v46, v46, v46
	v_mul_f32_e32 v46, 0x3fb8aa3b, v46
	v_exp_f32_e32 v46, v46
	v_div_fmas_f32 v36, v36, v45, v37
	v_div_fixup_f32 v36, v36, v38, 2.0
	v_sub_f32_e32 v36, 1.0, v36
	v_add_f32_e32 v37, 1.0, v46
	v_div_scale_f32 v38, s[2:3], v37, v37, 2.0
	v_rcp_f32_e32 v45, v38
	v_add_f32_e32 v36, 1.0, v36
	v_mul_f32_e32 v99, v32, v36
	v_and_b32_e32 v33, 0xffff0000, v33
	v_fma_f32 v32, -v38, v45, 1.0
	v_fmac_f32_e32 v45, v32, v45
	v_div_scale_f32 v32, vcc, 2.0, v37, 2.0
	v_mul_f32_e32 v36, v32, v45
	v_fma_f32 v46, -v38, v36, v32
	v_fmac_f32_e32 v36, v46, v45
	v_fma_f32 v32, -v38, v36, v32
	v_mul_f32_e32 v38, 0x3d372713, v33
	v_mul_f32_e32 v38, v38, v33
	v_fma_f32 v38, v38, v33, v33
	v_mul_f32_e32 v38, 0x3f4c422a, v38
	v_add_f32_e32 v38, v38, v38
	v_mul_f32_e32 v38, 0x3fb8aa3b, v38
	v_exp_f32_e32 v38, v38
	v_div_fmas_f32 v32, v32, v45, v36
	v_div_fixup_f32 v32, v32, v37, 2.0
	v_sub_f32_e32 v32, 1.0, v32
	v_add_f32_e32 v36, 1.0, v38
	v_div_scale_f32 v37, s[2:3], v36, v36, 2.0
	v_rcp_f32_e32 v38, v37
	v_mul_f32_e32 v39, 0.5, v39
	v_add_f32_e32 v32, 1.0, v32
	v_mul_f32_e32 v100, v39, v32
	v_fma_f32 v32, -v37, v38, 1.0
	v_fmac_f32_e32 v38, v32, v38
	v_div_scale_f32 v32, vcc, 2.0, v36, 2.0
	v_mul_f32_e32 v39, v32, v38
	v_fma_f32 v45, -v37, v39, v32
	v_fmac_f32_e32 v39, v45, v38
	v_fma_f32 v32, -v37, v39, v32
	v_div_fmas_f32 v32, v32, v38, v39
	v_div_fixup_f32 v32, v32, v36, 2.0
	v_mul_f32_e32 v39, 0.5, v33
	v_lshlrev_b32_e32 v33, 16, v34
	v_sub_f32_e32 v38, 1.0, v32
	v_and_b32_e32 v32, 0xffff0000, v34
	v_mul_f32_e32 v34, 0x3d372713, v33
	v_mul_f32_e32 v34, v34, v33
	v_mov_b32_e32 v36, v33
	v_fmac_f32_e32 v36, v34, v36
	v_mul_f32_e32 v34, 0x3f4c422a, v36
	v_add_f32_e32 v34, v34, v34
	v_mul_f32_e32 v34, 0x3fb8aa3b, v34
	v_exp_f32_e32 v37, v34
	v_mul_f32_e32 v34, 0x3d372713, v32
	v_mul_f32_e32 v34, v34, v32
	v_mov_b32_e32 v36, v32
	v_fmac_f32_e32 v36, v34, v36
	v_mul_f32_e32 v34, 0x3f4c422a, v36
	v_add_f32_e32 v34, v34, v34
	v_mul_f32_e32 v34, 0x3fb8aa3b, v34
	v_exp_f32_e32 v36, v34
	v_add_f32_e32 v34, 1.0, v38
	v_mul_f32_e32 v101, v39, v34
	v_fmac_f32_e32 v44, v94, v94
	v_pk_add_f32 v[36:37], v[36:37], 1.0 op_sel_hi:[1,0]
	v_fmac_f32_e32 v44, v95, v95
	v_div_scale_f32 v34, s[2:3], v37, v37, 2.0
	v_rcp_f32_e32 v38, v34
	v_fmac_f32_e32 v44, v96, v96
	v_fmac_f32_e32 v44, v97, v97
	v_fmac_f32_e32 v44, v98, v98
	v_fma_f32 v39, -v34, v38, 1.0
	v_fmac_f32_e32 v38, v39, v38
	v_div_scale_f32 v39, vcc, 2.0, v37, 2.0
	v_mul_f32_e32 v45, v39, v38
	v_fma_f32 v46, -v34, v45, v39
	v_fmac_f32_e32 v45, v46, v38
	v_fma_f32 v34, -v34, v45, v39
	v_div_scale_f32 v39, s[2:3], v36, v36, 2.0
	v_rcp_f32_e32 v46, v39
	v_div_fmas_f32 v34, v34, v38, v45
	v_div_fixup_f32 v37, v34, v37, 2.0
	v_fmac_f32_e32 v44, v99, v99
	v_fma_f32 v34, -v39, v46, 1.0
	v_fmac_f32_e32 v46, v34, v46
	v_div_scale_f32 v34, vcc, 2.0, v36, 2.0
; __device__ void phase_post(const Ctx& c, int l, bool ctx_full) {
;     ...
;             for (int i = 0; i < 2; ++i) { const int cc = i * 512 + c.lane * 8;
;                 const u32x4 zv = *(const u32x4*)(zr + OFF_GV + cc);
;                 fv[i * 8 + 0] = gelu_tanh(lo_f(zv.x)); fv[i * 8 + 1] = gelu_tanh(hi_f(zv.x)); fv[i * 8 + 2] = gelu_tanh(lo_f(zv.y)); fv[i * 8 + 3] = gelu_tanh(hi_f(zv.y));
;                 fv[i * 8 + 4] = gelu_tanh(lo_f(zv.z)); fv[i * 8 + 5] = gelu_tanh(hi_f(zv.z)); fv[i * 8 + 6] = gelu_tanh(lo_f(zv.w)); fv[i * 8 + 7] = gelu_tanh(hi_f(zv.w));
; #pragma unroll
;                 for (int j = 0; j < 8; ++j) ss += fv[i * 8 + j] * fv[i * 8 + j]; }
;             ss = wave_sum(ss, c.lane); const float rstd = rsqrtf(ss * (1.f / 1024.f) + EPS);
; #pragma unroll
;             for (int i = 0; i < 2; ++i) { const int cc = i * 512 + c.lane * 8;
;                 const f32x4 g0 = *(const f32x4*)(gv + cc), g1 = *(const f32x4*)(gv + cc + 4);
;                 u32x4 w;
;                 w.x = cvt_pk_bf16(fv[i * 8 + 0] * rstd * g0[0], fv[i * 8 + 1] * rstd * g0[1]); w.y = cvt_pk_bf16(fv[i * 8 + 2] * rstd * g0[2], fv[i * 8 + 3] * rstd * g0[3]);
;                 w.z = cvt_pk_bf16(fv[i * 8 + 4] * rstd * g1[0], fv[i * 8 + 5] * rstd * g1[1]); w.w = cvt_pk_bf16(fv[i * 8 + 6] * rstd * g1[2], fv[i * 8 + 7] * rstd * g1[3]);
;                 *(u32x4*)(VN + (size_t)row * 1024 + cc) = w; }
; #pragma unroll
;             for (int i = 0; i < 2; ++i) { const int cc = i * 512 + c.lane * 8;
;                 float a[8] = {0.f, 0.f, 0.f, 0.f, 0.f, 0.f, 0.f, 0.f};
; #pragma unroll
;                 for (int k = 0; k < 3; ++k) { const int tt = t + k - 1;
;                     if (tt >= 0 && tt < slen) { const bf16_t* z2 = zr + (ptrdiff_t)(k - 1) * IN_DIM;
;                         const u32x4 cg = *(const u32x4*)(z2 + OFF_CC + cc), hh = *(const u32x4*)(z2 + OFF_CH + cc);
;                         const f32x4 w0 = *(const f32x4*)(wsc + k * 1024 + cc), w1 = *(const f32x4*)(wsc + k * 1024 + cc + 4);
;                         a[0] += w0[0] * lo_f(cg.x) * lo_f(hh.x); a[1] += w0[1] * hi_f(cg.x) * hi_f(hh.x); a[2] += w0[2] * lo_f(cg.y) * lo_f(hh.y); a[3] += w0[3] * hi_f(cg.y) * hi_f(hh.y);
;                         a[4] += w1[0] * lo_f(cg.z) * lo_f(hh.z); a[5] += w1[1] * hi_f(cg.z) * hi_f(hh.z); a[6] += w1[2] * lo_f(cg.w) * lo_f(hh.w); a[7] += w1[3] * hi_f(cg.w) * hi_f(hh.w); } }
	v_mul_f32_e32 v38, v34, v46
	v_fma_f32 v45, -v39, v38, v34
	v_fmac_f32_e32 v38, v45, v46
	v_fma_f32 v34, -v39, v38, v34
	v_div_fmas_f32 v34, v34, v46, v38
	v_lshlrev_b32_e32 v39, 16, v35
	v_div_fixup_f32 v36, v34, v36, 2.0
	v_mul_f32_e32 v34, 0x3d372713, v39
	v_and_b32_e32 v38, 0xffff0000, v35
	v_mul_f32_e32 v34, v34, v39
	v_mov_b32_e32 v35, v39
	v_fmac_f32_e32 v35, v34, v35
	v_mul_f32_e32 v34, 0x3f4c422a, v35
	v_add_f32_e32 v34, v34, v34
	v_mul_f32_e32 v34, 0x3fb8aa3b, v34
	v_exp_f32_e32 v35, v34
	v_mul_f32_e32 v34, 0x3d372713, v38
	v_mul_f32_e32 v34, v34, v38
	v_mov_b32_e32 v45, v38
	v_fmac_f32_e32 v45, v34, v45
	v_mul_f32_e32 v34, 0x3f4c422a, v45
	v_add_f32_e32 v34, v34, v34
	v_mul_f32_e32 v34, 0x3fb8aa3b, v34
	v_exp_f32_e32 v34, v34
	v_pk_add_f32 v[36:37], v[36:37], 1.0 op_sel_hi:[1,0] neg_lo:[1,0] neg_hi:[1,0]
	v_pk_mul_f32 v[32:33], v[32:33], 0.5 op_sel_hi:[1,0]
	v_pk_add_f32 v[36:37], v[36:37], 1.0 op_sel_hi:[1,0]
	v_fmac_f32_e32 v44, v100, v100
	v_pk_mul_f32 v[48:49], v[32:33], v[36:37]
	v_fmac_f32_e32 v44, v101, v101
	v_pk_add_f32 v[32:33], v[34:35], 1.0 op_sel_hi:[1,0]
	v_pk_mul_f32 v[34:35], v[48:49], v[48:49]
	v_div_scale_f32 v102, s[2:3], v33, v33, 2.0
	v_add_f32_e32 v35, v35, v44
	v_add_f32_e32 v104, v34, v35
	ds_read_b128 v[34:37], v245 offset:12304
	ds_read_b128 v[44:47], v245 offset:12288
	v_rcp_f32_e32 v103, v102
	v_pk_mul_f32 v[38:39], v[38:39], 0.5 op_sel_hi:[1,0]
	v_cmp_ne_u32_e64 s[6:7], 0, v127
	v_fma_f32 v105, -v102, v103, 1.0
	v_fmac_f32_e32 v103, v105, v103
	v_div_scale_f32 v105, vcc, 2.0, v33, 2.0
	v_mul_f32_e32 v106, v105, v103
	v_fma_f32 v107, -v102, v106, v105
	v_fmac_f32_e32 v106, v107, v103
	v_fma_f32 v102, -v102, v106, v105
	v_div_scale_f32 v105, s[2:3], v32, v32, 2.0
	v_rcp_f32_e32 v107, v105
	v_div_fmas_f32 v102, v102, v103, v106
	v_div_fixup_f32 v33, v102, v33, 2.0
	v_fma_f32 v102, -v105, v107, 1.0
	v_fmac_f32_e32 v107, v102, v107
	v_div_scale_f32 v102, vcc, 2.0, v32, 2.0
	v_mul_f32_e32 v103, v102, v107
	v_fma_f32 v106, -v105, v103, v102
	v_fmac_f32_e32 v103, v106, v107
	v_fma_f32 v102, -v105, v103, v102
	v_div_fmas_f32 v102, v102, v107, v103
	v_div_fixup_f32 v32, v102, v32, 2.0
	v_pk_add_f32 v[32:33], v[32:33], 1.0 op_sel_hi:[1,0] neg_lo:[1,0] neg_hi:[1,0]
	s_nop 0
	v_pk_add_f32 v[32:33], v[32:33], 1.0 op_sel_hi:[1,0]
	s_nop 0
	v_pk_mul_f32 v[38:39], v[38:39], v[32:33]
	s_nop 0
	v_pk_mul_f32 v[32:33], v[38:39], v[38:39]
	s_nop 0
	v_add_f32_e32 v33, v33, v104
	v_add_f32_e32 v32, v32, v33
	s_waitcnt lgkmcnt(0)
	v_mov_b32_e32 v33, v32
	s_nop 1
	v_permlane32_swap_b32_e32 v32, v33
	s_nop 1
	v_add_f32_e32 v32, v32, v33
	s_waitcnt lgkmcnt(0)
	v_mov_b32_e32 v33, v32
	s_nop 1
	v_permlane16_swap_b32_e32 v32, v33
	s_nop 1
	v_add_f32_e32 v32, v32, v33
	s_waitcnt lgkmcnt(0)
	s_nop 1
	v_add_f32_dpp v32, v32, v32 row_mirror row_mask:0xf bank_mask:0xf
	s_waitcnt lgkmcnt(0)
	s_nop 1
	v_add_f32_dpp v32, v32, v32 row_half_mirror row_mask:0xf bank_mask:0xf
	s_waitcnt lgkmcnt(0)
	s_nop 1
	v_add_f32_dpp v32, v32, v32 quad_perm:[2,3,0,1] row_mask:0xf bank_mask:0xf
	s_waitcnt lgkmcnt(0)
	s_nop 1
	v_add_f32_dpp v32, v32, v32 quad_perm:[1,0,3,2] row_mask:0xf bank_mask:0xf
	v_fmamk_f32 v32, v32, 0x3a800000, v124
	v_mul_f32_e32 v33, 0x4b800000, v32
	v_cmp_gt_f32_e32 vcc, s78, v32
	s_nop 1
	v_cndmask_b32_e32 v32, v32, v33, vcc
	v_rsq_f32_e32 v32, v32
	s_nop 0
	v_mul_f32_e32 v33, 0x45800000, v32
	v_cndmask_b32_e32 v102, v32, v33, vcc
	v_mul_f32_e32 v51, v51, v102
	v_mul_f32_e32 v50, v50, v102
	s_waitcnt lgkmcnt(0)
	v_mul_f32_e32 v44, v44, v51
	v_mul_f32_e32 v45, v45, v50
	v_cvt_pk_bf16_f32 v44, v44, v45
	v_mul_f32_e32 v45, v92, v102
	v_mul_f32_e32 v45, v46, v45
	v_mul_f32_e32 v46, v93, v102
	v_mul_f32_e32 v46, v47, v46
	v_cvt_pk_bf16_f32 v45, v45, v46
	v_mul_f32_e32 v46, v94, v102
	v_mul_f32_e32 v34, v34, v46
	v_mul_f32_e32 v46, v95, v102
	v_lshlrev_b64 v[32:33], 11, v[52:53]
	v_mul_f32_e32 v35, v35, v46
	v_cvt_pk_bf16_f32 v46, v34, v35
	v_mul_f32_e32 v34, v96, v102
	v_mul_f32_e32 v35, v97, v102
	v_lshl_add_u64 v[50:51], v[84:85], 0, v[32:33]
	v_mul_f32_e32 v34, v36, v34
	v_mul_f32_e32 v35, v37, v35
	v_cvt_pk_bf16_f32 v47, v34, v35
	global_store_dwordx4 v[50:51], v[44:47], off
	ds_read_b128 v[34:37], v245 offset:14336
	s_nop 0
	ds_read_b128 v[44:47], v245 offset:14352
	v_mul_f32_e32 v53, v98, v102
	v_mul_f32_e32 v38, v38, v102
	s_waitcnt lgkmcnt(1)
	v_mul_f32_e32 v34, v34, v53
	v_mul_f32_e32 v53, v99, v102
	v_mul_f32_e32 v35, v35, v53
	v_cvt_pk_bf16_f32 v34, v34, v35
	v_mul_f32_e32 v35, v100, v102
	v_mul_f32_e32 v35, v36, v35
	v_mul_f32_e32 v36, v101, v102
	v_mul_f32_e32 v36, v37, v36
	v_cvt_pk_bf16_f32 v35, v35, v36
	v_mul_f32_e32 v36, v49, v102
	v_mul_f32_e32 v37, v48, v102
	s_waitcnt lgkmcnt(0)
	v_mul_f32_e32 v36, v44, v36
	v_mul_f32_e32 v37, v45, v37
	v_cvt_pk_bf16_f32 v36, v36, v37
	v_mul_f32_e32 v37, v39, v102
	v_mul_f32_e32 v37, v46, v37
	v_mul_f32_e32 v38, v47, v38
	v_cvt_pk_bf16_f32 v37, v37, v38
	v_mov_b32_e32 v38, 0
	global_store_dwordx4 v[50:51], v[34:37], off offset:1024
	v_mov_b32_e32 v39, v38
	v_mov_b32_e32 v44, v38
	v_mov_b32_e32 v45, v38
	v_mov_b32_e32 v46, v38
	v_mov_b32_e32 v47, v38
	v_mov_b32_e32 v50, v38
	v_mov_b32_e32 v51, v38
	s_and_saveexec_b64 s[2:3], s[6:7]
	s_cbranch_execz .LBB0_1464
	v_add_co_u32_e32 v34, vcc, 0xffffc000, v42
	s_nop 1
	v_addc_co_u32_e32 v35, vcc, -1, v43, vcc
	v_mov_b64_e32 v[34:35], v[184:185]
	v_mov_b64_e32 v[36:37], v[186:187]
	v_add_co_u32_e32 v38, vcc, 0xffffd000, v42
	v_lshlrev_b32_e32 v50, 16, v36
	v_addc_co_u32_e32 v39, vcc, -1, v43, vcc
	ds_read_b128 v[42:45], v245 offset:0
	v_mov_b64_e32 v[46:47], v[188:189]
	v_mov_b64_e32 v[48:49], v[190:191]
	ds_read_b128 v[92:95], v245 offset:16
	v_lshlrev_b32_e32 v38, 16, v34
	v_and_b32_e32 v39, 0xffff0000, v34
	v_lshlrev_b32_e32 v34, 16, v35
	v_and_b32_e32 v35, 0xffff0000, v35
	v_and_b32_e32 v51, 0xffff0000, v36
	v_lshlrev_b32_e32 v36, 16, v37
	v_and_b32_e32 v37, 0xffff0000, v37
	s_waitcnt lgkmcnt(1)
	v_pk_mul_f32 v[38:39], v[42:43], v[38:39]
	s_waitcnt lgkmcnt(1)
	v_lshlrev_b32_e32 v42, 16, v46
	v_and_b32_e32 v43, 0xffff0000, v46
	v_pk_mul_f32 v[34:35], v[44:45], v[34:35]
	v_lshlrev_b32_e32 v44, 16, v47
	v_and_b32_e32 v45, 0xffff0000, v47
	s_waitcnt lgkmcnt(0)
	v_pk_mul_f32 v[46:47], v[92:93], v[50:51]
	v_lshlrev_b32_e32 v50, 16, v48
	v_and_b32_e32 v51, 0xffff0000, v48
	v_pk_mul_f32 v[36:37], v[94:95], v[36:37]
	v_lshlrev_b32_e32 v48, 16, v49
	v_and_b32_e32 v49, 0xffff0000, v49
	v_pk_fma_f32 v[38:39], v[38:39], v[42:43], 0 op_sel_hi:[1,1,0]
	v_pk_fma_f32 v[44:45], v[34:35], v[44:45], 0 op_sel_hi:[1,1,0]
	v_pk_fma_f32 v[46:47], v[46:47], v[50:51], 0 op_sel_hi:[1,1,0]
	v_pk_fma_f32 v[50:51], v[36:37], v[48:49], 0 op_sel_hi:[1,1,0]

; __device__ __forceinline__ float lo_f(unsigned w) { return __uint_as_float(w << 16); }
; __device__ __forceinline__ float wave_sum(float v, int lane) {
; #pragma unroll
;     for (int o = 32; o; o >>= 1) v += __int_as_float(__builtin_amdgcn_ds_bpermute((lane ^ o) << 2, __float_as_int(v)));
;     return v;
; __device__ __forceinline__ void load_row32(f32x4 (&v)[8], const void* base, bool isf32, size_t rowoff, int lane) {
;     ...
;     else { const bf16_t* p = (const bf16_t*)base + rowoff + lane * 8;
; #pragma unroll
;         for (int i = 0; i < 4; ++i) { const u32x4 xb = *(const u32x4*)(p + i * 512);
;             v[2 * i] = (f32x4){lo_f(xb.x), hi_f(xb.x), lo_f(xb.y), hi_f(xb.y)}; v[2 * i + 1] = (f32x4){lo_f(xb.z), hi_f(xb.z), lo_f(xb.w), hi_f(xb.w)}; } }
; }
; __device__ void phase_norm(const Ctx& c, const void* xlat, bool lat_f32, const void* xctx, bool ctx_f32, const float* __restrict__ g, const float* __restrict__ mod, int sh_off, int sc_off,
;                            bf16_t* __restrict__ dst, int nrows, const float* part) {
;     bf16_t* XW = c.bfp(WS_XW);
;     for (int row = c.bid * 8 + c.wave; row < nrows; row += c.G * 8) {
;         f32x4 v[8];
;         if (row < TL) load_row32(v, xlat, lat_f32, (size_t)row * DM, c.lane); else load_row32(v, xctx, ctx_f32, (size_t)(row - TL) * DM, c.lane);
;         if (part != nullptr && row >= TL) {
;             const float* pr = part + (size_t)(row - TL) * DM + c.lane * 8; bf16_t* xo = XW + (size_t)row * DM + c.lane * 8;
; #pragma unroll
;             for (int i = 0; i < 4; ++i) {
; #pragma unroll
;                 for (int sp = 0; sp < 8; ++sp) { v[2 * i] += *(const f32x4*)(pr + (size_t)sp * TC * DM + i * 512); v[2 * i + 1] += *(const f32x4*)(pr + (size_t)sp * TC * DM + i * 512 + 4); }
;                 u32x4 w; w.x = cvt_pk_bf16(v[2 * i][0], v[2 * i][1]); w.y = cvt_pk_bf16(v[2 * i][2], v[2 * i][3]); w.z = cvt_pk_bf16(v[2 * i + 1][0], v[2 * i + 1][1]); w.w = cvt_pk_bf16(v[2 * i + 1][2], v[2 * i + 1][3]);
;                 *(u32x4*)(xo + i * 512) = w;
;                 __builtin_amdgcn_sched_barrier(0); }
;         }
;         float ss = 0.f;
; #pragma unroll
;         for (int i = 0; i < 8; ++i) ss += v[i][0] * v[i][0] + v[i][1] * v[i][1] + v[i][2] * v[i][2] + v[i][3] * v[i][3];
;         ss = wave_sum(ss, c.lane);
;         const float rstd = rsqrtf(ss * (1.f / DM) + EPS);
.LBB0_1748:
	v_add_co_u32_e32 v22, vcc, 0xfb800000, v16
	s_nop 1
	v_addc_co_u32_e32 v23, vcc, -1, v17, vcc
	global_load_dwordx4 v[18:21], v[22:23], off offset:-3072
	global_load_dwordx4 v[24:27], v[22:23], off offset:-2048
	global_load_dwordx4 v[40:43], v[22:23], off offset:-1024
	global_load_dwordx4 v[44:47], v[22:23], off
	v_ashrrev_i32_e32 v22, 11, v32
	v_mul_hi_i32_i24_e32 v23, 0xc000, v22
	v_mul_i32_i24_e32 v22, 0xc000, v22
	v_lshl_add_u64 v[22:23], v[8:9], 0, v[22:23]
	v_add_co_u32_e32 v28, vcc, s30, v22
	v_lshl_add_u64 v[64:65], v[22:23], 0, s[10:11]
	s_nop 0
	v_addc_co_u32_e32 v29, vcc, 0, v23, vcc
	v_add_co_u32_e32 v30, vcc, s31, v22
	v_lshl_add_u64 v[66:67], v[22:23], 0, s[14:15]
	s_nop 0
	v_addc_co_u32_e32 v31, vcc, 0, v23, vcc
	global_load_dwordx4 v[48:51], v[28:29], off offset:-4096
	global_load_dwordx4 v[52:55], v[30:31], off offset:-4096
	global_load_dwordx4 v[56:59], v[64:65], off offset:16
	global_load_dwordx4 v[60:63], v[66:67], off offset:16
	v_add_co_u32_e32 v72, vcc, s29, v22
	v_add_u32_e32 v32, s4, v32
	s_nop 0
	v_addc_co_u32_e32 v73, vcc, 0, v23, vcc
	s_waitcnt vmcnt(0)
	v_and_b32_e32 v75, 0xffff0000, v18
	v_and_b32_e32 v79, 0xffff0000, v20
	v_lshlrev_b32_e32 v74, 16, v18
	v_lshlrev_b32_e32 v76, 16, v19
	v_and_b32_e32 v77, 0xffff0000, v19
	v_lshlrev_b32_e32 v78, 16, v20
	v_lshlrev_b32_e32 v80, 16, v21
	v_and_b32_e32 v81, 0xffff0000, v21
	v_and_b32_e32 v83, 0xffff0000, v24
	v_lshlrev_b32_e32 v84, 16, v25
	v_and_b32_e32 v85, 0xffff0000, v25
	v_lshlrev_b32_e32 v88, 16, v27
	v_and_b32_e32 v89, 0xffff0000, v27
	v_lshlrev_b32_e32 v19, 16, v44
	v_and_b32_e32 v21, 0xffff0000, v44
	v_lshlrev_b32_e32 v25, 16, v45
	v_and_b32_e32 v27, 0xffff0000, v45
	v_mul_f32_e32 v44, v75, v75
	v_mul_f32_e32 v45, v79, v79
	v_lshlrev_b32_e32 v82, 16, v24
	v_and_b32_e32 v87, 0xffff0000, v26
	v_lshlrev_b32_e32 v18, 16, v46
	v_and_b32_e32 v20, 0xffff0000, v46
	v_mul_f32_e32 v46, v83, v83
	v_fmac_f32_e32 v44, v74, v74
	v_fmac_f32_e32 v45, v78, v78
	v_lshlrev_b32_e32 v86, 16, v26
	v_and_b32_e32 v67, 0xffff0000, v40
	v_and_b32_e32 v66, 0xffff0000, v42
	v_lshlrev_b32_e32 v24, 16, v47
	v_and_b32_e32 v26, 0xffff0000, v47
	v_mul_f32_e32 v47, v87, v87
	v_fmac_f32_e32 v46, v82, v82
	v_fmac_f32_e32 v44, v76, v76
	v_fmac_f32_e32 v45, v80, v80
	v_lshlrev_b32_e32 v65, 16, v40
	v_lshlrev_b32_e32 v64, 16, v42
	v_lshlrev_b32_e32 v69, 16, v41
	v_and_b32_e32 v71, 0xffff0000, v41
	v_pk_mul_f32 v[40:41], v[66:67], v[66:67]
	v_fmac_f32_e32 v47, v86, v86
	v_fmac_f32_e32 v46, v84, v84
	v_fmac_f32_e32 v44, v77, v77
	v_fmac_f32_e32 v45, v81, v81
	v_lshlrev_b32_e32 v68, 16, v43
	v_pk_fma_f32 v[40:41], v[64:65], v[64:65], v[40:41]
	v_fmac_f32_e32 v47, v88, v88
	v_fmac_f32_e32 v46, v85, v85
	v_add_f32_e32 v44, v44, v45
	v_and_b32_e32 v70, 0xffff0000, v43
	v_pk_mul_f32 v[42:43], v[20:21], v[20:21]
	v_pk_fma_f32 v[40:41], v[68:69], v[68:69], v[40:41]
	v_fmac_f32_e32 v47, v89, v89
	v_add_f32_e32 v44, v44, v46
	v_pk_fma_f32 v[42:43], v[18:19], v[18:19], v[42:43]
	v_pk_fma_f32 v[40:41], v[70:71], v[70:71], v[40:41]
	v_add_f32_e32 v44, v47, v44
	v_pk_fma_f32 v[42:43], v[24:25], v[24:25], v[42:43]
	v_add_f32_e32 v41, v41, v44
	v_pk_fma_f32 v[42:43], v[26:27], v[26:27], v[42:43]
	v_add_f32_e32 v40, v40, v41
	v_add_f32_e32 v40, v43, v40
	v_add_f32_e32 v40, v42, v40
	v_add_f32_e32 v42, 1.0, v52
	v_add_f32_e32 v43, 1.0, v53
	v_add_f32_e32 v44, 1.0, v54
	v_add_f32_e32 v45, 1.0, v55
	s_waitcnt lgkmcnt(0)
	v_mov_b32_e32 v41, v40
	s_nop 1
	v_permlane32_swap_b32_e32 v40, v41
	s_nop 1
	v_add_f32_e32 v40, v40, v41
	v_add_f32_e32 v46, 1.0, v61
	v_add_f32_e32 v47, 1.0, v62
	s_waitcnt lgkmcnt(0)
	v_mov_b32_e32 v41, v40
	s_nop 1
	v_permlane16_swap_b32_e32 v40, v41
	s_nop 1
	v_add_f32_e32 v40, v40, v41
	s_waitcnt lgkmcnt(0)
	s_nop 1
	v_add_f32_dpp v40, v40, v40 row_mirror row_mask:0xf bank_mask:0xf
	s_waitcnt lgkmcnt(0)
	s_nop 1
	v_add_f32_dpp v40, v40, v40 row_half_mirror row_mask:0xf bank_mask:0xf
	s_waitcnt lgkmcnt(0)
	s_nop 1
	v_add_f32_dpp v40, v40, v40 quad_perm:[2,3,0,1] row_mask:0xf bank_mask:0xf
	s_waitcnt lgkmcnt(0)
; __device__ __forceinline__ unsigned cvt_pk_bf16(float lo, float hi) { unsigned r; asm volatile("v_cvt_pk_bf16_f32 %0, %1, %2" : "=v"(r) : "v"(lo), "v"(hi)); return r; }
; __device__ void phase_norm(const Ctx& c, const void* xlat, bool lat_f32, const void* xctx, bool ctx_f32, const float* __restrict__ g, const float* __restrict__ mod, int sh_off, int sc_off,
;                            bf16_t* __restrict__ dst, int nrows, const float* part) {
;     ...
;         const float rstd = rsqrtf(ss * (1.f / DM) + EPS);
;         const int r = row < TL ? (row >> 11) : 4;
;         const float* md = mod + (size_t)r * MODW + c.lane * 8;
; #pragma unroll
;         for (int i = 0; i < 4; ++i) { const int cc = i * 512;
;             f32x4 y[2];
; #pragma unroll
;             for (int h = 0; h < 2; ++h) { const f32x4 gg = *(const f32x4*)(g + cc + c.lane * 8 + 4 * h), sh = *(const f32x4*)(md + sh_off + cc + 4 * h), sc = *(const f32x4*)(md + sc_off + cc + 4 * h);
; #pragma unroll
;                 for (int j = 0; j < 4; ++j) y[h][j] = v[2 * i + h][j] * rstd * gg[j] * (1.f + sc[j]) + sh[j]; }
;             u32x4 w; w.x = cvt_pk_bf16(y[0][0], y[0][1]); w.y = cvt_pk_bf16(y[0][2], y[0][3]); w.z = cvt_pk_bf16(y[1][0], y[1][1]); w.w = cvt_pk_bf16(y[1][2], y[1][3]);
;             *(u32x4*)(dst + (size_t)row * DM + cc + c.lane * 8) = w; }
	s_nop 1
	v_add_f32_dpp v40, v40, v40 quad_perm:[1,0,3,2] row_mask:0xf bank_mask:0xf
	v_fmamk_f32 v40, v40, 0x3a000000, v39
	v_mul_f32_e32 v41, 0x4b800000, v40
	v_cmp_gt_f32_e32 vcc, s5, v40
	s_nop 1
	v_cndmask_b32_e32 v40, v40, v41, vcc
	v_rsq_f32_e32 v40, v40
	v_add_f32_e32 v41, 1.0, v60
	v_mul_f32_e32 v52, 0x45800000, v40
	v_cndmask_b32_e32 v90, v40, v52, vcc
	v_mul_f32_e32 v40, v90, v74
	v_mul_f32_e32 v52, v90, v75
	v_mul_f32_e32 v53, v90, v76
	v_mul_f32_e32 v54, v90, v77
	v_mul_f32_e32 v55, v90, v78
	v_mul_f32_e32 v60, v90, v79
	v_mul_f32_e32 v61, v90, v80
	v_mul_f32_e32 v62, v90, v81
	v_mul_f32_e32 v40, v0, v40
	v_mul_f32_e32 v52, v1, v52
	v_mul_f32_e32 v53, v2, v53
	v_mul_f32_e32 v54, v3, v54
	v_mul_f32_e32 v55, v4, v55
	v_mul_f32_e32 v60, v5, v60
	v_mul_f32_e32 v61, v6, v61
	v_fma_f32 v40, v42, v40, v48
	v_fma_f32 v42, v43, v52, v49
	v_fma_f32 v43, v44, v53, v50
	v_fmac_f32_e32 v51, v45, v54
	v_fma_f32 v44, v41, v55, v56
	v_fma_f32 v45, v46, v60, v57
	v_fma_f32 v46, v47, v61, v58
	v_mul_f32_e32 v41, v7, v62
	v_add_f32_e32 v47, 1.0, v63
	v_fmac_f32_e32 v59, v47, v41
	v_cvt_pk_bf16_f32 v40, v40, v42
	v_cvt_pk_bf16_f32 v41, v43, v51
	v_cvt_pk_bf16_f32 v42, v44, v45
	v_cvt_pk_bf16_f32 v43, v46, v59
	global_store_dwordx4 v[16:17], v[40:43], off offset:-3072
	v_lshl_add_u64 v[52:53], v[22:23], 0, s[18:19]
	v_add_co_u32_e32 v56, vcc, s28, v22
	global_load_dwordx4 v[40:43], v[10:11], off
	global_load_dwordx4 v[44:47], v[72:73], off offset:2048
	global_load_dwordx4 v[48:51], v[10:11], off offset:16
	v_addc_co_u32_e32 v57, vcc, 0, v23, vcc
	global_load_dwordx4 v[52:55], v[52:53], off offset:16
	v_lshl_add_u64 v[60:61], v[22:23], 0, s[16:17]
	global_load_dwordx4 v[56:59], v[56:57], off offset:2048
	v_mul_f32_e32 v72, v90, v82
	global_load_dwordx4 v[60:63], v[60:61], off offset:16
	v_mul_f32_e32 v73, v90, v83
	v_mul_f32_e32 v74, v90, v84
	v_mul_f32_e32 v75, v90, v85
	v_mul_f32_e32 v76, v90, v86
	v_mul_f32_e32 v77, v90, v87
	v_mul_f32_e32 v78, v90, v88
	v_mul_f32_e32 v79, v90, v89
	v_mul_f32_e32 v65, v90, v65
	v_mul_f32_e32 v67, v90, v67
	v_mul_f32_e32 v69, v90, v69
	v_mul_f32_e32 v71, v90, v71
	v_mul_f32_e32 v64, v90, v64
	v_mul_f32_e32 v66, v90, v66
	v_mul_f32_e32 v68, v90, v68
	v_mul_f32_e32 v70, v90, v70
	v_mul_f32_e32 v19, v90, v19
	v_mul_f32_e32 v21, v90, v21
	v_mul_f32_e32 v20, v90, v20
	v_mul_f32_e32 v18, v90, v18
	v_mul_f32_e32 v24, v90, v24
	v_cmp_lt_i32_e32 vcc, s34, v32
	s_or_b64 s[8:9], vcc, s[8:9]
	s_waitcnt vmcnt(5)
	v_mul_f32_e32 v40, v40, v72
	s_waitcnt vmcnt(4)
	v_add_f32_e32 v44, 1.0, v44
	v_mul_f32_e32 v41, v41, v73
	v_add_f32_e32 v45, 1.0, v45
	v_mul_f32_e32 v42, v42, v74
	v_add_f32_e32 v46, 1.0, v46
	v_mul_f32_e32 v43, v43, v75
	v_add_f32_e32 v47, 1.0, v47
	s_waitcnt vmcnt(3)
	v_mul_f32_e32 v48, v48, v76
	s_waitcnt vmcnt(2)
	v_add_f32_e32 v52, 1.0, v52
	v_mul_f32_e32 v49, v49, v77
	v_add_f32_e32 v53, 1.0, v53
	v_mul_f32_e32 v50, v50, v78
	v_add_f32_e32 v54, 1.0, v54
	v_mul_f32_e32 v51, v51, v79
	v_add_f32_e32 v55, 1.0, v55
	s_waitcnt vmcnt(1)
	v_fma_f32 v40, v44, v40, v56
	v_fma_f32 v41, v45, v41, v57
	v_fma_f32 v42, v46, v42, v58
	v_fmac_f32_e32 v59, v47, v43
	s_waitcnt vmcnt(0)
	v_fma_f32 v43, v52, v48, v60
	v_fma_f32 v44, v53, v49, v61
	v_fma_f32 v45, v54, v50, v62
	v_fmac_f32_e32 v63, v55, v51
	v_cvt_pk_bf16_f32 v40, v40, v41
	v_cvt_pk_bf16_f32 v41, v42, v59
	v_cvt_pk_bf16_f32 v42, v43, v44
	v_cvt_pk_bf16_f32 v43, v45, v63
	global_store_dwordx4 v[16:17], v[40:43], off offset:-2048
	v_lshl_add_u64 v[60:61], v[22:23], 0, s[22:23]
	global_load_dwordx4 v[40:43], v[12:13], off
	global_load_dwordx4 v[44:47], v[30:31], off
	global_load_dwordx4 v[48:51], v[12:13], off offset:16
	global_load_dwordx4 v[52:55], v[60:61], off offset:16
	global_load_dwordx4 v[56:59], v[28:29], off
	v_lshl_add_u64 v[60:61], v[22:23], 0, s[20:21]
	global_load_dwordx4 v[60:63], v[60:61], off offset:16
	s_waitcnt vmcnt(5)
	v_mul_f32_e32 v40, v65, v40
	s_waitcnt vmcnt(4)
	v_add_f32_e32 v44, 1.0, v44
	v_mul_f32_e32 v41, v67, v41
	v_add_f32_e32 v45, 1.0, v45
	v_mul_f32_e32 v42, v69, v42
	v_add_f32_e32 v46, 1.0, v46
	v_mul_f32_e32 v43, v71, v43
	v_add_f32_e32 v47, 1.0, v47
	s_waitcnt vmcnt(3)
	v_mul_f32_e32 v48, v64, v48
	s_waitcnt vmcnt(2)
	v_add_f32_e32 v52, 1.0, v52
	v_mul_f32_e32 v49, v66, v49
	v_add_f32_e32 v53, 1.0, v53
	v_mul_f32_e32 v50, v68, v50
	v_add_f32_e32 v54, 1.0, v54
	v_mul_f32_e32 v51, v70, v51
	v_add_f32_e32 v55, 1.0, v55
	s_waitcnt vmcnt(1)
	v_fma_f32 v40, v40, v44, v56
	v_fma_f32 v41, v41, v45, v57
	v_fma_f32 v42, v42, v46, v58
	v_fmac_f32_e32 v59, v43, v47
	s_waitcnt vmcnt(0)
	v_fma_f32 v43, v48, v52, v60
	v_fma_f32 v44, v49, v53, v61
	v_fma_f32 v45, v50, v54, v62
	v_fmac_f32_e32 v63, v51, v55
	v_cvt_pk_bf16_f32 v40, v40, v41
	v_cvt_pk_bf16_f32 v41, v42, v59
	v_cvt_pk_bf16_f32 v42, v43, v44
	v_cvt_pk_bf16_f32 v43, v45, v63
	global_store_dwordx4 v[16:17], v[40:43], off offset:-1024
	global_load_dwordx4 v[40:43], v[14:15], off
	s_nop 0
	global_load_dwordx4 v[44:47], v[30:31], off offset:2048
	global_load_dwordx4 v[48:51], v[14:15], off offset:16
	v_lshl_add_u64 v[30:31], v[22:23], 0, s[26:27]
	v_lshl_add_u64 v[22:23], v[22:23], 0, s[24:25]
	global_load_dwordx4 v[52:55], v[30:31], off offset:16
	global_load_dwordx4 v[56:59], v[28:29], off offset:2048
	s_waitcnt vmcnt(4)
	v_mul_f32_e32 v19, v19, v40
	global_load_dwordx4 v[28:31], v[22:23], off offset:16
	v_mul_f32_e32 v23, v90, v27
	v_mul_f32_e32 v22, v90, v25
	v_mul_f32_e32 v25, v90, v26
	s_waitcnt vmcnt(4)
	v_add_f32_e32 v26, 1.0, v44
	v_mul_f32_e32 v21, v21, v41
	v_add_f32_e32 v27, 1.0, v45
	v_mul_f32_e32 v23, v23, v43
	s_waitcnt vmcnt(3)
	v_mul_f32_e32 v20, v20, v49
	s_waitcnt vmcnt(2)
	v_add_f32_e32 v43, 1.0, v53
	v_mul_f32_e32 v22, v22, v42
	v_add_f32_e32 v40, 1.0, v46
	v_add_f32_e32 v41, 1.0, v47
	v_mul_f32_e32 v18, v18, v48
	v_add_f32_e32 v42, 1.0, v52
	v_mul_f32_e32 v24, v24, v50
	v_add_f32_e32 v44, 1.0, v54
	v_mul_f32_e32 v25, v25, v51
	v_add_f32_e32 v45, 1.0, v55
	s_waitcnt vmcnt(1)
	v_fma_f32 v19, v19, v26, v56
	v_fma_f32 v21, v21, v27, v57
	v_fma_f32 v22, v22, v40, v58
	v_fmac_f32_e32 v59, v23, v41
	s_waitcnt vmcnt(0)
	v_fma_f32 v20, v20, v43, v29
	v_fma_f32 v23, v18, v42, v28
	v_fma_f32 v24, v24, v44, v30
	v_fmac_f32_e32 v31, v25, v45
	v_cvt_pk_bf16_f32 v18, v19, v21
	v_cvt_pk_bf16_f32 v19, v22, v59
	v_cvt_pk_bf16_f32 v20, v23, v20
	v_cvt_pk_bf16_f32 v21, v24, v31
	global_store_dwordx4 v[16:17], v[18:21], off
	v_lshl_add_u64 v[16:17], v[16:17], 0, s[6:7]
	s_andn2_b64 exec, exec, s[8:9]
	s_cbranch_execnz .LBB0_1748

; __device__ void phase_final(const Ctx& c) {
;     ...
;     for (int row = c.bid * 8 + c.wave; row < TL; row += c.G * 8) {
;         f32x4 v[8]; load_row32(v, xw, false, (size_t)row * DM, c.lane);
;         float ss = 0.f;
; #pragma unroll
;         for (int i = 0; i < 8; ++i) ss += v[i][0] * v[i][0] + v[i][1] * v[i][1] + v[i][2] * v[i][2] + v[i][3] * v[i][3];
;         ss = wave_sum(ss, c.lane);
;         const float rstd = rsqrtf(ss * (1.f / DM) + EPS);
; #pragma unroll
;         for (int i = 0; i < 8; ++i) { const int cc = (i >> 1) * 512 + c.lane * 8 + 4 * (i & 1); const f32x4 gg = *(const f32x4*)(g + cc); f32x4 y;
; #pragma unroll
;             for (int j = 0; j < 4; ++j) y[j] = v[i][j] * rstd * gg[j];
;             *(f32x4*)(out + (size_t)row * DM + cc) = y; }
.LBB0_2010:
	global_load_dwordx4 v[26:29], v[16:17], off offset:-2048
	global_load_dwordx4 v[30:33], v[16:17], off offset:-1024
	global_load_dwordx4 v[34:37], v[16:17], off
	global_load_dwordx4 v[38:41], v[16:17], off offset:1024
	v_mov_b64_e32 v[0:1], v[100:101]
	v_mov_b64_e32 v[2:3], v[102:103]
	v_add_co_u32_e32 v42, vcc, s8, v14
	v_add_u32_e32 v18, s0, v18
	s_nop 0
	v_addc_co_u32_e32 v43, vcc, -1, v15, vcc
	v_lshl_add_u64 v[16:17], v[16:17], 0, s[4:5]
	s_waitcnt vmcnt(0)
	v_lshlrev_b32_e32 v44, 16, v26
	v_and_b32_e32 v45, 0xffff0000, v26
	v_lshlrev_b32_e32 v46, 16, v28
	v_and_b32_e32 v47, 0xffff0000, v28
	v_and_b32_e32 v57, 0xffff0000, v38
	v_and_b32_e32 v59, 0xffff0000, v40
	v_lshlrev_b32_e32 v26, 16, v27
	v_and_b32_e32 v27, 0xffff0000, v27
	v_lshlrev_b32_e32 v28, 16, v29
	v_and_b32_e32 v29, 0xffff0000, v29
	v_lshlrev_b32_e32 v48, 16, v30
	v_and_b32_e32 v49, 0xffff0000, v30
	v_lshlrev_b32_e32 v56, 16, v38
	v_lshlrev_b32_e32 v58, 16, v40
	v_pk_mul_f32 v[60:61], v[44:45], v[44:45]
	v_pk_mul_f32 v[64:65], v[46:47], v[46:47]
	v_mov_b32_e32 v86, v59
	v_mov_b32_e32 v87, v57
	v_lshlrev_b32_e32 v30, 16, v31
	v_and_b32_e32 v31, 0xffff0000, v31
	v_lshlrev_b32_e32 v50, 16, v32
	v_and_b32_e32 v51, 0xffff0000, v32
	v_and_b32_e32 v53, 0xffff0000, v34
	v_and_b32_e32 v55, 0xffff0000, v36
	v_lshlrev_b32_e32 v38, 16, v39
	v_lshlrev_b32_e32 v40, 16, v41
	v_pk_mul_f32 v[62:63], v[26:27], v[26:27]
	v_pk_mul_f32 v[66:67], v[28:29], v[28:29]
	v_pk_mul_f32 v[68:69], v[48:49], v[48:49]
	v_mov_b32_e32 v84, v58
	v_mov_b32_e32 v85, v56
	v_pk_mul_f32 v[86:87], v[86:87], v[86:87]
	v_add_f32_e32 v92, v64, v65
	v_add_f32_e32 v93, v60, v61
	v_lshlrev_b32_e32 v32, 16, v33
	v_and_b32_e32 v33, 0xffff0000, v33
	v_lshlrev_b32_e32 v52, 16, v34
	v_lshlrev_b32_e32 v54, 16, v36
	v_and_b32_e32 v39, 0xffff0000, v39
	v_and_b32_e32 v41, 0xffff0000, v41
	v_pk_mul_f32 v[70:71], v[30:31], v[30:31]
	v_pk_mul_f32 v[72:73], v[50:51], v[50:51]
	v_mov_b32_e32 v78, v55
	v_mov_b32_e32 v79, v53
	v_mov_b32_e32 v88, v40
	v_mov_b32_e32 v89, v38
	v_add_f32_e32 v68, v68, v69
	v_pk_fma_f32 v[64:65], v[84:85], v[84:85], v[86:87]
	v_add_f32_e32 v66, v66, v92
	v_add_f32_e32 v62, v62, v93
	v_lshlrev_b32_e32 v34, 16, v35
	v_lshlrev_b32_e32 v36, 16, v37
	v_pk_mul_f32 v[74:75], v[32:33], v[32:33]
	v_mov_b32_e32 v76, v54
	v_mov_b32_e32 v77, v52
	v_mov_b32_e32 v90, v41
	v_mov_b32_e32 v91, v39
	v_pk_mul_f32 v[78:79], v[78:79], v[78:79]
	v_add_f32_e32 v69, v72, v73
	v_add_f32_e32 v68, v70, v68
	v_pk_fma_f32 v[64:65], v[88:89], v[88:89], v[64:65]
	v_add_f32_e32 v66, v67, v66
	v_add_f32_e32 v67, v63, v62
	v_and_b32_e32 v35, 0xffff0000, v35
	v_and_b32_e32 v37, 0xffff0000, v37
	v_mov_b32_e32 v80, v36
	v_mov_b32_e32 v81, v34
	v_pk_fma_f32 v[60:61], v[76:77], v[76:77], v[78:79]
	v_add_f32_e32 v69, v74, v69
	v_add_f32_e32 v68, v71, v68
	v_pk_fma_f32 v[62:63], v[90:91], v[90:91], v[64:65]
	v_add_f32_e32 v64, v67, v66
	v_mov_b32_e32 v82, v37
	v_mov_b32_e32 v83, v35
	v_pk_fma_f32 v[60:61], v[80:81], v[80:81], v[60:61]
	v_add_f32_e32 v69, v75, v69
	v_add_f32_e32 v64, v64, v68
	v_pk_fma_f32 v[60:61], v[82:83], v[82:83], v[60:61]
	v_add_f32_e32 v64, v69, v64
	v_add_f32_e32 v61, v61, v64
	v_add_f32_e32 v60, v60, v61
	v_add_f32_e32 v60, v63, v60
	v_add_f32_e32 v60, v62, v60
	s_waitcnt lgkmcnt(0)
	v_mov_b32_e32 v61, v60
	s_nop 1
	v_permlane32_swap_b32_e32 v60, v61
	s_nop 1
	v_add_f32_e32 v60, v60, v61
	s_waitcnt lgkmcnt(0)
	v_mov_b32_e32 v61, v60
	s_nop 1
	v_permlane16_swap_b32_e32 v60, v61
	s_nop 1
	v_add_f32_e32 v60, v60, v61
	s_waitcnt lgkmcnt(0)
	s_nop 1
	v_add_f32_dpp v60, v60, v60 row_mirror row_mask:0xf bank_mask:0xf
	s_waitcnt lgkmcnt(0)
	s_nop 1
	v_add_f32_dpp v60, v60, v60 row_half_mirror row_mask:0xf bank_mask:0xf
	s_waitcnt lgkmcnt(0)
	s_nop 1
	v_add_f32_dpp v60, v60, v60 quad_perm:[2,3,0,1] row_mask:0xf bank_mask:0xf
	s_waitcnt lgkmcnt(0)
	s_nop 1
	v_add_f32_dpp v60, v60, v60 quad_perm:[1,0,3,2] row_mask:0xf bank_mask:0xf
	v_fmamk_f32 v60, v60, 0x3a000000, v25
	v_mul_f32_e32 v61, 0x4b800000, v60
	v_cmp_gt_f32_e32 vcc, s1, v60
	s_nop 1
	v_cndmask_b32_e32 v60, v60, v61, vcc
	v_rsq_f32_e32 v60, v60
	s_nop 0
	v_mul_f32_e32 v61, 0x45800000, v60
	v_cndmask_b32_e32 v60, v60, v61, vcc
	v_pk_mul_f32 v[44:45], v[60:61], v[44:45] op_sel_hi:[0,1]
	v_pk_mul_f32 v[26:27], v[60:61], v[26:27] op_sel_hi:[0,1]
	v_pk_mul_f32 v[2:3], v[2:3], v[26:27]
	v_pk_mul_f32 v[0:1], v[0:1], v[44:45]
	global_store_dwordx4 v[42:43], v[0:3], off offset:-2064
	v_pk_mul_f32 v[26:27], v[60:61], v[28:29] op_sel_hi:[0,1]
	v_pk_mul_f32 v[28:29], v[60:61], v[46:47] op_sel_hi:[0,1]
	v_cmp_lt_i32_e32 vcc, s9, v18
	s_or_b64 s[6:7], vcc, s[6:7]
	v_mov_b64_e32 v[0:1], v[104:105]
	v_mov_b64_e32 v[2:3], v[106:107]
	v_pk_mul_f32 v[0:1], v[0:1], v[28:29]
	v_pk_mul_f32 v[2:3], v[2:3], v[26:27]
	global_store_dwordx4 v[42:43], v[0:3], off offset:-2048
	v_pk_mul_f32 v[26:27], v[60:61], v[30:31] op_sel_hi:[0,1]
	v_pk_mul_f32 v[28:29], v[60:61], v[48:49] op_sel_hi:[0,1]
	v_mov_b64_e32 v[0:1], v[108:109]
	v_mov_b64_e32 v[2:3], v[110:111]
	v_pk_mul_f32 v[0:1], v[0:1], v[28:29]
	v_pk_mul_f32 v[2:3], v[2:3], v[26:27]
	global_store_dwordx4 v[42:43], v[0:3], off offset:-16
	v_pk_mul_f32 v[26:27], v[60:61], v[32:33] op_sel_hi:[0,1]
	v_pk_mul_f32 v[28:29], v[60:61], v[50:51] op_sel_hi:[0,1]
	v_mov_b64_e32 v[0:1], v[112:113]
	v_mov_b64_e32 v[2:3], v[114:115]
	v_pk_mul_f32 v[0:1], v[0:1], v[28:29]
	v_pk_mul_f32 v[2:3], v[2:3], v[26:27]
	global_store_dwordx4 v[14:15], v[0:3], off offset:-4096
	v_pk_mul_f32 v[26:27], v[60:61], v[52:53] op_sel_hi:[0,1]
	v_pk_mul_f32 v[28:29], v[60:61], v[34:35] op_sel_hi:[0,1]
	v_mov_b64_e32 v[0:1], v[116:117]
	v_mov_b64_e32 v[2:3], v[118:119]
	v_pk_mul_f32 v[0:1], v[0:1], v[26:27]
	v_pk_mul_f32 v[2:3], v[2:3], v[28:29]
	global_store_dwordx4 v[14:15], v[0:3], off offset:-2064
	v_pk_mul_f32 v[26:27], v[60:61], v[54:55] op_sel_hi:[0,1]
	v_pk_mul_f32 v[28:29], v[60:61], v[36:37] op_sel_hi:[0,1]
	v_mov_b64_e32 v[0:1], v[120:121]
	v_mov_b64_e32 v[2:3], v[122:123]
	v_pk_mul_f32 v[0:1], v[0:1], v[26:27]
	v_pk_mul_f32 v[2:3], v[2:3], v[28:29]
	global_store_dwordx4 v[14:15], v[0:3], off offset:-2048
	v_pk_mul_f32 v[26:27], v[60:61], v[56:57] op_sel_hi:[0,1]
	v_pk_mul_f32 v[28:29], v[60:61], v[38:39] op_sel_hi:[0,1]
	v_mov_b64_e32 v[0:1], v[124:125]
	v_mov_b64_e32 v[2:3], v[126:127]
	v_pk_mul_f32 v[0:1], v[0:1], v[26:27]
	v_pk_mul_f32 v[2:3], v[2:3], v[28:29]
	global_store_dwordx4 v[14:15], v[0:3], off offset:-16
	v_pk_mul_f32 v[26:27], v[60:61], v[58:59] op_sel_hi:[0,1]
	v_pk_mul_f32 v[28:29], v[60:61], v[40:41] op_sel_hi:[0,1]
	v_mov_b64_e32 v[0:1], v[128:129]
	v_mov_b64_e32 v[2:3], v[130:131]
	v_pk_mul_f32 v[0:1], v[0:1], v[26:27]
	v_pk_mul_f32 v[2:3], v[2:3], v[28:29]
	global_store_dwordx4 v[14:15], v[0:3], off
	v_lshl_add_u64 v[14:15], v[14:15], 0, s[2:3]
	s_andn2_b64 exec, exec, s[6:7]
	s_cbranch_execnz .LBB0_2010
